# k37
# speedup vs baseline: 1.0027x; 1.0027x over previous
; #define PG8_STAGE(bufoff, gbase, voff) do { _Pragma("unroll") for (int _i = 0; _i < 2; ++_i) \
;         __builtin_amdgcn_global_load_lds((const unsigned*)((const char*)(gbase) + (voff)[_i]), (PG8_LAS unsigned*)(lds + (bufoff) + ldsw + _i * 8192), 16, 0, 0); } while (0)
; #define PG8_LDA(dst, b, h) do { _Pragma("unroll") for (int m = 0; m < 4; ++m) _Pragma("unroll") for (int k = 0; k < 2; ++k) dst[m][k] = *(const PG8_LAS bf16x8*)(lds + PG8_SA(b, h) + aoff + m * 2048 + k * 1024); } while (0)
; #define PG8_LDB(dst, b, h) do { _Pragma("unroll") for (int n = 0; n < 2; ++n) _Pragma("unroll") for (int k = 0; k < 2; ++k) dst[n][k] = *(const PG8_LAS bf16x8*)(lds + PG8_SB(b, h) + boff + n * 2048 + k * 1024); } while (0)
; #define PG8_MMA(ai, bj, At, Bt) do { __builtin_amdgcn_s_setprio(1); _Pragma("unroll") for (int m = 0; m < 4; ++m) _Pragma("unroll") for (int n = 0; n < 2; ++n) _Pragma("unroll") for (int k = 0; k < 2; ++k) \
;         acc[ai][bj][m][n] = __builtin_amdgcn_mfma_f32_16x16x32_bf16(Bt[n][k], At[m][k], acc[ai][bj][m][n], 0, 0, 0); __builtin_amdgcn_s_setprio(0); } while (0)
; #define PG8_WAIT_V(n) asm volatile("s_waitcnt vmcnt(" #n ")" ::: "memory")
; #define PG8_WAIT_L(n) asm volatile("s_waitcnt lgkmcnt(" #n ")" ::: "memory")
; #define PG8_BAR __builtin_amdgcn_s_barrier()
; #define PG8_SCHED __builtin_amdgcn_sched_barrier(0)
; template <class Epi, class Sched, bool ALIGN_EPI = false, bool SP2 = false>
; __device__ __forceinline__ void gemm_phase(PG8_LAS unsigned char* lds, const Gemm g, const Sched& S, const Epi& E) {
;     ...
;             const bool last = (t == nt - 2);
;             const char* a1 = cA + (size_t)(t + 1) * kstep;
;             const char* a2 = last ? nA : cA + (size_t)(t + 2) * kstep; const char* b2 = last ? nB : cB + (size_t)(t + 2) * kstep;
;             const char* a3 = a2 + kstep; const char* b3 = b2 + kstep;
;             if (last && has_next) S.a_ready(nxt);
;             if constexpr (SP2) {
;             PG8_LDB(B0, 0, 0); PG8_LDB(B1, 0, 1); PG8_SCHED; PG8_LDA(At, 0, 0); PG8_STAGE(PG8_SA(1, 1), a1 + hstep, voffA);
;             PG8_WAIT_V(8); PG8_WAIT_L(0); PG8_BAR; PG8_MMA(0, 0, At, B0); PG8_MMA(0, 1, At, B1); PG8_BAR; PG8_SCHED;
;             PG8_LDA(At, 0, 1); PG8_STAGE(PG8_SB(0, 0), b2, voffB); PG8_STAGE(PG8_SB(0, 1), b2 + hstep, voffB); PG8_STAGE(PG8_SA(0, 0), a2, voffA);
.LBB0_215:
	ds_read_b128 v[130:133], v186
	ds_read_b128 v[134:137], v186 offset:1024
	ds_read_b128 v[138:141], v186 offset:2048
	ds_read_b128 v[166:169], v186 offset:3072
	ds_read_b128 v[170:173], v187
	ds_read_b128 v[174:177], v187 offset:1024
	ds_read_b128 v[178:181], v187 offset:2048
	ds_read_b128 v[182:185], v187 offset:3072
	s_add_u32 s30, s76, 0xfffc0080
	s_addc_u32 s31, s77, -1
	s_cmp_eq_u32 s75, 12
	s_cselect_b32 s81, s1, s31
	s_cselect_b32 s80, s8, s30
	s_cselect_b32 s79, s19, s63
	s_cselect_b32 s78, s33, s61
	v_lshl_add_u64 v[202:203], s[76:77], 0, v[158:159]
	s_add_i32 m0, s28, 0xc000
	ds_read_b128 v[190:193], v188
	ds_read_b128 v[194:197], v188 offset:1024
	ds_read_b128 v[198:201], v188 offset:2048
	ds_read_b128 v[206:209], v188 offset:3072
	ds_read_b128 v[210:213], v188 offset:4096
	ds_read_b128 v[214:217], v188 offset:5120
	ds_read_b128 v[218:221], v188 offset:6144
	ds_read_b128 v[222:225], v188 offset:7168
	global_load_lds_dwordx4 v[202:203], off
	v_lshl_add_u64 v[202:203], s[76:77], 0, v[160:161]
	s_add_i32 m0, s28, 0xe000
	s_nop 0
	global_load_lds_dwordx4 v[202:203], off
	s_waitcnt vmcnt(8)
	s_waitcnt lgkmcnt(0)
	s_barrier
	s_setprio 1
	s_waitcnt lgkmcnt(0)
	v_mfma_f32_16x16x32_bf16 v[126:129], v[130:133], v[190:193], v[126:129]
	v_mfma_f32_16x16x32_bf16 v[122:125], v[138:141], v[190:193], v[122:125]
	v_mfma_f32_16x16x32_bf16 v[118:121], v[130:133], v[198:201], v[118:121]
	v_mfma_f32_16x16x32_bf16 v[114:117], v[138:141], v[198:201], v[114:117]
	v_mfma_f32_16x16x32_bf16 v[110:113], v[130:133], v[210:213], v[110:113]
	v_mfma_f32_16x16x32_bf16 v[106:109], v[138:141], v[210:213], v[106:109]
	v_mfma_f32_16x16x32_bf16 v[102:105], v[130:133], v[218:221], v[102:105]
	v_mfma_f32_16x16x32_bf16 v[98:101], v[138:141], v[218:221], v[98:101]
	v_mfma_f32_16x16x32_bf16 v[126:129], v[134:137], v[194:197], v[126:129]
	v_mfma_f32_16x16x32_bf16 v[122:125], v[166:169], v[194:197], v[122:125]
	v_mfma_f32_16x16x32_bf16 v[118:121], v[134:137], v[206:209], v[118:121]
	v_mfma_f32_16x16x32_bf16 v[114:117], v[166:169], v[206:209], v[114:117]
	v_mfma_f32_16x16x32_bf16 v[110:113], v[134:137], v[214:217], v[110:113]
	v_mfma_f32_16x16x32_bf16 v[106:109], v[166:169], v[214:217], v[106:109]
	v_mfma_f32_16x16x32_bf16 v[102:105], v[134:137], v[222:225], v[102:105]
	v_mfma_f32_16x16x32_bf16 v[98:101], v[166:169], v[222:225], v[98:101]
	s_setprio 0
	s_setprio 1
	v_mfma_f32_16x16x32_bf16 v[62:65], v[170:173], v[190:193], v[62:65]
	v_mfma_f32_16x16x32_bf16 v[58:61], v[178:181], v[190:193], v[58:61]
	v_mfma_f32_16x16x32_bf16 v[54:57], v[170:173], v[198:201], v[54:57]
	v_mfma_f32_16x16x32_bf16 v[50:53], v[178:181], v[198:201], v[50:53]
	v_mfma_f32_16x16x32_bf16 v[46:49], v[170:173], v[210:213], v[46:49]
	v_mfma_f32_16x16x32_bf16 v[42:45], v[178:181], v[210:213], v[42:45]
	v_mfma_f32_16x16x32_bf16 v[38:41], v[170:173], v[218:221], v[38:41]
	v_mfma_f32_16x16x32_bf16 v[34:37], v[178:181], v[218:221], v[34:37]
	v_mfma_f32_16x16x32_bf16 v[62:65], v[174:177], v[194:197], v[62:65]
	v_mfma_f32_16x16x32_bf16 v[58:61], v[182:185], v[194:197], v[58:61]
	v_mfma_f32_16x16x32_bf16 v[54:57], v[174:177], v[206:209], v[54:57]
	v_mfma_f32_16x16x32_bf16 v[50:53], v[182:185], v[206:209], v[50:53]
	s_setprio 2
	s_barrier
	v_mfma_f32_16x16x32_bf16 v[46:49], v[174:177], v[214:217], v[46:49]
	v_mfma_f32_16x16x32_bf16 v[42:45], v[182:185], v[214:217], v[42:45]
	v_mfma_f32_16x16x32_bf16 v[38:41], v[174:177], v[222:225], v[38:41]
	v_mfma_f32_16x16x32_bf16 v[34:37], v[182:185], v[222:225], v[34:37]
	s_setprio 0
	s_add_i32 s30, s7, s97
	v_lshl_add_u64 v[202:203], s[78:79], 0, v[146:147]
	s_mov_b32 m0, s30
	ds_read_b128 v[190:193], v188 offset:16384
	ds_read_b128 v[194:197], v188 offset:17408
	ds_read_b128 v[198:201], v188 offset:18432
	ds_read_b128 v[206:209], v188 offset:19456
	ds_read_b128 v[210:213], v188 offset:20480
	ds_read_b128 v[214:217], v188 offset:21504
	ds_read_b128 v[218:221], v188 offset:22528
	ds_read_b128 v[222:225], v188 offset:23552
	global_load_lds_dwordx4 v[202:203], off
	s_add_i32 m0, s30, 0x2000
	s_add_u32 s30, s78, 0x40000
	v_lshl_add_u64 v[226:227], s[78:79], 0, v[150:151]
	s_addc_u32 s31, s79, 0
	s_add_i32 s94, s92, s97
	global_load_lds_dwordx4 v[226:227], off
	v_lshl_add_u64 v[228:229], s[30:31], 0, v[146:147]
	s_mov_b32 m0, s94
	v_lshl_add_u64 v[230:231], s[80:81], 0, v[148:149]
	global_load_lds_dwordx4 v[228:229], off
	v_lshl_add_u64 v[228:229], s[30:31], 0, v[150:151]
	s_add_i32 m0, s94, 0x2000
	s_nop 0
	global_load_lds_dwordx4 v[228:229], off
	v_lshl_add_u64 v[228:229], s[80:81], 0, v[144:145]
	s_mov_b32 m0, s28
	s_nop 0
	global_load_lds_dwordx4 v[228:229], off
	s_mov_b32 m0, s29
	s_nop 0
	global_load_lds_dwordx4 v[230:231], off
	s_waitcnt vmcnt(8)
	s_waitcnt lgkmcnt(0)
	s_barrier
; #define PG8_STAGE(bufoff, gbase, voff) do { _Pragma("unroll") for (int _i = 0; _i < 2; ++_i) \
;         __builtin_amdgcn_global_load_lds((const unsigned*)((const char*)(gbase) + (voff)[_i]), (PG8_LAS unsigned*)(lds + (bufoff) + ldsw + _i * 8192), 16, 0, 0); } while (0)
; #define PG8_LDA(dst, b, h) do { _Pragma("unroll") for (int m = 0; m < 4; ++m) _Pragma("unroll") for (int k = 0; k < 2; ++k) dst[m][k] = *(const PG8_LAS bf16x8*)(lds + PG8_SA(b, h) + aoff + m * 2048 + k * 1024); } while (0)
; #define PG8_LDB(dst, b, h) do { _Pragma("unroll") for (int n = 0; n < 2; ++n) _Pragma("unroll") for (int k = 0; k < 2; ++k) dst[n][k] = *(const PG8_LAS bf16x8*)(lds + PG8_SB(b, h) + boff + n * 2048 + k * 1024); } while (0)
; #define PG8_MMA(ai, bj, At, Bt) do { __builtin_amdgcn_s_setprio(1); _Pragma("unroll") for (int m = 0; m < 4; ++m) _Pragma("unroll") for (int n = 0; n < 2; ++n) _Pragma("unroll") for (int k = 0; k < 2; ++k) \
;         acc[ai][bj][m][n] = __builtin_amdgcn_mfma_f32_16x16x32_bf16(Bt[n][k], At[m][k], acc[ai][bj][m][n], 0, 0, 0); __builtin_amdgcn_s_setprio(0); } while (0)
; #define PG8_WAIT_V(n) asm volatile("s_waitcnt vmcnt(" #n ")" ::: "memory")
; #define PG8_WAIT_L(n) asm volatile("s_waitcnt lgkmcnt(" #n ")" ::: "memory")
; #define PG8_BAR __builtin_amdgcn_s_barrier()
; #define PG8_SCHED __builtin_amdgcn_sched_barrier(0)
; template <class Epi, class Sched, bool ALIGN_EPI = false, bool SP2 = false>
; __device__ __forceinline__ void gemm_phase(PG8_LAS unsigned char* lds, const Gemm g, const Sched& S, const Epi& E) {
;     ...
;             PG8_WAIT_V(8); PG8_WAIT_L(0); PG8_BAR; PG8_MMA(1, 0, At, B0); PG8_MMA(1, 1, At, B1); PG8_BAR; PG8_SCHED;
;             PG8_LDB(B0, 1, 0); PG8_LDB(B1, 1, 1); PG8_SCHED; PG8_LDA(At, 1, 0); PG8_STAGE(PG8_SA(0, 1), a2 + hstep, voffA);
;             PG8_WAIT_V(8); PG8_WAIT_L(0); PG8_BAR; PG8_MMA(0, 0, At, B0); PG8_MMA(0, 1, At, B1); PG8_BAR; PG8_SCHED;
	s_setprio 1
	s_waitcnt lgkmcnt(0)
	v_mfma_f32_16x16x32_bf16 v[94:97], v[130:133], v[190:193], v[94:97]
	v_mfma_f32_16x16x32_bf16 v[90:93], v[138:141], v[190:193], v[90:93]
	v_mfma_f32_16x16x32_bf16 v[86:89], v[130:133], v[198:201], v[86:89]
	v_mfma_f32_16x16x32_bf16 v[82:85], v[138:141], v[198:201], v[82:85]
	v_mfma_f32_16x16x32_bf16 v[78:81], v[130:133], v[210:213], v[78:81]
	v_mfma_f32_16x16x32_bf16 v[74:77], v[138:141], v[210:213], v[74:77]
	v_mfma_f32_16x16x32_bf16 v[70:73], v[130:133], v[218:221], v[70:73]
	v_mfma_f32_16x16x32_bf16 v[66:69], v[138:141], v[218:221], v[66:69]
	v_mfma_f32_16x16x32_bf16 v[94:97], v[134:137], v[194:197], v[94:97]
	v_mfma_f32_16x16x32_bf16 v[90:93], v[166:169], v[194:197], v[90:93]
	v_mfma_f32_16x16x32_bf16 v[86:89], v[134:137], v[206:209], v[86:89]
	v_mfma_f32_16x16x32_bf16 v[82:85], v[166:169], v[206:209], v[82:85]
	v_mfma_f32_16x16x32_bf16 v[78:81], v[134:137], v[214:217], v[78:81]
	v_mfma_f32_16x16x32_bf16 v[74:77], v[166:169], v[214:217], v[74:77]
	v_mfma_f32_16x16x32_bf16 v[70:73], v[134:137], v[222:225], v[70:73]
	v_mfma_f32_16x16x32_bf16 v[66:69], v[166:169], v[222:225], v[66:69]
	s_setprio 0
	s_setprio 1
	v_mfma_f32_16x16x32_bf16 v[30:33], v[170:173], v[190:193], v[30:33]
	v_mfma_f32_16x16x32_bf16 v[26:29], v[178:181], v[190:193], v[26:29]
	v_mfma_f32_16x16x32_bf16 v[22:25], v[170:173], v[198:201], v[22:25]
	v_mfma_f32_16x16x32_bf16 v[18:21], v[178:181], v[198:201], v[18:21]
	v_mfma_f32_16x16x32_bf16 v[14:17], v[170:173], v[210:213], v[14:17]
	v_mfma_f32_16x16x32_bf16 v[10:13], v[178:181], v[210:213], v[10:13]
	v_mfma_f32_16x16x32_bf16 v[6:9], v[170:173], v[218:221], v[6:9]
	v_mfma_f32_16x16x32_bf16 v[2:5], v[178:181], v[218:221], v[2:5]
	v_mfma_f32_16x16x32_bf16 v[30:33], v[174:177], v[194:197], v[30:33]
	v_mfma_f32_16x16x32_bf16 v[26:29], v[182:185], v[194:197], v[26:29]
	v_mfma_f32_16x16x32_bf16 v[22:25], v[174:177], v[206:209], v[22:25]
	v_mfma_f32_16x16x32_bf16 v[18:21], v[182:185], v[206:209], v[18:21]
	s_setprio 2
	s_barrier
	v_mfma_f32_16x16x32_bf16 v[14:17], v[174:177], v[214:217], v[14:17]
	v_mfma_f32_16x16x32_bf16 v[10:13], v[182:185], v[214:217], v[10:13]
	v_mfma_f32_16x16x32_bf16 v[6:9], v[174:177], v[222:225], v[6:9]
	v_mfma_f32_16x16x32_bf16 v[2:5], v[182:185], v[222:225], v[2:5]
	s_setprio 0
	s_add_i32 s94, 0, 0x18000
	v_add_u32_e32 v152, s94, v155
	s_add_i32 s95, 0, 0x1c000
	ds_read_b128 v[130:133], v152
	ds_read_b128 v[134:137], v152 offset:1024
	ds_read_b128 v[138:141], v152 offset:2048
	ds_read_b128 v[166:169], v152 offset:3072
	v_add_u32_e32 v152, s95, v155
	ds_read_b128 v[170:173], v152
	ds_read_b128 v[174:177], v152 offset:1024
	ds_read_b128 v[178:181], v152 offset:2048
	ds_read_b128 v[182:185], v152 offset:3072
	s_add_u32 s30, s80, 0x40000
	s_addc_u32 s31, s81, 0
	s_mov_b32 m0, s50
	v_lshl_add_u64 v[232:233], s[30:31], 0, v[144:145]
	ds_read_b128 v[190:193], v188 offset:32768
	ds_read_b128 v[194:197], v188 offset:33792
	ds_read_b128 v[198:201], v188 offset:34816
	ds_read_b128 v[206:209], v188 offset:35840
	ds_read_b128 v[210:213], v188 offset:36864
	ds_read_b128 v[214:217], v188 offset:37888
	ds_read_b128 v[218:221], v188 offset:38912
	ds_read_b128 v[222:225], v188 offset:39936
	global_load_lds_dwordx4 v[232:233], off
	v_lshl_add_u64 v[232:233], s[30:31], 0, v[148:149]
	s_mov_b32 m0, s51
	s_nop 0
	global_load_lds_dwordx4 v[232:233], off
	s_waitcnt vmcnt(8)
	s_waitcnt lgkmcnt(0)
	s_barrier
	s_setprio 1
	s_waitcnt lgkmcnt(0)
	v_mfma_f32_16x16x32_bf16 v[126:129], v[130:133], v[190:193], v[126:129]
	v_mfma_f32_16x16x32_bf16 v[122:125], v[138:141], v[190:193], v[122:125]
	v_mfma_f32_16x16x32_bf16 v[118:121], v[130:133], v[198:201], v[118:121]
	v_mfma_f32_16x16x32_bf16 v[114:117], v[138:141], v[198:201], v[114:117]
	v_mfma_f32_16x16x32_bf16 v[110:113], v[130:133], v[210:213], v[110:113]
	v_mfma_f32_16x16x32_bf16 v[106:109], v[138:141], v[210:213], v[106:109]
	v_mfma_f32_16x16x32_bf16 v[102:105], v[130:133], v[218:221], v[102:105]
	v_mfma_f32_16x16x32_bf16 v[98:101], v[138:141], v[218:221], v[98:101]
	v_mfma_f32_16x16x32_bf16 v[126:129], v[134:137], v[194:197], v[126:129]
	v_mfma_f32_16x16x32_bf16 v[122:125], v[166:169], v[194:197], v[122:125]
	v_mfma_f32_16x16x32_bf16 v[118:121], v[134:137], v[206:209], v[118:121]
	v_mfma_f32_16x16x32_bf16 v[114:117], v[166:169], v[206:209], v[114:117]
	v_mfma_f32_16x16x32_bf16 v[110:113], v[134:137], v[214:217], v[110:113]
	v_mfma_f32_16x16x32_bf16 v[106:109], v[166:169], v[214:217], v[106:109]
	v_mfma_f32_16x16x32_bf16 v[102:105], v[134:137], v[222:225], v[102:105]
	v_mfma_f32_16x16x32_bf16 v[98:101], v[166:169], v[222:225], v[98:101]
	s_setprio 0
	s_setprio 1
	v_mfma_f32_16x16x32_bf16 v[62:65], v[170:173], v[190:193], v[62:65]
	v_mfma_f32_16x16x32_bf16 v[58:61], v[178:181], v[190:193], v[58:61]
	v_mfma_f32_16x16x32_bf16 v[54:57], v[170:173], v[198:201], v[54:57]
	v_mfma_f32_16x16x32_bf16 v[50:53], v[178:181], v[198:201], v[50:53]
	v_mfma_f32_16x16x32_bf16 v[46:49], v[170:173], v[210:213], v[46:49]
	v_mfma_f32_16x16x32_bf16 v[42:45], v[178:181], v[210:213], v[42:45]
	v_mfma_f32_16x16x32_bf16 v[38:41], v[170:173], v[218:221], v[38:41]
	v_mfma_f32_16x16x32_bf16 v[34:37], v[178:181], v[218:221], v[34:37]
	v_mfma_f32_16x16x32_bf16 v[62:65], v[174:177], v[194:197], v[62:65]
	v_mfma_f32_16x16x32_bf16 v[58:61], v[182:185], v[194:197], v[58:61]
	v_mfma_f32_16x16x32_bf16 v[54:57], v[174:177], v[206:209], v[54:57]
	v_mfma_f32_16x16x32_bf16 v[50:53], v[182:185], v[206:209], v[50:53]
	s_setprio 2
	s_barrier
; #define PG8_STAGE(bufoff, gbase, voff) do { _Pragma("unroll") for (int _i = 0; _i < 2; ++_i) \
;         __builtin_amdgcn_global_load_lds((const unsigned*)((const char*)(gbase) + (voff)[_i]), (PG8_LAS unsigned*)(lds + (bufoff) + ldsw + _i * 8192), 16, 0, 0); } while (0)
; #define PG8_LDA(dst, b, h) do { _Pragma("unroll") for (int m = 0; m < 4; ++m) _Pragma("unroll") for (int k = 0; k < 2; ++k) dst[m][k] = *(const PG8_LAS bf16x8*)(lds + PG8_SA(b, h) + aoff + m * 2048 + k * 1024); } while (0)
; #define PG8_MMA(ai, bj, At, Bt) do { __builtin_amdgcn_s_setprio(1); _Pragma("unroll") for (int m = 0; m < 4; ++m) _Pragma("unroll") for (int n = 0; n < 2; ++n) _Pragma("unroll") for (int k = 0; k < 2; ++k) \
;         acc[ai][bj][m][n] = __builtin_amdgcn_mfma_f32_16x16x32_bf16(Bt[n][k], At[m][k], acc[ai][bj][m][n], 0, 0, 0); __builtin_amdgcn_s_setprio(0); } while (0)
; #define PG8_WAIT_V(n) asm volatile("s_waitcnt vmcnt(" #n ")" ::: "memory")
; #define PG8_WAIT_L(n) asm volatile("s_waitcnt lgkmcnt(" #n ")" ::: "memory")
; #define PG8_BAR __builtin_amdgcn_s_barrier()
; #define PG8_SCHED __builtin_amdgcn_sched_barrier(0)
; template <class Epi, class Sched, bool ALIGN_EPI = false, bool SP2 = false>
; __device__ __forceinline__ void gemm_phase(PG8_LAS unsigned char* lds, const Gemm g, const Sched& S, const Epi& E) {
;     ...
;         for (int t = 0; t < nt; t += 2) {
;             const bool last = (t == nt - 2);
;             const char* a1 = cA + (size_t)(t + 1) * kstep;
;             const char* a2 = last ? nA : cA + (size_t)(t + 2) * kstep; const char* b2 = last ? nB : cB + (size_t)(t + 2) * kstep;
;             const char* a3 = a2 + kstep; const char* b3 = b2 + kstep;
;     ...
;             PG8_WAIT_V(8); PG8_WAIT_L(0); PG8_BAR; PG8_MMA(0, 0, At, B0); PG8_MMA(0, 1, At, B1); PG8_BAR; PG8_SCHED;
;             PG8_LDA(At, 1, 1); PG8_STAGE(PG8_SB(1, 0), b3, voffB); PG8_STAGE(PG8_SB(1, 1), b3 + hstep, voffB); PG8_STAGE(PG8_SA(1, 0), a3, voffA);
;             PG8_WAIT_V(8); PG8_WAIT_L(0); PG8_BAR; PG8_MMA(1, 0, At, B0); PG8_MMA(1, 1, At, B1); PG8_BAR; PG8_SCHED;
;     ...
;         if constexpr (ALIGN_EPI) { if (wr == 0) PG8_BAR; }
	v_mfma_f32_16x16x32_bf16 v[46:49], v[174:177], v[214:217], v[46:49]
	v_mfma_f32_16x16x32_bf16 v[42:45], v[182:185], v[214:217], v[42:45]
	v_mfma_f32_16x16x32_bf16 v[38:41], v[174:177], v[222:225], v[38:41]
	v_mfma_f32_16x16x32_bf16 v[34:37], v[182:185], v[222:225], v[34:37]
	s_setprio 0
	s_add_i32 s30, s94, s97
	v_lshl_add_u64 v[202:203], v[202:203], 0, s[40:41]
	s_mov_b32 m0, s30
	ds_read_b128 v[190:193], v188 offset:49152
	ds_read_b128 v[194:197], v188 offset:50176
	ds_read_b128 v[198:201], v188 offset:51200
	ds_read_b128 v[206:209], v188 offset:52224
	ds_read_b128 v[210:213], v188 offset:53248
	ds_read_b128 v[214:217], v188 offset:54272
	ds_read_b128 v[218:221], v188 offset:55296
	ds_read_b128 v[222:225], v188 offset:56320
	global_load_lds_dwordx4 v[202:203], off
	s_add_i32 m0, s30, 0x2000
	s_add_u32 s30, s78, 0x40080
	v_lshl_add_u64 v[202:203], v[226:227], 0, s[40:41]
	s_addc_u32 s31, s79, 0
	s_add_i32 s78, s95, s97
	global_load_lds_dwordx4 v[202:203], off
	v_lshl_add_u64 v[202:203], s[30:31], 0, v[146:147]
	s_mov_b32 m0, s78
	s_nop 0
	global_load_lds_dwordx4 v[202:203], off
	v_lshl_add_u64 v[202:203], s[30:31], 0, v[150:151]
	s_add_i32 m0, s78, 0x2000
	s_nop 0
	global_load_lds_dwordx4 v[202:203], off
	v_lshl_add_u64 v[202:203], v[228:229], 0, s[40:41]
	s_mov_b32 m0, s57
	s_nop 0
	global_load_lds_dwordx4 v[202:203], off
	v_lshl_add_u64 v[202:203], v[230:231], 0, s[40:41]
	s_mov_b32 m0, s58
	s_nop 0
	global_load_lds_dwordx4 v[202:203], off
	s_waitcnt vmcnt(8)
	s_waitcnt lgkmcnt(0)
	s_barrier
	s_setprio 1
	s_waitcnt lgkmcnt(0)
	v_mfma_f32_16x16x32_bf16 v[94:97], v[130:133], v[190:193], v[94:97]
	v_mfma_f32_16x16x32_bf16 v[90:93], v[138:141], v[190:193], v[90:93]
	v_mfma_f32_16x16x32_bf16 v[86:89], v[130:133], v[198:201], v[86:89]
	v_mfma_f32_16x16x32_bf16 v[82:85], v[138:141], v[198:201], v[82:85]
	v_mfma_f32_16x16x32_bf16 v[78:81], v[130:133], v[210:213], v[78:81]
	v_mfma_f32_16x16x32_bf16 v[74:77], v[138:141], v[210:213], v[74:77]
	v_mfma_f32_16x16x32_bf16 v[70:73], v[130:133], v[218:221], v[70:73]
	v_mfma_f32_16x16x32_bf16 v[66:69], v[138:141], v[218:221], v[66:69]
	v_mfma_f32_16x16x32_bf16 v[94:97], v[134:137], v[194:197], v[94:97]
	v_mfma_f32_16x16x32_bf16 v[90:93], v[166:169], v[194:197], v[90:93]
	v_mfma_f32_16x16x32_bf16 v[86:89], v[134:137], v[206:209], v[86:89]
	v_mfma_f32_16x16x32_bf16 v[82:85], v[166:169], v[206:209], v[82:85]
	v_mfma_f32_16x16x32_bf16 v[78:81], v[134:137], v[214:217], v[78:81]
	v_mfma_f32_16x16x32_bf16 v[74:77], v[166:169], v[214:217], v[74:77]
	v_mfma_f32_16x16x32_bf16 v[70:73], v[134:137], v[222:225], v[70:73]
	v_mfma_f32_16x16x32_bf16 v[66:69], v[166:169], v[222:225], v[66:69]
	s_setprio 0
	s_setprio 1
	v_mfma_f32_16x16x32_bf16 v[30:33], v[170:173], v[190:193], v[30:33]
	v_mfma_f32_16x16x32_bf16 v[26:29], v[178:181], v[190:193], v[26:29]
	v_mfma_f32_16x16x32_bf16 v[22:25], v[170:173], v[198:201], v[22:25]
	v_mfma_f32_16x16x32_bf16 v[18:21], v[178:181], v[198:201], v[18:21]
	v_mfma_f32_16x16x32_bf16 v[14:17], v[170:173], v[210:213], v[14:17]
	v_mfma_f32_16x16x32_bf16 v[10:13], v[178:181], v[210:213], v[10:13]
	v_mfma_f32_16x16x32_bf16 v[6:9], v[170:173], v[218:221], v[6:9]
	v_mfma_f32_16x16x32_bf16 v[2:5], v[178:181], v[218:221], v[2:5]
	v_mfma_f32_16x16x32_bf16 v[30:33], v[174:177], v[194:197], v[30:33]
	v_mfma_f32_16x16x32_bf16 v[26:29], v[182:185], v[194:197], v[26:29]
	v_mfma_f32_16x16x32_bf16 v[22:25], v[174:177], v[206:209], v[22:25]
	v_mfma_f32_16x16x32_bf16 v[18:21], v[182:185], v[206:209], v[18:21]
	s_setprio 2
	s_barrier
	v_mfma_f32_16x16x32_bf16 v[14:17], v[174:177], v[214:217], v[14:17]
	v_mfma_f32_16x16x32_bf16 v[10:13], v[182:185], v[214:217], v[10:13]
	v_mfma_f32_16x16x32_bf16 v[6:9], v[174:177], v[222:225], v[6:9]
	v_mfma_f32_16x16x32_bf16 v[2:5], v[182:185], v[222:225], v[2:5]
	s_setprio 0
	s_add_i32 s75, s75, 2
	s_add_u32 s76, s76, 0x100
	s_addc_u32 s77, s77, 0
	s_add_u32 s61, s61, 0x100
	s_addc_u32 s63, s63, 0
	s_cmp_gt_u32 s75, 13
	s_cbranch_scc0 .LBB0_215
	s_and_b64 vcc, exec, s[44:45]
	s_cbranch_vccz .LBB0_218
	s_barrier

; #define PG8_STAGE(bufoff, gbase, voff) do { _Pragma("unroll") for (int _i = 0; _i < 2; ++_i) \
;         __builtin_amdgcn_global_load_lds((const unsigned*)((const char*)(gbase) + (voff)[_i]), (PG8_LAS unsigned*)(lds + (bufoff) + ldsw + _i * 8192), 16, 0, 0); } while (0)
; #define PG8_LDA(dst, b, h) do { _Pragma("unroll") for (int m = 0; m < 4; ++m) _Pragma("unroll") for (int k = 0; k < 2; ++k) dst[m][k] = *(const PG8_LAS bf16x8*)(lds + PG8_SA(b, h) + aoff + m * 2048 + k * 1024); } while (0)
; #define PG8_LDB(dst, b, h) do { _Pragma("unroll") for (int n = 0; n < 2; ++n) _Pragma("unroll") for (int k = 0; k < 2; ++k) dst[n][k] = *(const PG8_LAS bf16x8*)(lds + PG8_SB(b, h) + boff + n * 2048 + k * 1024); } while (0)
; #define PG8_MMA(ai, bj, At, Bt) do { __builtin_amdgcn_s_setprio(1); _Pragma("unroll") for (int m = 0; m < 4; ++m) _Pragma("unroll") for (int n = 0; n < 2; ++n) _Pragma("unroll") for (int k = 0; k < 2; ++k) \
;         acc[ai][bj][m][n] = __builtin_amdgcn_mfma_f32_16x16x32_bf16(Bt[n][k], At[m][k], acc[ai][bj][m][n], 0, 0, 0); __builtin_amdgcn_s_setprio(0); } while (0)
; #define PG8_WAIT_V(n) asm volatile("s_waitcnt vmcnt(" #n ")" ::: "memory")
; #define PG8_WAIT_L(n) asm volatile("s_waitcnt lgkmcnt(" #n ")" ::: "memory")
; #define PG8_BAR __builtin_amdgcn_s_barrier()
; #define PG8_SCHED __builtin_amdgcn_sched_barrier(0)
; template <class Epi, class Sched, bool ALIGN_EPI = false, bool SP2 = false>
; __device__ __forceinline__ void gemm_phase(PG8_LAS unsigned char* lds, const Gemm g, const Sched& S, const Epi& E) {
;     ...
;             const bool last = (t == nt - 2);
;             const char* a1 = cA + (size_t)(t + 1) * kstep;
;             const char* a2 = last ? nA : cA + (size_t)(t + 2) * kstep; const char* b2 = last ? nB : cB + (size_t)(t + 2) * kstep;
;             const char* a3 = a2 + kstep; const char* b3 = b2 + kstep;
;             if (last && has_next) S.a_ready(nxt);
;             if constexpr (SP2) {
;             PG8_LDB(B0, 0, 0); PG8_LDB(B1, 0, 1); PG8_SCHED; PG8_LDA(At, 0, 0); PG8_STAGE(PG8_SA(1, 1), a1 + hstep, voffA);
;             PG8_WAIT_V(8); PG8_WAIT_L(0); PG8_BAR; PG8_MMA(0, 0, At, B0); PG8_MMA(0, 1, At, B1); PG8_BAR; PG8_SCHED;
;             PG8_LDA(At, 0, 1); PG8_STAGE(PG8_SB(0, 0), b2, voffB); PG8_STAGE(PG8_SB(0, 1), b2 + hstep, voffB); PG8_STAGE(PG8_SA(0, 0), a2, voffA);
.LBB0_752:
	ds_read_b128 v[122:125], v184
	ds_read_b128 v[126:129], v184 offset:1024
	ds_read_b128 v[130:133], v184 offset:2048
	ds_read_b128 v[134:137], v184 offset:3072
	ds_read_b128 v[138:141], v185
	ds_read_b128 v[142:145], v185 offset:1024
	ds_read_b128 v[150:153], v185 offset:2048
	ds_read_b128 v[154:157], v185 offset:3072
	s_add_u32 s30, s26, 0xfffc0080
	s_addc_u32 s31, s27, -1
	s_cmp_eq_u32 s64, 12
	s_cselect_b32 s41, s19, s31
	s_cselect_b32 s40, s60, s30
	s_cselect_b32 s39, s17, s63
	s_cselect_b32 s38, s61, s62
	v_lshl_add_u64 v[218:219], s[26:27], 0, v[170:171]
	s_add_i32 m0, s25, 0xc000
	ds_read_b128 v[178:181], v186
	ds_read_b128 v[188:191], v186 offset:1024
	ds_read_b128 v[192:195], v186 offset:2048
	ds_read_b128 v[196:199], v186 offset:3072
	ds_read_b128 v[200:203], v186 offset:4096
	ds_read_b128 v[206:209], v186 offset:5120
	ds_read_b128 v[210:213], v186 offset:6144
	ds_read_b128 v[214:217], v186 offset:7168
	global_load_lds_dwordx4 v[218:219], off
	v_lshl_add_u64 v[218:219], s[26:27], 0, v[172:173]
	s_add_i32 m0, s25, 0xe000
	s_nop 0
	global_load_lds_dwordx4 v[218:219], off
	s_waitcnt vmcnt(8)
	s_waitcnt lgkmcnt(0)
	s_barrier
	s_setprio 1
	s_waitcnt lgkmcnt(0)
	v_mfma_f32_16x16x32_bf16 v[158:161], v[122:125], v[178:181], v[158:161]
	v_mfma_f32_16x16x32_bf16 v[146:149], v[130:133], v[178:181], v[146:149]
	v_mfma_f32_16x16x32_bf16 v[114:117], v[122:125], v[192:195], v[114:117]
	v_mfma_f32_16x16x32_bf16 v[106:109], v[130:133], v[192:195], v[106:109]
	v_mfma_f32_16x16x32_bf16 v[94:97], v[122:125], v[200:203], v[94:97]
	v_mfma_f32_16x16x32_bf16 v[90:93], v[130:133], v[200:203], v[90:93]
	v_mfma_f32_16x16x32_bf16 v[82:85], v[122:125], v[210:213], v[82:85]
	v_mfma_f32_16x16x32_bf16 v[74:77], v[130:133], v[210:213], v[74:77]
	v_mfma_f32_16x16x32_bf16 v[158:161], v[126:129], v[188:191], v[158:161]
	v_mfma_f32_16x16x32_bf16 v[146:149], v[134:137], v[188:191], v[146:149]
	v_mfma_f32_16x16x32_bf16 v[114:117], v[126:129], v[196:199], v[114:117]
	v_mfma_f32_16x16x32_bf16 v[106:109], v[134:137], v[196:199], v[106:109]
	v_mfma_f32_16x16x32_bf16 v[94:97], v[126:129], v[206:209], v[94:97]
	v_mfma_f32_16x16x32_bf16 v[90:93], v[134:137], v[206:209], v[90:93]
	v_mfma_f32_16x16x32_bf16 v[82:85], v[126:129], v[214:217], v[82:85]
	v_mfma_f32_16x16x32_bf16 v[74:77], v[134:137], v[214:217], v[74:77]
	s_setprio 0
	s_setprio 1
	v_mfma_f32_16x16x32_bf16 v[118:121], v[138:141], v[178:181], v[118:121]
	v_mfma_f32_16x16x32_bf16 v[110:113], v[150:153], v[178:181], v[110:113]
	v_mfma_f32_16x16x32_bf16 v[102:105], v[138:141], v[192:195], v[102:105]
	v_mfma_f32_16x16x32_bf16 v[98:101], v[150:153], v[192:195], v[98:101]
	v_mfma_f32_16x16x32_bf16 v[86:89], v[138:141], v[200:203], v[86:89]
	v_mfma_f32_16x16x32_bf16 v[78:81], v[150:153], v[200:203], v[78:81]
	v_mfma_f32_16x16x32_bf16 v[70:73], v[138:141], v[210:213], v[70:73]
	v_mfma_f32_16x16x32_bf16 v[66:69], v[150:153], v[210:213], v[66:69]
	v_mfma_f32_16x16x32_bf16 v[118:121], v[142:145], v[188:191], v[118:121]
	v_mfma_f32_16x16x32_bf16 v[110:113], v[154:157], v[188:191], v[110:113]
	v_mfma_f32_16x16x32_bf16 v[102:105], v[142:145], v[196:199], v[102:105]
	v_mfma_f32_16x16x32_bf16 v[98:101], v[154:157], v[196:199], v[98:101]
	s_setprio 2
	s_barrier
	v_mfma_f32_16x16x32_bf16 v[86:89], v[142:145], v[206:209], v[86:89]
	v_mfma_f32_16x16x32_bf16 v[78:81], v[154:157], v[206:209], v[78:81]
	v_mfma_f32_16x16x32_bf16 v[70:73], v[142:145], v[214:217], v[70:73]
	v_mfma_f32_16x16x32_bf16 v[66:69], v[154:157], v[214:217], v[66:69]
	s_setprio 0
	s_add_i32 s30, s57, s33
	v_lshl_add_u64 v[218:219], s[38:39], 0, v[164:165]
	s_mov_b32 m0, s30
	ds_read_b128 v[178:181], v186 offset:16384
	ds_read_b128 v[188:191], v186 offset:17408
	ds_read_b128 v[192:195], v186 offset:18432
	ds_read_b128 v[196:199], v186 offset:19456
	ds_read_b128 v[200:203], v186 offset:20480
	ds_read_b128 v[206:209], v186 offset:21504
	ds_read_b128 v[210:213], v186 offset:22528
	ds_read_b128 v[214:217], v186 offset:23552
	global_load_lds_dwordx4 v[218:219], off
	s_add_i32 m0, s30, 0x2000
	s_add_u32 s30, s38, 0x40000
	v_lshl_add_u64 v[220:221], s[38:39], 0, v[168:169]
	s_addc_u32 s31, s39, 0
	s_add_i32 s65, s58, s33
	global_load_lds_dwordx4 v[220:221], off
	v_lshl_add_u64 v[222:223], s[30:31], 0, v[164:165]
	s_mov_b32 m0, s65
	v_lshl_add_u64 v[224:225], s[40:41], 0, v[166:167]
	global_load_lds_dwordx4 v[222:223], off
	v_lshl_add_u64 v[222:223], s[30:31], 0, v[168:169]
	s_add_i32 m0, s65, 0x2000
	s_nop 0
	global_load_lds_dwordx4 v[222:223], off
	v_lshl_add_u64 v[222:223], s[40:41], 0, v[162:163]
	s_mov_b32 m0, s25
	s_nop 0
	global_load_lds_dwordx4 v[222:223], off
	s_mov_b32 m0, s44
	s_nop 0
	global_load_lds_dwordx4 v[224:225], off
	s_waitcnt vmcnt(8)
	s_waitcnt lgkmcnt(0)
	s_barrier
; #define PG8_STAGE(bufoff, gbase, voff) do { _Pragma("unroll") for (int _i = 0; _i < 2; ++_i) \
;         __builtin_amdgcn_global_load_lds((const unsigned*)((const char*)(gbase) + (voff)[_i]), (PG8_LAS unsigned*)(lds + (bufoff) + ldsw + _i * 8192), 16, 0, 0); } while (0)
; #define PG8_LDA(dst, b, h) do { _Pragma("unroll") for (int m = 0; m < 4; ++m) _Pragma("unroll") for (int k = 0; k < 2; ++k) dst[m][k] = *(const PG8_LAS bf16x8*)(lds + PG8_SA(b, h) + aoff + m * 2048 + k * 1024); } while (0)
; #define PG8_LDB(dst, b, h) do { _Pragma("unroll") for (int n = 0; n < 2; ++n) _Pragma("unroll") for (int k = 0; k < 2; ++k) dst[n][k] = *(const PG8_LAS bf16x8*)(lds + PG8_SB(b, h) + boff + n * 2048 + k * 1024); } while (0)
; #define PG8_MMA(ai, bj, At, Bt) do { __builtin_amdgcn_s_setprio(1); _Pragma("unroll") for (int m = 0; m < 4; ++m) _Pragma("unroll") for (int n = 0; n < 2; ++n) _Pragma("unroll") for (int k = 0; k < 2; ++k) \
;         acc[ai][bj][m][n] = __builtin_amdgcn_mfma_f32_16x16x32_bf16(Bt[n][k], At[m][k], acc[ai][bj][m][n], 0, 0, 0); __builtin_amdgcn_s_setprio(0); } while (0)
; #define PG8_WAIT_V(n) asm volatile("s_waitcnt vmcnt(" #n ")" ::: "memory")
; #define PG8_WAIT_L(n) asm volatile("s_waitcnt lgkmcnt(" #n ")" ::: "memory")
; #define PG8_BAR __builtin_amdgcn_s_barrier()
; #define PG8_SCHED __builtin_amdgcn_sched_barrier(0)
; template <class Epi, class Sched, bool ALIGN_EPI = false, bool SP2 = false>
; __device__ __forceinline__ void gemm_phase(PG8_LAS unsigned char* lds, const Gemm g, const Sched& S, const Epi& E) {
;     ...
;             PG8_WAIT_V(8); PG8_WAIT_L(0); PG8_BAR; PG8_MMA(1, 0, At, B0); PG8_MMA(1, 1, At, B1); PG8_BAR; PG8_SCHED;
;             PG8_LDB(B0, 1, 0); PG8_LDB(B1, 1, 1); PG8_SCHED; PG8_LDA(At, 1, 0); PG8_STAGE(PG8_SA(0, 1), a2 + hstep, voffA);
;             PG8_WAIT_V(8); PG8_WAIT_L(0); PG8_BAR; PG8_MMA(0, 0, At, B0); PG8_MMA(0, 1, At, B1); PG8_BAR; PG8_SCHED;
	s_setprio 1
	s_waitcnt lgkmcnt(0)
	v_mfma_f32_16x16x32_bf16 v[62:65], v[122:125], v[178:181], v[62:65]
	v_mfma_f32_16x16x32_bf16 v[58:61], v[130:133], v[178:181], v[58:61]
	v_mfma_f32_16x16x32_bf16 v[50:53], v[122:125], v[192:195], v[50:53]
	v_mfma_f32_16x16x32_bf16 v[42:45], v[130:133], v[192:195], v[42:45]
	v_mfma_f32_16x16x32_bf16 v[30:33], v[122:125], v[200:203], v[30:33]
	v_mfma_f32_16x16x32_bf16 v[26:29], v[130:133], v[200:203], v[26:29]
	v_mfma_f32_16x16x32_bf16 v[18:21], v[122:125], v[210:213], v[18:21]
	v_mfma_f32_16x16x32_bf16 v[10:13], v[130:133], v[210:213], v[10:13]
	v_mfma_f32_16x16x32_bf16 v[62:65], v[126:129], v[188:191], v[62:65]
	v_mfma_f32_16x16x32_bf16 v[58:61], v[134:137], v[188:191], v[58:61]
	v_mfma_f32_16x16x32_bf16 v[50:53], v[126:129], v[196:199], v[50:53]
	v_mfma_f32_16x16x32_bf16 v[42:45], v[134:137], v[196:199], v[42:45]
	v_mfma_f32_16x16x32_bf16 v[30:33], v[126:129], v[206:209], v[30:33]
	v_mfma_f32_16x16x32_bf16 v[26:29], v[134:137], v[206:209], v[26:29]
	v_mfma_f32_16x16x32_bf16 v[18:21], v[126:129], v[214:217], v[18:21]
	v_mfma_f32_16x16x32_bf16 v[10:13], v[134:137], v[214:217], v[10:13]
	s_setprio 0
	s_setprio 1
	v_mfma_f32_16x16x32_bf16 v[54:57], v[138:141], v[178:181], v[54:57]
	v_mfma_f32_16x16x32_bf16 v[46:49], v[150:153], v[178:181], v[46:49]
	v_mfma_f32_16x16x32_bf16 v[38:41], v[138:141], v[192:195], v[38:41]
	v_mfma_f32_16x16x32_bf16 v[34:37], v[150:153], v[192:195], v[34:37]
	v_mfma_f32_16x16x32_bf16 v[22:25], v[138:141], v[200:203], v[22:25]
	v_mfma_f32_16x16x32_bf16 v[14:17], v[150:153], v[200:203], v[14:17]
	v_mfma_f32_16x16x32_bf16 v[6:9], v[138:141], v[210:213], v[6:9]
	v_mfma_f32_16x16x32_bf16 v[2:5], v[150:153], v[210:213], v[2:5]
	v_mfma_f32_16x16x32_bf16 v[54:57], v[142:145], v[188:191], v[54:57]
	v_mfma_f32_16x16x32_bf16 v[46:49], v[154:157], v[188:191], v[46:49]
	v_mfma_f32_16x16x32_bf16 v[38:41], v[142:145], v[196:199], v[38:41]
	v_mfma_f32_16x16x32_bf16 v[34:37], v[154:157], v[196:199], v[34:37]
	s_setprio 2
	s_barrier
	v_mfma_f32_16x16x32_bf16 v[22:25], v[142:145], v[206:209], v[22:25]
	v_mfma_f32_16x16x32_bf16 v[14:17], v[154:157], v[206:209], v[14:17]
	v_mfma_f32_16x16x32_bf16 v[6:9], v[142:145], v[214:217], v[6:9]
	v_mfma_f32_16x16x32_bf16 v[2:5], v[154:157], v[214:217], v[2:5]
	s_setprio 0
	s_add_i32 s65, 0, 0x18000
	s_add_i32 s66, 0, 0x1c000
	v_add_u32_e32 v134, s65, v182
	v_add_u32_e32 v154, s66, v182
	ds_read_b128 v[122:125], v134
	ds_read_b128 v[126:129], v134 offset:1024
	ds_read_b128 v[130:133], v134 offset:2048
	ds_read_b128 v[134:137], v134 offset:3072
	ds_read_b128 v[138:141], v154
	ds_read_b128 v[142:145], v154 offset:1024
	ds_read_b128 v[150:153], v154 offset:2048
	ds_read_b128 v[154:157], v154 offset:3072
	s_add_u32 s30, s40, 0x40000
	s_addc_u32 s31, s41, 0
	s_mov_b32 m0, s45
	v_lshl_add_u64 v[226:227], s[30:31], 0, v[162:163]
	ds_read_b128 v[178:181], v186 offset:32768
	ds_read_b128 v[188:191], v186 offset:33792
	ds_read_b128 v[192:195], v186 offset:34816
	ds_read_b128 v[196:199], v186 offset:35840
	ds_read_b128 v[200:203], v186 offset:36864
	ds_read_b128 v[206:209], v186 offset:37888
	ds_read_b128 v[210:213], v186 offset:38912
	ds_read_b128 v[214:217], v186 offset:39936
	global_load_lds_dwordx4 v[226:227], off
	v_lshl_add_u64 v[226:227], s[30:31], 0, v[166:167]
	s_mov_b32 m0, s50
	s_nop 0
	global_load_lds_dwordx4 v[226:227], off
	s_waitcnt vmcnt(8)
	s_waitcnt lgkmcnt(0)
	s_barrier
	s_setprio 1
	s_waitcnt lgkmcnt(0)
	v_mfma_f32_16x16x32_bf16 v[158:161], v[122:125], v[178:181], v[158:161]
	v_mfma_f32_16x16x32_bf16 v[146:149], v[130:133], v[178:181], v[146:149]
	v_mfma_f32_16x16x32_bf16 v[114:117], v[122:125], v[192:195], v[114:117]
	v_mfma_f32_16x16x32_bf16 v[106:109], v[130:133], v[192:195], v[106:109]
	v_mfma_f32_16x16x32_bf16 v[94:97], v[122:125], v[200:203], v[94:97]
	v_mfma_f32_16x16x32_bf16 v[90:93], v[130:133], v[200:203], v[90:93]
	v_mfma_f32_16x16x32_bf16 v[82:85], v[122:125], v[210:213], v[82:85]
	v_mfma_f32_16x16x32_bf16 v[74:77], v[130:133], v[210:213], v[74:77]
	v_mfma_f32_16x16x32_bf16 v[158:161], v[126:129], v[188:191], v[158:161]
	v_mfma_f32_16x16x32_bf16 v[146:149], v[134:137], v[188:191], v[146:149]
	v_mfma_f32_16x16x32_bf16 v[114:117], v[126:129], v[196:199], v[114:117]
	v_mfma_f32_16x16x32_bf16 v[106:109], v[134:137], v[196:199], v[106:109]
	v_mfma_f32_16x16x32_bf16 v[94:97], v[126:129], v[206:209], v[94:97]
	v_mfma_f32_16x16x32_bf16 v[90:93], v[134:137], v[206:209], v[90:93]
	v_mfma_f32_16x16x32_bf16 v[82:85], v[126:129], v[214:217], v[82:85]
	v_mfma_f32_16x16x32_bf16 v[74:77], v[134:137], v[214:217], v[74:77]
	s_setprio 0
	s_setprio 1
	v_mfma_f32_16x16x32_bf16 v[118:121], v[138:141], v[178:181], v[118:121]
	v_mfma_f32_16x16x32_bf16 v[110:113], v[150:153], v[178:181], v[110:113]
	v_mfma_f32_16x16x32_bf16 v[102:105], v[138:141], v[192:195], v[102:105]
	v_mfma_f32_16x16x32_bf16 v[98:101], v[150:153], v[192:195], v[98:101]
	v_mfma_f32_16x16x32_bf16 v[86:89], v[138:141], v[200:203], v[86:89]
	v_mfma_f32_16x16x32_bf16 v[78:81], v[150:153], v[200:203], v[78:81]
	v_mfma_f32_16x16x32_bf16 v[70:73], v[138:141], v[210:213], v[70:73]
	v_mfma_f32_16x16x32_bf16 v[66:69], v[150:153], v[210:213], v[66:69]
	v_mfma_f32_16x16x32_bf16 v[118:121], v[142:145], v[188:191], v[118:121]
	v_mfma_f32_16x16x32_bf16 v[110:113], v[154:157], v[188:191], v[110:113]
	v_mfma_f32_16x16x32_bf16 v[102:105], v[142:145], v[196:199], v[102:105]
	v_mfma_f32_16x16x32_bf16 v[98:101], v[154:157], v[196:199], v[98:101]
	s_setprio 2
	s_barrier
; #define PG8_STAGE(bufoff, gbase, voff) do { _Pragma("unroll") for (int _i = 0; _i < 2; ++_i) \
;         __builtin_amdgcn_global_load_lds((const unsigned*)((const char*)(gbase) + (voff)[_i]), (PG8_LAS unsigned*)(lds + (bufoff) + ldsw + _i * 8192), 16, 0, 0); } while (0)
; #define PG8_LDA(dst, b, h) do { _Pragma("unroll") for (int m = 0; m < 4; ++m) _Pragma("unroll") for (int k = 0; k < 2; ++k) dst[m][k] = *(const PG8_LAS bf16x8*)(lds + PG8_SA(b, h) + aoff + m * 2048 + k * 1024); } while (0)
; #define PG8_MMA(ai, bj, At, Bt) do { __builtin_amdgcn_s_setprio(1); _Pragma("unroll") for (int m = 0; m < 4; ++m) _Pragma("unroll") for (int n = 0; n < 2; ++n) _Pragma("unroll") for (int k = 0; k < 2; ++k) \
;         acc[ai][bj][m][n] = __builtin_amdgcn_mfma_f32_16x16x32_bf16(Bt[n][k], At[m][k], acc[ai][bj][m][n], 0, 0, 0); __builtin_amdgcn_s_setprio(0); } while (0)
; #define PG8_WAIT_V(n) asm volatile("s_waitcnt vmcnt(" #n ")" ::: "memory")
; #define PG8_WAIT_L(n) asm volatile("s_waitcnt lgkmcnt(" #n ")" ::: "memory")
; #define PG8_BAR __builtin_amdgcn_s_barrier()
; #define PG8_SCHED __builtin_amdgcn_sched_barrier(0)
; template <class Epi, class Sched, bool ALIGN_EPI = false, bool SP2 = false>
; __device__ __forceinline__ void gemm_phase(PG8_LAS unsigned char* lds, const Gemm g, const Sched& S, const Epi& E) {
;     ...
;         for (int t = 0; t < nt; t += 2) {
;             const bool last = (t == nt - 2);
;             const char* a1 = cA + (size_t)(t + 1) * kstep;
;             const char* a2 = last ? nA : cA + (size_t)(t + 2) * kstep; const char* b2 = last ? nB : cB + (size_t)(t + 2) * kstep;
;             const char* a3 = a2 + kstep; const char* b3 = b2 + kstep;
;     ...
;             PG8_WAIT_V(8); PG8_WAIT_L(0); PG8_BAR; PG8_MMA(0, 0, At, B0); PG8_MMA(0, 1, At, B1); PG8_BAR; PG8_SCHED;
;             PG8_LDA(At, 1, 1); PG8_STAGE(PG8_SB(1, 0), b3, voffB); PG8_STAGE(PG8_SB(1, 1), b3 + hstep, voffB); PG8_STAGE(PG8_SA(1, 0), a3, voffA);
;             PG8_WAIT_V(8); PG8_WAIT_L(0); PG8_BAR; PG8_MMA(1, 0, At, B0); PG8_MMA(1, 1, At, B1); PG8_BAR; PG8_SCHED;
;     ...
;         if constexpr (ALIGN_EPI) { if (wr == 0) PG8_BAR; }
	v_mfma_f32_16x16x32_bf16 v[86:89], v[142:145], v[206:209], v[86:89]
	v_mfma_f32_16x16x32_bf16 v[78:81], v[154:157], v[206:209], v[78:81]
	v_mfma_f32_16x16x32_bf16 v[70:73], v[142:145], v[214:217], v[70:73]
	v_mfma_f32_16x16x32_bf16 v[66:69], v[154:157], v[214:217], v[66:69]
	s_setprio 0
	s_add_i32 s30, s65, s33
	v_lshl_add_u64 v[218:219], v[218:219], 0, s[10:11]
	s_mov_b32 m0, s30
	ds_read_b128 v[178:181], v186 offset:49152
	ds_read_b128 v[188:191], v186 offset:50176
	ds_read_b128 v[192:195], v186 offset:51200
	ds_read_b128 v[196:199], v186 offset:52224
	ds_read_b128 v[200:203], v186 offset:53248
	ds_read_b128 v[206:209], v186 offset:54272
	ds_read_b128 v[210:213], v186 offset:55296
	ds_read_b128 v[214:217], v186 offset:56320
	global_load_lds_dwordx4 v[218:219], off
	s_add_i32 m0, s30, 0x2000
	s_add_u32 s30, s38, 0x40080
	v_lshl_add_u64 v[218:219], v[220:221], 0, s[10:11]
	s_addc_u32 s31, s39, 0
	s_add_i32 s38, s66, s33
	global_load_lds_dwordx4 v[218:219], off
	v_lshl_add_u64 v[218:219], s[30:31], 0, v[164:165]
	s_mov_b32 m0, s38
	s_nop 0
	global_load_lds_dwordx4 v[218:219], off
	v_lshl_add_u64 v[218:219], s[30:31], 0, v[168:169]
	s_add_i32 m0, s38, 0x2000
	s_nop 0
	global_load_lds_dwordx4 v[218:219], off
	v_lshl_add_u64 v[218:219], v[222:223], 0, s[10:11]
	s_mov_b32 m0, s52
	s_nop 0
	global_load_lds_dwordx4 v[218:219], off
	v_lshl_add_u64 v[218:219], v[224:225], 0, s[10:11]
	s_mov_b32 m0, s53
	s_nop 0
	global_load_lds_dwordx4 v[218:219], off
	s_waitcnt vmcnt(8)
	s_waitcnt lgkmcnt(0)
	s_barrier
	s_setprio 1
	s_waitcnt lgkmcnt(0)
	v_mfma_f32_16x16x32_bf16 v[62:65], v[122:125], v[178:181], v[62:65]
	v_mfma_f32_16x16x32_bf16 v[58:61], v[130:133], v[178:181], v[58:61]
	v_mfma_f32_16x16x32_bf16 v[50:53], v[122:125], v[192:195], v[50:53]
	v_mfma_f32_16x16x32_bf16 v[42:45], v[130:133], v[192:195], v[42:45]
	v_mfma_f32_16x16x32_bf16 v[30:33], v[122:125], v[200:203], v[30:33]
	v_mfma_f32_16x16x32_bf16 v[26:29], v[130:133], v[200:203], v[26:29]
	v_mfma_f32_16x16x32_bf16 v[18:21], v[122:125], v[210:213], v[18:21]
	v_mfma_f32_16x16x32_bf16 v[10:13], v[130:133], v[210:213], v[10:13]
	v_mfma_f32_16x16x32_bf16 v[62:65], v[126:129], v[188:191], v[62:65]
	v_mfma_f32_16x16x32_bf16 v[58:61], v[134:137], v[188:191], v[58:61]
	v_mfma_f32_16x16x32_bf16 v[50:53], v[126:129], v[196:199], v[50:53]
	v_mfma_f32_16x16x32_bf16 v[42:45], v[134:137], v[196:199], v[42:45]
	v_mfma_f32_16x16x32_bf16 v[30:33], v[126:129], v[206:209], v[30:33]
	v_mfma_f32_16x16x32_bf16 v[26:29], v[134:137], v[206:209], v[26:29]
	v_mfma_f32_16x16x32_bf16 v[18:21], v[126:129], v[214:217], v[18:21]
	v_mfma_f32_16x16x32_bf16 v[10:13], v[134:137], v[214:217], v[10:13]
	s_setprio 0
	s_setprio 1
	v_mfma_f32_16x16x32_bf16 v[54:57], v[138:141], v[178:181], v[54:57]
	v_mfma_f32_16x16x32_bf16 v[46:49], v[150:153], v[178:181], v[46:49]
	v_mfma_f32_16x16x32_bf16 v[38:41], v[138:141], v[192:195], v[38:41]
	v_mfma_f32_16x16x32_bf16 v[34:37], v[150:153], v[192:195], v[34:37]
	v_mfma_f32_16x16x32_bf16 v[22:25], v[138:141], v[200:203], v[22:25]
	v_mfma_f32_16x16x32_bf16 v[14:17], v[150:153], v[200:203], v[14:17]
	v_mfma_f32_16x16x32_bf16 v[6:9], v[138:141], v[210:213], v[6:9]
	v_mfma_f32_16x16x32_bf16 v[2:5], v[150:153], v[210:213], v[2:5]
	v_mfma_f32_16x16x32_bf16 v[54:57], v[142:145], v[188:191], v[54:57]
	v_mfma_f32_16x16x32_bf16 v[46:49], v[154:157], v[188:191], v[46:49]
	v_mfma_f32_16x16x32_bf16 v[38:41], v[142:145], v[196:199], v[38:41]
	v_mfma_f32_16x16x32_bf16 v[34:37], v[154:157], v[196:199], v[34:37]
	s_setprio 2
	s_barrier
	v_mfma_f32_16x16x32_bf16 v[22:25], v[142:145], v[206:209], v[22:25]
	v_mfma_f32_16x16x32_bf16 v[14:17], v[154:157], v[206:209], v[14:17]
	v_mfma_f32_16x16x32_bf16 v[6:9], v[142:145], v[214:217], v[6:9]
	v_mfma_f32_16x16x32_bf16 v[2:5], v[154:157], v[214:217], v[2:5]
	s_setprio 0
	s_add_i32 s64, s64, 2
	s_add_u32 s26, s26, 0x100
	s_addc_u32 s27, s27, 0
	s_add_u32 s62, s62, 0x100
	s_addc_u32 s63, s63, 0
	s_cmp_gt_u32 s64, 13
	s_cbranch_scc0 .LBB0_752
	s_and_b64 vcc, exec, s[12:13]
	s_cbranch_vccz .LBB0_755
	s_barrier

; #define PG8_STAGE(bufoff, gbase, voff) do { _Pragma("unroll") for (int _i = 0; _i < 2; ++_i) \
;         __builtin_amdgcn_global_load_lds((const unsigned*)((const char*)(gbase) + (voff)[_i]), (PG8_LAS unsigned*)(lds + (bufoff) + ldsw + _i * 8192), 16, 0, 0); } while (0)
; #define PG8_LDA(dst, b, h) do { _Pragma("unroll") for (int m = 0; m < 4; ++m) _Pragma("unroll") for (int k = 0; k < 2; ++k) dst[m][k] = *(const PG8_LAS bf16x8*)(lds + PG8_SA(b, h) + aoff + m * 2048 + k * 1024); } while (0)
; #define PG8_LDB(dst, b, h) do { _Pragma("unroll") for (int n = 0; n < 2; ++n) _Pragma("unroll") for (int k = 0; k < 2; ++k) dst[n][k] = *(const PG8_LAS bf16x8*)(lds + PG8_SB(b, h) + boff + n * 2048 + k * 1024); } while (0)
; #define PG8_MMA(ai, bj, At, Bt) do { __builtin_amdgcn_s_setprio(1); _Pragma("unroll") for (int m = 0; m < 4; ++m) _Pragma("unroll") for (int n = 0; n < 2; ++n) _Pragma("unroll") for (int k = 0; k < 2; ++k) \
;         acc[ai][bj][m][n] = __builtin_amdgcn_mfma_f32_16x16x32_bf16(Bt[n][k], At[m][k], acc[ai][bj][m][n], 0, 0, 0); __builtin_amdgcn_s_setprio(0); } while (0)
; #define PG8_WAIT_V(n) asm volatile("s_waitcnt vmcnt(" #n ")" ::: "memory")
; #define PG8_WAIT_L(n) asm volatile("s_waitcnt lgkmcnt(" #n ")" ::: "memory")
; #define PG8_BAR __builtin_amdgcn_s_barrier()
; #define PG8_SCHED __builtin_amdgcn_sched_barrier(0)
; template <class Epi, class Sched, bool ALIGN_EPI = false, bool SP2 = false>
; __device__ __forceinline__ void gemm_phase(PG8_LAS unsigned char* lds, const Gemm g, const Sched& S, const Epi& E) {
;     ...
;             const bool last = (t == nt - 2);
;             const char* a1 = cA + (size_t)(t + 1) * kstep;
;             const char* a2 = last ? nA : cA + (size_t)(t + 2) * kstep; const char* b2 = last ? nB : cB + (size_t)(t + 2) * kstep;
;             const char* a3 = a2 + kstep; const char* b3 = b2 + kstep;
;             if (last && has_next) S.a_ready(nxt);
;             if constexpr (SP2) {
;             PG8_LDB(B0, 0, 0); PG8_LDB(B1, 0, 1); PG8_SCHED; PG8_LDA(At, 0, 0); PG8_STAGE(PG8_SA(1, 1), a1 + hstep, voffA);
;             PG8_WAIT_V(8); PG8_WAIT_L(0); PG8_BAR; PG8_MMA(0, 0, At, B0); PG8_MMA(0, 1, At, B1); PG8_BAR; PG8_SCHED;
;             PG8_LDA(At, 0, 1); PG8_STAGE(PG8_SB(0, 0), b2, voffB); PG8_STAGE(PG8_SB(0, 1), b2 + hstep, voffB); PG8_STAGE(PG8_SA(0, 0), a2, voffA);
.LBB0_901:
	ds_read_b128 v[154:157], v150
	ds_read_b128 v[158:161], v150 offset:1024
	ds_read_b128 v[162:165], v150 offset:2048
	ds_read_b128 v[166:169], v150 offset:3072
	ds_read_b128 v[170:173], v151
	ds_read_b128 v[174:177], v151 offset:1024
	ds_read_b128 v[178:181], v151 offset:2048
	ds_read_b128 v[182:185], v151 offset:3072
	s_add_u32 s30, s44, 0xfffc0080
	s_addc_u32 s31, s45, -1
	s_cmp_eq_u32 s75, 12
	s_cselect_b32 s53, s25, s31
	s_cselect_b32 s52, s71, s30
	s_cselect_b32 s51, s23, s74
	s_cselect_b32 s50, s72, s73
	v_lshl_add_u64 v[146:147], s[44:45], 0, v[138:139]
	s_add_i32 m0, s41, 0xc000
	ds_read_b128 v[186:189], v152
	ds_read_b128 v[190:193], v152 offset:1024
	ds_read_b128 v[194:197], v152 offset:2048
	ds_read_b128 v[198:201], v152 offset:3072
	ds_read_b128 v[206:209], v152 offset:4096
	ds_read_b128 v[210:213], v152 offset:5120
	ds_read_b128 v[214:217], v152 offset:6144
	ds_read_b128 v[218:221], v152 offset:7168
	global_load_lds_dwordx4 v[146:147], off
	v_lshl_add_u64 v[146:147], s[44:45], 0, v[140:141]
	s_add_i32 m0, s41, 0xe000
	s_nop 0
	global_load_lds_dwordx4 v[146:147], off
	s_waitcnt vmcnt(8)
	s_waitcnt lgkmcnt(0)
	s_barrier
	s_setprio 1
	s_waitcnt lgkmcnt(0)
	v_mfma_f32_16x16x32_bf16 v[126:129], v[154:157], v[186:189], v[126:129]
	v_mfma_f32_16x16x32_bf16 v[122:125], v[162:165], v[186:189], v[122:125]
	v_mfma_f32_16x16x32_bf16 v[114:117], v[154:157], v[194:197], v[114:117]
	v_mfma_f32_16x16x32_bf16 v[106:109], v[162:165], v[194:197], v[106:109]
	v_mfma_f32_16x16x32_bf16 v[98:101], v[154:157], v[206:209], v[98:101]
	v_mfma_f32_16x16x32_bf16 v[90:93], v[162:165], v[206:209], v[90:93]
	v_mfma_f32_16x16x32_bf16 v[82:85], v[154:157], v[214:217], v[82:85]
	v_mfma_f32_16x16x32_bf16 v[74:77], v[162:165], v[214:217], v[74:77]
	v_mfma_f32_16x16x32_bf16 v[126:129], v[158:161], v[190:193], v[126:129]
	v_mfma_f32_16x16x32_bf16 v[122:125], v[166:169], v[190:193], v[122:125]
	v_mfma_f32_16x16x32_bf16 v[114:117], v[158:161], v[198:201], v[114:117]
	v_mfma_f32_16x16x32_bf16 v[106:109], v[166:169], v[198:201], v[106:109]
	v_mfma_f32_16x16x32_bf16 v[98:101], v[158:161], v[210:213], v[98:101]
	v_mfma_f32_16x16x32_bf16 v[90:93], v[166:169], v[210:213], v[90:93]
	v_mfma_f32_16x16x32_bf16 v[82:85], v[158:161], v[218:221], v[82:85]
	v_mfma_f32_16x16x32_bf16 v[74:77], v[166:169], v[218:221], v[74:77]
	s_setprio 0
	s_setprio 1
	v_mfma_f32_16x16x32_bf16 v[118:121], v[170:173], v[186:189], v[118:121]
	v_mfma_f32_16x16x32_bf16 v[110:113], v[178:181], v[186:189], v[110:113]
	v_mfma_f32_16x16x32_bf16 v[102:105], v[170:173], v[194:197], v[102:105]
	v_mfma_f32_16x16x32_bf16 v[94:97], v[178:181], v[194:197], v[94:97]
	v_mfma_f32_16x16x32_bf16 v[86:89], v[170:173], v[206:209], v[86:89]
	v_mfma_f32_16x16x32_bf16 v[78:81], v[178:181], v[206:209], v[78:81]
	v_mfma_f32_16x16x32_bf16 v[70:73], v[170:173], v[214:217], v[70:73]
	v_mfma_f32_16x16x32_bf16 v[66:69], v[178:181], v[214:217], v[66:69]
	v_mfma_f32_16x16x32_bf16 v[118:121], v[174:177], v[190:193], v[118:121]
	v_mfma_f32_16x16x32_bf16 v[110:113], v[182:185], v[190:193], v[110:113]
	v_mfma_f32_16x16x32_bf16 v[102:105], v[174:177], v[198:201], v[102:105]
	v_mfma_f32_16x16x32_bf16 v[94:97], v[182:185], v[198:201], v[94:97]
	s_setprio 2
	s_barrier
	v_mfma_f32_16x16x32_bf16 v[86:89], v[174:177], v[210:213], v[86:89]
	v_mfma_f32_16x16x32_bf16 v[78:81], v[182:185], v[210:213], v[78:81]
	v_mfma_f32_16x16x32_bf16 v[70:73], v[174:177], v[218:221], v[70:73]
	v_mfma_f32_16x16x32_bf16 v[66:69], v[182:185], v[218:221], v[66:69]
	s_setprio 0
	s_add_i32 s30, s64, s56
	v_lshl_add_u64 v[146:147], s[50:51], 0, v[132:133]
	s_mov_b32 m0, s30
	ds_read_b128 v[186:189], v152 offset:16384
	ds_read_b128 v[190:193], v152 offset:17408
	ds_read_b128 v[194:197], v152 offset:18432
	ds_read_b128 v[198:201], v152 offset:19456
	ds_read_b128 v[206:209], v152 offset:20480
	ds_read_b128 v[210:213], v152 offset:21504
	ds_read_b128 v[214:217], v152 offset:22528
	ds_read_b128 v[218:221], v152 offset:23552
	global_load_lds_dwordx4 v[146:147], off
	s_add_i32 m0, s30, 0x2000
	s_add_u32 s30, s50, 0x40000
	v_lshl_add_u64 v[202:203], s[50:51], 0, v[136:137]
	s_addc_u32 s31, s51, 0
	s_add_i32 s76, s65, s56
	global_load_lds_dwordx4 v[202:203], off
	v_lshl_add_u64 v[222:223], s[30:31], 0, v[132:133]
	s_mov_b32 m0, s76
	v_lshl_add_u64 v[224:225], s[52:53], 0, v[134:135]
	global_load_lds_dwordx4 v[222:223], off
	v_lshl_add_u64 v[222:223], s[30:31], 0, v[136:137]
	s_add_i32 m0, s76, 0x2000
	s_nop 0
	global_load_lds_dwordx4 v[222:223], off
	v_lshl_add_u64 v[222:223], s[52:53], 0, v[130:131]
	s_mov_b32 m0, s41
	s_nop 0
	global_load_lds_dwordx4 v[222:223], off
	s_mov_b32 m0, s57
	s_nop 0
	global_load_lds_dwordx4 v[224:225], off
	s_waitcnt vmcnt(8)
	s_waitcnt lgkmcnt(0)
	s_barrier
; #define PG8_STAGE(bufoff, gbase, voff) do { _Pragma("unroll") for (int _i = 0; _i < 2; ++_i) \
;         __builtin_amdgcn_global_load_lds((const unsigned*)((const char*)(gbase) + (voff)[_i]), (PG8_LAS unsigned*)(lds + (bufoff) + ldsw + _i * 8192), 16, 0, 0); } while (0)
; #define PG8_LDA(dst, b, h) do { _Pragma("unroll") for (int m = 0; m < 4; ++m) _Pragma("unroll") for (int k = 0; k < 2; ++k) dst[m][k] = *(const PG8_LAS bf16x8*)(lds + PG8_SA(b, h) + aoff + m * 2048 + k * 1024); } while (0)
; #define PG8_LDB(dst, b, h) do { _Pragma("unroll") for (int n = 0; n < 2; ++n) _Pragma("unroll") for (int k = 0; k < 2; ++k) dst[n][k] = *(const PG8_LAS bf16x8*)(lds + PG8_SB(b, h) + boff + n * 2048 + k * 1024); } while (0)
; #define PG8_MMA(ai, bj, At, Bt) do { __builtin_amdgcn_s_setprio(1); _Pragma("unroll") for (int m = 0; m < 4; ++m) _Pragma("unroll") for (int n = 0; n < 2; ++n) _Pragma("unroll") for (int k = 0; k < 2; ++k) \
;         acc[ai][bj][m][n] = __builtin_amdgcn_mfma_f32_16x16x32_bf16(Bt[n][k], At[m][k], acc[ai][bj][m][n], 0, 0, 0); __builtin_amdgcn_s_setprio(0); } while (0)
; #define PG8_WAIT_V(n) asm volatile("s_waitcnt vmcnt(" #n ")" ::: "memory")
; #define PG8_WAIT_L(n) asm volatile("s_waitcnt lgkmcnt(" #n ")" ::: "memory")
; #define PG8_BAR __builtin_amdgcn_s_barrier()
; #define PG8_SCHED __builtin_amdgcn_sched_barrier(0)
; template <class Epi, class Sched, bool ALIGN_EPI = false, bool SP2 = false>
; __device__ __forceinline__ void gemm_phase(PG8_LAS unsigned char* lds, const Gemm g, const Sched& S, const Epi& E) {
;     ...
;             PG8_WAIT_V(8); PG8_WAIT_L(0); PG8_BAR; PG8_MMA(1, 0, At, B0); PG8_MMA(1, 1, At, B1); PG8_BAR; PG8_SCHED;
;             PG8_LDB(B0, 1, 0); PG8_LDB(B1, 1, 1); PG8_SCHED; PG8_LDA(At, 1, 0); PG8_STAGE(PG8_SA(0, 1), a2 + hstep, voffA);
;             PG8_WAIT_V(8); PG8_WAIT_L(0); PG8_BAR; PG8_MMA(0, 0, At, B0); PG8_MMA(0, 1, At, B1); PG8_BAR; PG8_SCHED;
	s_setprio 1
	s_waitcnt lgkmcnt(0)
	v_mfma_f32_16x16x32_bf16 v[62:65], v[154:157], v[186:189], v[62:65]
	v_mfma_f32_16x16x32_bf16 v[58:61], v[162:165], v[186:189], v[58:61]
	v_mfma_f32_16x16x32_bf16 v[50:53], v[154:157], v[194:197], v[50:53]
	v_mfma_f32_16x16x32_bf16 v[42:45], v[162:165], v[194:197], v[42:45]
	v_mfma_f32_16x16x32_bf16 v[34:37], v[154:157], v[206:209], v[34:37]
	v_mfma_f32_16x16x32_bf16 v[26:29], v[162:165], v[206:209], v[26:29]
	v_mfma_f32_16x16x32_bf16 v[18:21], v[154:157], v[214:217], v[18:21]
	v_mfma_f32_16x16x32_bf16 v[10:13], v[162:165], v[214:217], v[10:13]
	v_mfma_f32_16x16x32_bf16 v[62:65], v[158:161], v[190:193], v[62:65]
	v_mfma_f32_16x16x32_bf16 v[58:61], v[166:169], v[190:193], v[58:61]
	v_mfma_f32_16x16x32_bf16 v[50:53], v[158:161], v[198:201], v[50:53]
	v_mfma_f32_16x16x32_bf16 v[42:45], v[166:169], v[198:201], v[42:45]
	v_mfma_f32_16x16x32_bf16 v[34:37], v[158:161], v[210:213], v[34:37]
	v_mfma_f32_16x16x32_bf16 v[26:29], v[166:169], v[210:213], v[26:29]
	v_mfma_f32_16x16x32_bf16 v[18:21], v[158:161], v[218:221], v[18:21]
	v_mfma_f32_16x16x32_bf16 v[10:13], v[166:169], v[218:221], v[10:13]
	s_setprio 0
	s_setprio 1
	v_mfma_f32_16x16x32_bf16 v[54:57], v[170:173], v[186:189], v[54:57]
	v_mfma_f32_16x16x32_bf16 v[46:49], v[178:181], v[186:189], v[46:49]
	v_mfma_f32_16x16x32_bf16 v[38:41], v[170:173], v[194:197], v[38:41]
	v_mfma_f32_16x16x32_bf16 v[30:33], v[178:181], v[194:197], v[30:33]
	v_mfma_f32_16x16x32_bf16 v[22:25], v[170:173], v[206:209], v[22:25]
	v_mfma_f32_16x16x32_bf16 v[14:17], v[178:181], v[206:209], v[14:17]
	v_mfma_f32_16x16x32_bf16 v[6:9], v[170:173], v[214:217], v[6:9]
	v_mfma_f32_16x16x32_bf16 v[2:5], v[178:181], v[214:217], v[2:5]
	v_mfma_f32_16x16x32_bf16 v[54:57], v[174:177], v[190:193], v[54:57]
	v_mfma_f32_16x16x32_bf16 v[46:49], v[182:185], v[190:193], v[46:49]
	v_mfma_f32_16x16x32_bf16 v[38:41], v[174:177], v[198:201], v[38:41]
	v_mfma_f32_16x16x32_bf16 v[30:33], v[182:185], v[198:201], v[30:33]
	s_setprio 2
	s_barrier
	v_mfma_f32_16x16x32_bf16 v[22:25], v[174:177], v[210:213], v[22:25]
	v_mfma_f32_16x16x32_bf16 v[14:17], v[182:185], v[210:213], v[14:17]
	v_mfma_f32_16x16x32_bf16 v[6:9], v[174:177], v[218:221], v[6:9]
	v_mfma_f32_16x16x32_bf16 v[2:5], v[182:185], v[218:221], v[2:5]
	s_setprio 0
	s_add_i32 s76, 0, 0x18000
	v_add_u32_e32 v153, s76, v148
	s_add_i32 s77, 0, 0x1c000
	ds_read_b128 v[154:157], v153
	ds_read_b128 v[158:161], v153 offset:1024
	ds_read_b128 v[162:165], v153 offset:2048
	ds_read_b128 v[166:169], v153 offset:3072
	v_add_u32_e32 v153, s77, v148
	ds_read_b128 v[170:173], v153
	ds_read_b128 v[174:177], v153 offset:1024
	ds_read_b128 v[178:181], v153 offset:2048
	ds_read_b128 v[182:185], v153 offset:3072
	s_add_u32 s30, s52, 0x40000
	s_addc_u32 s31, s53, 0
	s_mov_b32 m0, s58
	v_lshl_add_u64 v[226:227], s[30:31], 0, v[130:131]
	ds_read_b128 v[186:189], v152 offset:32768
	ds_read_b128 v[190:193], v152 offset:33792
	ds_read_b128 v[194:197], v152 offset:34816
	ds_read_b128 v[198:201], v152 offset:35840
	ds_read_b128 v[206:209], v152 offset:36864
	ds_read_b128 v[210:213], v152 offset:37888
	ds_read_b128 v[214:217], v152 offset:38912
	ds_read_b128 v[218:221], v152 offset:39936
	global_load_lds_dwordx4 v[226:227], off
	v_lshl_add_u64 v[226:227], s[30:31], 0, v[134:135]
	s_mov_b32 m0, s59
	s_nop 0
	global_load_lds_dwordx4 v[226:227], off
	s_waitcnt vmcnt(8)
	s_waitcnt lgkmcnt(0)
	s_barrier
	s_setprio 1
	s_waitcnt lgkmcnt(0)
	v_mfma_f32_16x16x32_bf16 v[126:129], v[154:157], v[186:189], v[126:129]
	v_mfma_f32_16x16x32_bf16 v[122:125], v[162:165], v[186:189], v[122:125]
	v_mfma_f32_16x16x32_bf16 v[114:117], v[154:157], v[194:197], v[114:117]
	v_mfma_f32_16x16x32_bf16 v[106:109], v[162:165], v[194:197], v[106:109]
	v_mfma_f32_16x16x32_bf16 v[98:101], v[154:157], v[206:209], v[98:101]
	v_mfma_f32_16x16x32_bf16 v[90:93], v[162:165], v[206:209], v[90:93]
	v_mfma_f32_16x16x32_bf16 v[82:85], v[154:157], v[214:217], v[82:85]
	v_mfma_f32_16x16x32_bf16 v[74:77], v[162:165], v[214:217], v[74:77]
	v_mfma_f32_16x16x32_bf16 v[126:129], v[158:161], v[190:193], v[126:129]
	v_mfma_f32_16x16x32_bf16 v[122:125], v[166:169], v[190:193], v[122:125]
	v_mfma_f32_16x16x32_bf16 v[114:117], v[158:161], v[198:201], v[114:117]
	v_mfma_f32_16x16x32_bf16 v[106:109], v[166:169], v[198:201], v[106:109]
	v_mfma_f32_16x16x32_bf16 v[98:101], v[158:161], v[210:213], v[98:101]
	v_mfma_f32_16x16x32_bf16 v[90:93], v[166:169], v[210:213], v[90:93]
	v_mfma_f32_16x16x32_bf16 v[82:85], v[158:161], v[218:221], v[82:85]
	v_mfma_f32_16x16x32_bf16 v[74:77], v[166:169], v[218:221], v[74:77]
	s_setprio 0
	s_setprio 1
	v_mfma_f32_16x16x32_bf16 v[118:121], v[170:173], v[186:189], v[118:121]
	v_mfma_f32_16x16x32_bf16 v[110:113], v[178:181], v[186:189], v[110:113]
	v_mfma_f32_16x16x32_bf16 v[102:105], v[170:173], v[194:197], v[102:105]
	v_mfma_f32_16x16x32_bf16 v[94:97], v[178:181], v[194:197], v[94:97]
	v_mfma_f32_16x16x32_bf16 v[86:89], v[170:173], v[206:209], v[86:89]
	v_mfma_f32_16x16x32_bf16 v[78:81], v[178:181], v[206:209], v[78:81]
	v_mfma_f32_16x16x32_bf16 v[70:73], v[170:173], v[214:217], v[70:73]
	v_mfma_f32_16x16x32_bf16 v[66:69], v[178:181], v[214:217], v[66:69]
	v_mfma_f32_16x16x32_bf16 v[118:121], v[174:177], v[190:193], v[118:121]
	v_mfma_f32_16x16x32_bf16 v[110:113], v[182:185], v[190:193], v[110:113]
	v_mfma_f32_16x16x32_bf16 v[102:105], v[174:177], v[198:201], v[102:105]
	v_mfma_f32_16x16x32_bf16 v[94:97], v[182:185], v[198:201], v[94:97]
	s_setprio 2
	s_barrier
; #define PG8_STAGE(bufoff, gbase, voff) do { _Pragma("unroll") for (int _i = 0; _i < 2; ++_i) \
;         __builtin_amdgcn_global_load_lds((const unsigned*)((const char*)(gbase) + (voff)[_i]), (PG8_LAS unsigned*)(lds + (bufoff) + ldsw + _i * 8192), 16, 0, 0); } while (0)
; #define PG8_LDA(dst, b, h) do { _Pragma("unroll") for (int m = 0; m < 4; ++m) _Pragma("unroll") for (int k = 0; k < 2; ++k) dst[m][k] = *(const PG8_LAS bf16x8*)(lds + PG8_SA(b, h) + aoff + m * 2048 + k * 1024); } while (0)
; #define PG8_MMA(ai, bj, At, Bt) do { __builtin_amdgcn_s_setprio(1); _Pragma("unroll") for (int m = 0; m < 4; ++m) _Pragma("unroll") for (int n = 0; n < 2; ++n) _Pragma("unroll") for (int k = 0; k < 2; ++k) \
;         acc[ai][bj][m][n] = __builtin_amdgcn_mfma_f32_16x16x32_bf16(Bt[n][k], At[m][k], acc[ai][bj][m][n], 0, 0, 0); __builtin_amdgcn_s_setprio(0); } while (0)
; #define PG8_WAIT_V(n) asm volatile("s_waitcnt vmcnt(" #n ")" ::: "memory")
; #define PG8_WAIT_L(n) asm volatile("s_waitcnt lgkmcnt(" #n ")" ::: "memory")
; #define PG8_BAR __builtin_amdgcn_s_barrier()
; #define PG8_SCHED __builtin_amdgcn_sched_barrier(0)
; template <class Epi, class Sched, bool ALIGN_EPI = false, bool SP2 = false>
; __device__ __forceinline__ void gemm_phase(PG8_LAS unsigned char* lds, const Gemm g, const Sched& S, const Epi& E) {
;     ...
;         for (int t = 0; t < nt; t += 2) {
;             const bool last = (t == nt - 2);
;             const char* a1 = cA + (size_t)(t + 1) * kstep;
;             const char* a2 = last ? nA : cA + (size_t)(t + 2) * kstep; const char* b2 = last ? nB : cB + (size_t)(t + 2) * kstep;
;             const char* a3 = a2 + kstep; const char* b3 = b2 + kstep;
;     ...
;             PG8_WAIT_V(8); PG8_WAIT_L(0); PG8_BAR; PG8_MMA(0, 0, At, B0); PG8_MMA(0, 1, At, B1); PG8_BAR; PG8_SCHED;
;             PG8_LDA(At, 1, 1); PG8_STAGE(PG8_SB(1, 0), b3, voffB); PG8_STAGE(PG8_SB(1, 1), b3 + hstep, voffB); PG8_STAGE(PG8_SA(1, 0), a3, voffA);
;             PG8_WAIT_V(8); PG8_WAIT_L(0); PG8_BAR; PG8_MMA(1, 0, At, B0); PG8_MMA(1, 1, At, B1); PG8_BAR; PG8_SCHED;
;     ...
;         if constexpr (ALIGN_EPI) { if (wr == 0) PG8_BAR; }
	v_mfma_f32_16x16x32_bf16 v[86:89], v[174:177], v[210:213], v[86:89]
	v_mfma_f32_16x16x32_bf16 v[78:81], v[182:185], v[210:213], v[78:81]
	v_mfma_f32_16x16x32_bf16 v[70:73], v[174:177], v[218:221], v[70:73]
	v_mfma_f32_16x16x32_bf16 v[66:69], v[182:185], v[218:221], v[66:69]
	s_setprio 0
	s_add_i32 s30, s76, s56
	v_lshl_add_u64 v[146:147], v[146:147], 0, s[10:11]
	s_mov_b32 m0, s30
	ds_read_b128 v[186:189], v152 offset:49152
	ds_read_b128 v[190:193], v152 offset:50176
	ds_read_b128 v[194:197], v152 offset:51200
	ds_read_b128 v[198:201], v152 offset:52224
	ds_read_b128 v[206:209], v152 offset:53248
	ds_read_b128 v[210:213], v152 offset:54272
	ds_read_b128 v[214:217], v152 offset:55296
	ds_read_b128 v[218:221], v152 offset:56320
	global_load_lds_dwordx4 v[146:147], off
	s_add_i32 m0, s30, 0x2000
	s_add_u32 s30, s50, 0x40080
	v_lshl_add_u64 v[146:147], v[202:203], 0, s[10:11]
	s_addc_u32 s31, s51, 0
	s_add_i32 s50, s77, s56
	global_load_lds_dwordx4 v[146:147], off
	v_lshl_add_u64 v[146:147], s[30:31], 0, v[132:133]
	s_mov_b32 m0, s50
	s_nop 0
	global_load_lds_dwordx4 v[146:147], off
	v_lshl_add_u64 v[146:147], s[30:31], 0, v[136:137]
	s_add_i32 m0, s50, 0x2000
	s_nop 0
	global_load_lds_dwordx4 v[146:147], off
	v_lshl_add_u64 v[146:147], v[222:223], 0, s[10:11]
	s_mov_b32 m0, s61
	s_nop 0
	global_load_lds_dwordx4 v[146:147], off
	v_lshl_add_u64 v[146:147], v[224:225], 0, s[10:11]
	s_mov_b32 m0, s62
	s_nop 0
	global_load_lds_dwordx4 v[146:147], off
	s_waitcnt vmcnt(8)
	s_waitcnt lgkmcnt(0)
	s_barrier
	s_setprio 1
	s_waitcnt lgkmcnt(0)
	v_mfma_f32_16x16x32_bf16 v[62:65], v[154:157], v[186:189], v[62:65]
	v_mfma_f32_16x16x32_bf16 v[58:61], v[162:165], v[186:189], v[58:61]
	v_mfma_f32_16x16x32_bf16 v[50:53], v[154:157], v[194:197], v[50:53]
	v_mfma_f32_16x16x32_bf16 v[42:45], v[162:165], v[194:197], v[42:45]
	v_mfma_f32_16x16x32_bf16 v[34:37], v[154:157], v[206:209], v[34:37]
	v_mfma_f32_16x16x32_bf16 v[26:29], v[162:165], v[206:209], v[26:29]
	v_mfma_f32_16x16x32_bf16 v[18:21], v[154:157], v[214:217], v[18:21]
	v_mfma_f32_16x16x32_bf16 v[10:13], v[162:165], v[214:217], v[10:13]
	v_mfma_f32_16x16x32_bf16 v[62:65], v[158:161], v[190:193], v[62:65]
	v_mfma_f32_16x16x32_bf16 v[58:61], v[166:169], v[190:193], v[58:61]
	v_mfma_f32_16x16x32_bf16 v[50:53], v[158:161], v[198:201], v[50:53]
	v_mfma_f32_16x16x32_bf16 v[42:45], v[166:169], v[198:201], v[42:45]
	v_mfma_f32_16x16x32_bf16 v[34:37], v[158:161], v[210:213], v[34:37]
	v_mfma_f32_16x16x32_bf16 v[26:29], v[166:169], v[210:213], v[26:29]
	v_mfma_f32_16x16x32_bf16 v[18:21], v[158:161], v[218:221], v[18:21]
	v_mfma_f32_16x16x32_bf16 v[10:13], v[166:169], v[218:221], v[10:13]
	s_setprio 0
	s_setprio 1
	v_mfma_f32_16x16x32_bf16 v[54:57], v[170:173], v[186:189], v[54:57]
	v_mfma_f32_16x16x32_bf16 v[46:49], v[178:181], v[186:189], v[46:49]
	v_mfma_f32_16x16x32_bf16 v[38:41], v[170:173], v[194:197], v[38:41]
	v_mfma_f32_16x16x32_bf16 v[30:33], v[178:181], v[194:197], v[30:33]
	v_mfma_f32_16x16x32_bf16 v[22:25], v[170:173], v[206:209], v[22:25]
	v_mfma_f32_16x16x32_bf16 v[14:17], v[178:181], v[206:209], v[14:17]
	v_mfma_f32_16x16x32_bf16 v[6:9], v[170:173], v[214:217], v[6:9]
	v_mfma_f32_16x16x32_bf16 v[2:5], v[178:181], v[214:217], v[2:5]
	v_mfma_f32_16x16x32_bf16 v[54:57], v[174:177], v[190:193], v[54:57]
	v_mfma_f32_16x16x32_bf16 v[46:49], v[182:185], v[190:193], v[46:49]
	v_mfma_f32_16x16x32_bf16 v[38:41], v[174:177], v[198:201], v[38:41]
	v_mfma_f32_16x16x32_bf16 v[30:33], v[182:185], v[198:201], v[30:33]
	s_setprio 2
	s_barrier
	v_mfma_f32_16x16x32_bf16 v[22:25], v[174:177], v[210:213], v[22:25]
	v_mfma_f32_16x16x32_bf16 v[14:17], v[182:185], v[210:213], v[14:17]
	v_mfma_f32_16x16x32_bf16 v[6:9], v[174:177], v[218:221], v[6:9]
	v_mfma_f32_16x16x32_bf16 v[2:5], v[182:185], v[218:221], v[2:5]
	s_setprio 0
	s_add_i32 s75, s75, 2
	s_add_u32 s44, s44, 0x100
	s_addc_u32 s45, s45, 0
	s_add_u32 s73, s73, 0x100
	s_addc_u32 s74, s74, 0
	s_cmp_gt_u32 s75, 13
	s_cbranch_scc0 .LBB0_901
	s_and_b64 vcc, exec, s[12:13]
	s_cbranch_vccz .LBB0_904
	s_barrier

; #define PG8_STAGE(bufoff, gbase, voff) do { _Pragma("unroll") for (int _i = 0; _i < 2; ++_i) \
;         __builtin_amdgcn_global_load_lds((const unsigned*)((const char*)(gbase) + (voff)[_i]), (PG8_LAS unsigned*)(lds + (bufoff) + ldsw + _i * 8192), 16, 0, 0); } while (0)
; #define PG8_LDA(dst, b, h) do { _Pragma("unroll") for (int m = 0; m < 4; ++m) _Pragma("unroll") for (int k = 0; k < 2; ++k) dst[m][k] = *(const PG8_LAS bf16x8*)(lds + PG8_SA(b, h) + aoff + m * 2048 + k * 1024); } while (0)
; #define PG8_LDB(dst, b, h) do { _Pragma("unroll") for (int n = 0; n < 2; ++n) _Pragma("unroll") for (int k = 0; k < 2; ++k) dst[n][k] = *(const PG8_LAS bf16x8*)(lds + PG8_SB(b, h) + boff + n * 2048 + k * 1024); } while (0)
; #define PG8_MMA(ai, bj, At, Bt) do { __builtin_amdgcn_s_setprio(1); _Pragma("unroll") for (int m = 0; m < 4; ++m) _Pragma("unroll") for (int n = 0; n < 2; ++n) _Pragma("unroll") for (int k = 0; k < 2; ++k) \
;         acc[ai][bj][m][n] = __builtin_amdgcn_mfma_f32_16x16x32_bf16(Bt[n][k], At[m][k], acc[ai][bj][m][n], 0, 0, 0); __builtin_amdgcn_s_setprio(0); } while (0)
; #define PG8_WAIT_V(n) asm volatile("s_waitcnt vmcnt(" #n ")" ::: "memory")
; #define PG8_WAIT_L(n) asm volatile("s_waitcnt lgkmcnt(" #n ")" ::: "memory")
; #define PG8_BAR __builtin_amdgcn_s_barrier()
; #define PG8_SCHED __builtin_amdgcn_sched_barrier(0)
; template <class Epi, class Sched, bool ALIGN_EPI = false, bool SP2 = false>
; __device__ __forceinline__ void gemm_phase(PG8_LAS unsigned char* lds, const Gemm g, const Sched& S, const Epi& E) {
;     ...
;             const bool last = (t == nt - 2);
;             const char* a1 = cA + (size_t)(t + 1) * kstep;
;             const char* a2 = last ? nA : cA + (size_t)(t + 2) * kstep; const char* b2 = last ? nB : cB + (size_t)(t + 2) * kstep;
;             const char* a3 = a2 + kstep; const char* b3 = b2 + kstep;
;             if (last && has_next) S.a_ready(nxt);
;             if constexpr (SP2) {
;             PG8_LDB(B0, 0, 0); PG8_LDB(B1, 0, 1); PG8_SCHED; PG8_LDA(At, 0, 0); PG8_STAGE(PG8_SA(1, 1), a1 + hstep, voffA);
;             PG8_WAIT_V(8); PG8_WAIT_L(0); PG8_BAR; PG8_MMA(0, 0, At, B0); PG8_MMA(0, 1, At, B1); PG8_BAR; PG8_SCHED;
;             PG8_LDA(At, 0, 1); PG8_STAGE(PG8_SB(0, 0), b2, voffB); PG8_STAGE(PG8_SB(0, 1), b2 + hstep, voffB); PG8_STAGE(PG8_SA(0, 0), a2, voffA);
.LBB0_984:
	ds_read_b128 v[122:125], v184
	ds_read_b128 v[126:129], v184 offset:1024
	ds_read_b128 v[130:133], v184 offset:2048
	ds_read_b128 v[134:137], v184 offset:3072
	ds_read_b128 v[142:145], v185
	ds_read_b128 v[146:149], v185 offset:1024
	ds_read_b128 v[150:153], v185 offset:2048
	ds_read_b128 v[158:161], v185 offset:3072
	s_add_u32 s30, s26, 0xfff00080
	s_addc_u32 s31, s27, -1
	s_cmp_eq_u32 s64, 60
	s_cselect_b32 s41, s19, s31
	s_cselect_b32 s40, s60, s30
	s_cselect_b32 s39, s17, s63
	s_cselect_b32 s38, s61, s62
	v_lshl_add_u64 v[218:219], s[26:27], 0, v[170:171]
	s_add_i32 m0, s25, 0xc000
	ds_read_b128 v[178:181], v186
	ds_read_b128 v[188:191], v186 offset:1024
	ds_read_b128 v[192:195], v186 offset:2048
	ds_read_b128 v[196:199], v186 offset:3072
	ds_read_b128 v[200:203], v186 offset:4096
	ds_read_b128 v[206:209], v186 offset:5120
	ds_read_b128 v[210:213], v186 offset:6144
	ds_read_b128 v[214:217], v186 offset:7168
	global_load_lds_dwordx4 v[218:219], off
	v_lshl_add_u64 v[218:219], s[26:27], 0, v[172:173]
	s_add_i32 m0, s25, 0xe000
	s_nop 0
	global_load_lds_dwordx4 v[218:219], off
	s_waitcnt vmcnt(8)
	s_waitcnt lgkmcnt(0)
	s_barrier
	s_setprio 1
	s_waitcnt lgkmcnt(0)
	v_mfma_f32_16x16x32_bf16 v[154:157], v[122:125], v[178:181], v[154:157]
	v_mfma_f32_16x16x32_bf16 v[138:141], v[130:133], v[178:181], v[138:141]
	v_mfma_f32_16x16x32_bf16 v[114:117], v[122:125], v[192:195], v[114:117]
	v_mfma_f32_16x16x32_bf16 v[106:109], v[130:133], v[192:195], v[106:109]
	v_mfma_f32_16x16x32_bf16 v[94:97], v[122:125], v[200:203], v[94:97]
	v_mfma_f32_16x16x32_bf16 v[90:93], v[130:133], v[200:203], v[90:93]
	v_mfma_f32_16x16x32_bf16 v[82:85], v[122:125], v[210:213], v[82:85]
	v_mfma_f32_16x16x32_bf16 v[74:77], v[130:133], v[210:213], v[74:77]
	v_mfma_f32_16x16x32_bf16 v[154:157], v[126:129], v[188:191], v[154:157]
	v_mfma_f32_16x16x32_bf16 v[138:141], v[134:137], v[188:191], v[138:141]
	v_mfma_f32_16x16x32_bf16 v[114:117], v[126:129], v[196:199], v[114:117]
	v_mfma_f32_16x16x32_bf16 v[106:109], v[134:137], v[196:199], v[106:109]
	v_mfma_f32_16x16x32_bf16 v[94:97], v[126:129], v[206:209], v[94:97]
	v_mfma_f32_16x16x32_bf16 v[90:93], v[134:137], v[206:209], v[90:93]
	v_mfma_f32_16x16x32_bf16 v[82:85], v[126:129], v[214:217], v[82:85]
	v_mfma_f32_16x16x32_bf16 v[74:77], v[134:137], v[214:217], v[74:77]
	s_setprio 0
	s_setprio 1
	v_mfma_f32_16x16x32_bf16 v[118:121], v[142:145], v[178:181], v[118:121]
	v_mfma_f32_16x16x32_bf16 v[110:113], v[150:153], v[178:181], v[110:113]
	v_mfma_f32_16x16x32_bf16 v[102:105], v[142:145], v[192:195], v[102:105]
	v_mfma_f32_16x16x32_bf16 v[98:101], v[150:153], v[192:195], v[98:101]
	v_mfma_f32_16x16x32_bf16 v[86:89], v[142:145], v[200:203], v[86:89]
	v_mfma_f32_16x16x32_bf16 v[78:81], v[150:153], v[200:203], v[78:81]
	v_mfma_f32_16x16x32_bf16 v[70:73], v[142:145], v[210:213], v[70:73]
	v_mfma_f32_16x16x32_bf16 v[66:69], v[150:153], v[210:213], v[66:69]
	v_mfma_f32_16x16x32_bf16 v[118:121], v[146:149], v[188:191], v[118:121]
	v_mfma_f32_16x16x32_bf16 v[110:113], v[158:161], v[188:191], v[110:113]
	v_mfma_f32_16x16x32_bf16 v[102:105], v[146:149], v[196:199], v[102:105]
	v_mfma_f32_16x16x32_bf16 v[98:101], v[158:161], v[196:199], v[98:101]
	s_setprio 2
	s_barrier
	v_mfma_f32_16x16x32_bf16 v[86:89], v[146:149], v[206:209], v[86:89]
	v_mfma_f32_16x16x32_bf16 v[78:81], v[158:161], v[206:209], v[78:81]
	v_mfma_f32_16x16x32_bf16 v[70:73], v[146:149], v[214:217], v[70:73]
	v_mfma_f32_16x16x32_bf16 v[66:69], v[158:161], v[214:217], v[66:69]
	s_setprio 0
	s_add_i32 s30, s57, s33
	v_lshl_add_u64 v[218:219], s[38:39], 0, v[164:165]
	s_mov_b32 m0, s30
	ds_read_b128 v[178:181], v186 offset:16384
	ds_read_b128 v[188:191], v186 offset:17408
	ds_read_b128 v[192:195], v186 offset:18432
	ds_read_b128 v[196:199], v186 offset:19456
	ds_read_b128 v[200:203], v186 offset:20480
	ds_read_b128 v[206:209], v186 offset:21504
	ds_read_b128 v[210:213], v186 offset:22528
	ds_read_b128 v[214:217], v186 offset:23552
	global_load_lds_dwordx4 v[218:219], off
	s_add_i32 m0, s30, 0x2000
	s_add_u32 s30, s38, 0x100000
	v_lshl_add_u64 v[220:221], s[38:39], 0, v[168:169]
	s_addc_u32 s31, s39, 0
	s_add_i32 s65, s58, s33
	global_load_lds_dwordx4 v[220:221], off
	v_lshl_add_u64 v[222:223], s[30:31], 0, v[164:165]
	s_mov_b32 m0, s65
	v_lshl_add_u64 v[224:225], s[40:41], 0, v[166:167]
	global_load_lds_dwordx4 v[222:223], off
	v_lshl_add_u64 v[222:223], s[30:31], 0, v[168:169]
	s_add_i32 m0, s65, 0x2000
	s_nop 0
	global_load_lds_dwordx4 v[222:223], off
	v_lshl_add_u64 v[222:223], s[40:41], 0, v[162:163]
	s_mov_b32 m0, s25
	s_nop 0
	global_load_lds_dwordx4 v[222:223], off
	s_mov_b32 m0, s44
	s_nop 0
	global_load_lds_dwordx4 v[224:225], off
	s_waitcnt vmcnt(8)
	s_waitcnt lgkmcnt(0)
	s_barrier
; #define PG8_STAGE(bufoff, gbase, voff) do { _Pragma("unroll") for (int _i = 0; _i < 2; ++_i) \
;         __builtin_amdgcn_global_load_lds((const unsigned*)((const char*)(gbase) + (voff)[_i]), (PG8_LAS unsigned*)(lds + (bufoff) + ldsw + _i * 8192), 16, 0, 0); } while (0)
; #define PG8_LDA(dst, b, h) do { _Pragma("unroll") for (int m = 0; m < 4; ++m) _Pragma("unroll") for (int k = 0; k < 2; ++k) dst[m][k] = *(const PG8_LAS bf16x8*)(lds + PG8_SA(b, h) + aoff + m * 2048 + k * 1024); } while (0)
; #define PG8_LDB(dst, b, h) do { _Pragma("unroll") for (int n = 0; n < 2; ++n) _Pragma("unroll") for (int k = 0; k < 2; ++k) dst[n][k] = *(const PG8_LAS bf16x8*)(lds + PG8_SB(b, h) + boff + n * 2048 + k * 1024); } while (0)
; #define PG8_MMA(ai, bj, At, Bt) do { __builtin_amdgcn_s_setprio(1); _Pragma("unroll") for (int m = 0; m < 4; ++m) _Pragma("unroll") for (int n = 0; n < 2; ++n) _Pragma("unroll") for (int k = 0; k < 2; ++k) \
;         acc[ai][bj][m][n] = __builtin_amdgcn_mfma_f32_16x16x32_bf16(Bt[n][k], At[m][k], acc[ai][bj][m][n], 0, 0, 0); __builtin_amdgcn_s_setprio(0); } while (0)
; #define PG8_WAIT_V(n) asm volatile("s_waitcnt vmcnt(" #n ")" ::: "memory")
; #define PG8_WAIT_L(n) asm volatile("s_waitcnt lgkmcnt(" #n ")" ::: "memory")
; #define PG8_BAR __builtin_amdgcn_s_barrier()
; #define PG8_SCHED __builtin_amdgcn_sched_barrier(0)
; template <class Epi, class Sched, bool ALIGN_EPI = false, bool SP2 = false>
; __device__ __forceinline__ void gemm_phase(PG8_LAS unsigned char* lds, const Gemm g, const Sched& S, const Epi& E) {
;     ...
;             PG8_WAIT_V(8); PG8_WAIT_L(0); PG8_BAR; PG8_MMA(1, 0, At, B0); PG8_MMA(1, 1, At, B1); PG8_BAR; PG8_SCHED;
;             PG8_LDB(B0, 1, 0); PG8_LDB(B1, 1, 1); PG8_SCHED; PG8_LDA(At, 1, 0); PG8_STAGE(PG8_SA(0, 1), a2 + hstep, voffA);
;             PG8_WAIT_V(8); PG8_WAIT_L(0); PG8_BAR; PG8_MMA(0, 0, At, B0); PG8_MMA(0, 1, At, B1); PG8_BAR; PG8_SCHED;
	s_setprio 1
	s_waitcnt lgkmcnt(0)
	v_mfma_f32_16x16x32_bf16 v[62:65], v[122:125], v[178:181], v[62:65]
	v_mfma_f32_16x16x32_bf16 v[58:61], v[130:133], v[178:181], v[58:61]
	v_mfma_f32_16x16x32_bf16 v[50:53], v[122:125], v[192:195], v[50:53]
	v_mfma_f32_16x16x32_bf16 v[42:45], v[130:133], v[192:195], v[42:45]
	v_mfma_f32_16x16x32_bf16 v[30:33], v[122:125], v[200:203], v[30:33]
	v_mfma_f32_16x16x32_bf16 v[26:29], v[130:133], v[200:203], v[26:29]
	v_mfma_f32_16x16x32_bf16 v[18:21], v[122:125], v[210:213], v[18:21]
	v_mfma_f32_16x16x32_bf16 v[10:13], v[130:133], v[210:213], v[10:13]
	v_mfma_f32_16x16x32_bf16 v[62:65], v[126:129], v[188:191], v[62:65]
	v_mfma_f32_16x16x32_bf16 v[58:61], v[134:137], v[188:191], v[58:61]
	v_mfma_f32_16x16x32_bf16 v[50:53], v[126:129], v[196:199], v[50:53]
	v_mfma_f32_16x16x32_bf16 v[42:45], v[134:137], v[196:199], v[42:45]
	v_mfma_f32_16x16x32_bf16 v[30:33], v[126:129], v[206:209], v[30:33]
	v_mfma_f32_16x16x32_bf16 v[26:29], v[134:137], v[206:209], v[26:29]
	v_mfma_f32_16x16x32_bf16 v[18:21], v[126:129], v[214:217], v[18:21]
	v_mfma_f32_16x16x32_bf16 v[10:13], v[134:137], v[214:217], v[10:13]
	s_setprio 0
	s_setprio 1
	v_mfma_f32_16x16x32_bf16 v[54:57], v[142:145], v[178:181], v[54:57]
	v_mfma_f32_16x16x32_bf16 v[46:49], v[150:153], v[178:181], v[46:49]
	v_mfma_f32_16x16x32_bf16 v[38:41], v[142:145], v[192:195], v[38:41]
	v_mfma_f32_16x16x32_bf16 v[34:37], v[150:153], v[192:195], v[34:37]
	v_mfma_f32_16x16x32_bf16 v[22:25], v[142:145], v[200:203], v[22:25]
	v_mfma_f32_16x16x32_bf16 v[14:17], v[150:153], v[200:203], v[14:17]
	v_mfma_f32_16x16x32_bf16 v[6:9], v[142:145], v[210:213], v[6:9]
	v_mfma_f32_16x16x32_bf16 v[2:5], v[150:153], v[210:213], v[2:5]
	v_mfma_f32_16x16x32_bf16 v[54:57], v[146:149], v[188:191], v[54:57]
	v_mfma_f32_16x16x32_bf16 v[46:49], v[158:161], v[188:191], v[46:49]
	v_mfma_f32_16x16x32_bf16 v[38:41], v[146:149], v[196:199], v[38:41]
	v_mfma_f32_16x16x32_bf16 v[34:37], v[158:161], v[196:199], v[34:37]
	s_setprio 2
	s_barrier
	v_mfma_f32_16x16x32_bf16 v[22:25], v[146:149], v[206:209], v[22:25]
	v_mfma_f32_16x16x32_bf16 v[14:17], v[158:161], v[206:209], v[14:17]
	v_mfma_f32_16x16x32_bf16 v[6:9], v[146:149], v[214:217], v[6:9]
	v_mfma_f32_16x16x32_bf16 v[2:5], v[158:161], v[214:217], v[2:5]
	s_setprio 0
	s_add_i32 s65, 0, 0x18000
	s_add_i32 s66, 0, 0x1c000
	v_add_u32_e32 v134, s65, v182
	v_add_u32_e32 v158, s66, v182
	ds_read_b128 v[122:125], v134
	ds_read_b128 v[126:129], v134 offset:1024
	ds_read_b128 v[130:133], v134 offset:2048
	ds_read_b128 v[134:137], v134 offset:3072
	ds_read_b128 v[142:145], v158
	ds_read_b128 v[146:149], v158 offset:1024
	ds_read_b128 v[150:153], v158 offset:2048
	ds_read_b128 v[158:161], v158 offset:3072
	s_add_u32 s30, s40, 0x100000
	s_addc_u32 s31, s41, 0
	s_mov_b32 m0, s45
	v_lshl_add_u64 v[226:227], s[30:31], 0, v[162:163]
	ds_read_b128 v[178:181], v186 offset:32768
	ds_read_b128 v[188:191], v186 offset:33792
	ds_read_b128 v[192:195], v186 offset:34816
	ds_read_b128 v[196:199], v186 offset:35840
	ds_read_b128 v[200:203], v186 offset:36864
	ds_read_b128 v[206:209], v186 offset:37888
	ds_read_b128 v[210:213], v186 offset:38912
	ds_read_b128 v[214:217], v186 offset:39936
	global_load_lds_dwordx4 v[226:227], off
	v_lshl_add_u64 v[226:227], s[30:31], 0, v[166:167]
	s_mov_b32 m0, s50
	s_nop 0
	global_load_lds_dwordx4 v[226:227], off
	s_waitcnt vmcnt(8)
	s_waitcnt lgkmcnt(0)
	s_barrier
	s_setprio 1
	s_waitcnt lgkmcnt(0)
	v_mfma_f32_16x16x32_bf16 v[154:157], v[122:125], v[178:181], v[154:157]
	v_mfma_f32_16x16x32_bf16 v[138:141], v[130:133], v[178:181], v[138:141]
	v_mfma_f32_16x16x32_bf16 v[114:117], v[122:125], v[192:195], v[114:117]
	v_mfma_f32_16x16x32_bf16 v[106:109], v[130:133], v[192:195], v[106:109]
	v_mfma_f32_16x16x32_bf16 v[94:97], v[122:125], v[200:203], v[94:97]
	v_mfma_f32_16x16x32_bf16 v[90:93], v[130:133], v[200:203], v[90:93]
	v_mfma_f32_16x16x32_bf16 v[82:85], v[122:125], v[210:213], v[82:85]
	v_mfma_f32_16x16x32_bf16 v[74:77], v[130:133], v[210:213], v[74:77]
	v_mfma_f32_16x16x32_bf16 v[154:157], v[126:129], v[188:191], v[154:157]
	v_mfma_f32_16x16x32_bf16 v[138:141], v[134:137], v[188:191], v[138:141]
	v_mfma_f32_16x16x32_bf16 v[114:117], v[126:129], v[196:199], v[114:117]
	v_mfma_f32_16x16x32_bf16 v[106:109], v[134:137], v[196:199], v[106:109]
	v_mfma_f32_16x16x32_bf16 v[94:97], v[126:129], v[206:209], v[94:97]
	v_mfma_f32_16x16x32_bf16 v[90:93], v[134:137], v[206:209], v[90:93]
	v_mfma_f32_16x16x32_bf16 v[82:85], v[126:129], v[214:217], v[82:85]
	v_mfma_f32_16x16x32_bf16 v[74:77], v[134:137], v[214:217], v[74:77]
	s_setprio 0
	s_setprio 1
	v_mfma_f32_16x16x32_bf16 v[118:121], v[142:145], v[178:181], v[118:121]
	v_mfma_f32_16x16x32_bf16 v[110:113], v[150:153], v[178:181], v[110:113]
	v_mfma_f32_16x16x32_bf16 v[102:105], v[142:145], v[192:195], v[102:105]
	v_mfma_f32_16x16x32_bf16 v[98:101], v[150:153], v[192:195], v[98:101]
	v_mfma_f32_16x16x32_bf16 v[86:89], v[142:145], v[200:203], v[86:89]
	v_mfma_f32_16x16x32_bf16 v[78:81], v[150:153], v[200:203], v[78:81]
	v_mfma_f32_16x16x32_bf16 v[70:73], v[142:145], v[210:213], v[70:73]
	v_mfma_f32_16x16x32_bf16 v[66:69], v[150:153], v[210:213], v[66:69]
	v_mfma_f32_16x16x32_bf16 v[118:121], v[146:149], v[188:191], v[118:121]
	v_mfma_f32_16x16x32_bf16 v[110:113], v[158:161], v[188:191], v[110:113]
	v_mfma_f32_16x16x32_bf16 v[102:105], v[146:149], v[196:199], v[102:105]
	v_mfma_f32_16x16x32_bf16 v[98:101], v[158:161], v[196:199], v[98:101]
	s_setprio 2
	s_barrier
; #define PG8_STAGE(bufoff, gbase, voff) do { _Pragma("unroll") for (int _i = 0; _i < 2; ++_i) \
;         __builtin_amdgcn_global_load_lds((const unsigned*)((const char*)(gbase) + (voff)[_i]), (PG8_LAS unsigned*)(lds + (bufoff) + ldsw + _i * 8192), 16, 0, 0); } while (0)
; #define PG8_LDA(dst, b, h) do { _Pragma("unroll") for (int m = 0; m < 4; ++m) _Pragma("unroll") for (int k = 0; k < 2; ++k) dst[m][k] = *(const PG8_LAS bf16x8*)(lds + PG8_SA(b, h) + aoff + m * 2048 + k * 1024); } while (0)
; #define PG8_MMA(ai, bj, At, Bt) do { __builtin_amdgcn_s_setprio(1); _Pragma("unroll") for (int m = 0; m < 4; ++m) _Pragma("unroll") for (int n = 0; n < 2; ++n) _Pragma("unroll") for (int k = 0; k < 2; ++k) \
;         acc[ai][bj][m][n] = __builtin_amdgcn_mfma_f32_16x16x32_bf16(Bt[n][k], At[m][k], acc[ai][bj][m][n], 0, 0, 0); __builtin_amdgcn_s_setprio(0); } while (0)
; #define PG8_WAIT_V(n) asm volatile("s_waitcnt vmcnt(" #n ")" ::: "memory")
; #define PG8_WAIT_L(n) asm volatile("s_waitcnt lgkmcnt(" #n ")" ::: "memory")
; #define PG8_BAR __builtin_amdgcn_s_barrier()
; #define PG8_SCHED __builtin_amdgcn_sched_barrier(0)
; template <class Epi, class Sched, bool ALIGN_EPI = false, bool SP2 = false>
; __device__ __forceinline__ void gemm_phase(PG8_LAS unsigned char* lds, const Gemm g, const Sched& S, const Epi& E) {
;     ...
;         for (int t = 0; t < nt; t += 2) {
;             const bool last = (t == nt - 2);
;             const char* a1 = cA + (size_t)(t + 1) * kstep;
;             const char* a2 = last ? nA : cA + (size_t)(t + 2) * kstep; const char* b2 = last ? nB : cB + (size_t)(t + 2) * kstep;
;             const char* a3 = a2 + kstep; const char* b3 = b2 + kstep;
;     ...
;             PG8_WAIT_V(8); PG8_WAIT_L(0); PG8_BAR; PG8_MMA(0, 0, At, B0); PG8_MMA(0, 1, At, B1); PG8_BAR; PG8_SCHED;
;             PG8_LDA(At, 1, 1); PG8_STAGE(PG8_SB(1, 0), b3, voffB); PG8_STAGE(PG8_SB(1, 1), b3 + hstep, voffB); PG8_STAGE(PG8_SA(1, 0), a3, voffA);
;             PG8_WAIT_V(8); PG8_WAIT_L(0); PG8_BAR; PG8_MMA(1, 0, At, B0); PG8_MMA(1, 1, At, B1); PG8_BAR; PG8_SCHED;
;     ...
;         if constexpr (ALIGN_EPI) { if (wr == 0) PG8_BAR; }
	v_mfma_f32_16x16x32_bf16 v[86:89], v[146:149], v[206:209], v[86:89]
	v_mfma_f32_16x16x32_bf16 v[78:81], v[158:161], v[206:209], v[78:81]
	v_mfma_f32_16x16x32_bf16 v[70:73], v[146:149], v[214:217], v[70:73]
	v_mfma_f32_16x16x32_bf16 v[66:69], v[158:161], v[214:217], v[66:69]
	s_setprio 0
	s_add_i32 s30, s65, s33
	v_lshl_add_u64 v[218:219], v[218:219], 0, s[10:11]
	s_mov_b32 m0, s30
	ds_read_b128 v[178:181], v186 offset:49152
	ds_read_b128 v[188:191], v186 offset:50176
	ds_read_b128 v[192:195], v186 offset:51200
	ds_read_b128 v[196:199], v186 offset:52224
	ds_read_b128 v[200:203], v186 offset:53248
	ds_read_b128 v[206:209], v186 offset:54272
	ds_read_b128 v[210:213], v186 offset:55296
	ds_read_b128 v[214:217], v186 offset:56320
	global_load_lds_dwordx4 v[218:219], off
	s_add_i32 m0, s30, 0x2000
	s_add_u32 s30, s38, 0x100080
	v_lshl_add_u64 v[218:219], v[220:221], 0, s[10:11]
	s_addc_u32 s31, s39, 0
	s_add_i32 s38, s66, s33
	global_load_lds_dwordx4 v[218:219], off
	v_lshl_add_u64 v[218:219], s[30:31], 0, v[164:165]
	s_mov_b32 m0, s38
	s_nop 0
	global_load_lds_dwordx4 v[218:219], off
	v_lshl_add_u64 v[218:219], s[30:31], 0, v[168:169]
	s_add_i32 m0, s38, 0x2000
	s_nop 0
	global_load_lds_dwordx4 v[218:219], off
	v_lshl_add_u64 v[218:219], v[222:223], 0, s[10:11]
	s_mov_b32 m0, s52
	s_nop 0
	global_load_lds_dwordx4 v[218:219], off
	v_lshl_add_u64 v[218:219], v[224:225], 0, s[10:11]
	s_mov_b32 m0, s53
	s_nop 0
	global_load_lds_dwordx4 v[218:219], off
	s_waitcnt vmcnt(8)
	s_waitcnt lgkmcnt(0)
	s_barrier
	s_setprio 1
	s_waitcnt lgkmcnt(0)
	v_mfma_f32_16x16x32_bf16 v[62:65], v[122:125], v[178:181], v[62:65]
	v_mfma_f32_16x16x32_bf16 v[58:61], v[130:133], v[178:181], v[58:61]
	v_mfma_f32_16x16x32_bf16 v[50:53], v[122:125], v[192:195], v[50:53]
	v_mfma_f32_16x16x32_bf16 v[42:45], v[130:133], v[192:195], v[42:45]
	v_mfma_f32_16x16x32_bf16 v[30:33], v[122:125], v[200:203], v[30:33]
	v_mfma_f32_16x16x32_bf16 v[26:29], v[130:133], v[200:203], v[26:29]
	v_mfma_f32_16x16x32_bf16 v[18:21], v[122:125], v[210:213], v[18:21]
	v_mfma_f32_16x16x32_bf16 v[10:13], v[130:133], v[210:213], v[10:13]
	v_mfma_f32_16x16x32_bf16 v[62:65], v[126:129], v[188:191], v[62:65]
	v_mfma_f32_16x16x32_bf16 v[58:61], v[134:137], v[188:191], v[58:61]
	v_mfma_f32_16x16x32_bf16 v[50:53], v[126:129], v[196:199], v[50:53]
	v_mfma_f32_16x16x32_bf16 v[42:45], v[134:137], v[196:199], v[42:45]
	v_mfma_f32_16x16x32_bf16 v[30:33], v[126:129], v[206:209], v[30:33]
	v_mfma_f32_16x16x32_bf16 v[26:29], v[134:137], v[206:209], v[26:29]
	v_mfma_f32_16x16x32_bf16 v[18:21], v[126:129], v[214:217], v[18:21]
	v_mfma_f32_16x16x32_bf16 v[10:13], v[134:137], v[214:217], v[10:13]
	s_setprio 0
	s_setprio 1
	v_mfma_f32_16x16x32_bf16 v[54:57], v[142:145], v[178:181], v[54:57]
	v_mfma_f32_16x16x32_bf16 v[46:49], v[150:153], v[178:181], v[46:49]
	v_mfma_f32_16x16x32_bf16 v[38:41], v[142:145], v[192:195], v[38:41]
	v_mfma_f32_16x16x32_bf16 v[34:37], v[150:153], v[192:195], v[34:37]
	v_mfma_f32_16x16x32_bf16 v[22:25], v[142:145], v[200:203], v[22:25]
	v_mfma_f32_16x16x32_bf16 v[14:17], v[150:153], v[200:203], v[14:17]
	v_mfma_f32_16x16x32_bf16 v[6:9], v[142:145], v[210:213], v[6:9]
	v_mfma_f32_16x16x32_bf16 v[2:5], v[150:153], v[210:213], v[2:5]
	v_mfma_f32_16x16x32_bf16 v[54:57], v[146:149], v[188:191], v[54:57]
	v_mfma_f32_16x16x32_bf16 v[46:49], v[158:161], v[188:191], v[46:49]
	v_mfma_f32_16x16x32_bf16 v[38:41], v[146:149], v[196:199], v[38:41]
	v_mfma_f32_16x16x32_bf16 v[34:37], v[158:161], v[196:199], v[34:37]
	s_setprio 2
	s_barrier
	v_mfma_f32_16x16x32_bf16 v[22:25], v[146:149], v[206:209], v[22:25]
	v_mfma_f32_16x16x32_bf16 v[14:17], v[158:161], v[206:209], v[14:17]
	v_mfma_f32_16x16x32_bf16 v[6:9], v[146:149], v[214:217], v[6:9]
	v_mfma_f32_16x16x32_bf16 v[2:5], v[158:161], v[214:217], v[2:5]
	s_setprio 0
	s_add_i32 s64, s64, 2
	s_add_u32 s26, s26, 0x100
	s_addc_u32 s27, s27, 0
	s_add_u32 s62, s62, 0x100
	s_addc_u32 s63, s63, 0
	s_cmp_gt_u32 s64, 61
	s_cbranch_scc0 .LBB0_984
	s_and_b64 vcc, exec, s[12:13]
	s_cbranch_vccz .LBB0_987
	s_barrier

; #define PG8_STAGE(bufoff, gbase, voff) do { _Pragma("unroll") for (int _i = 0; _i < 2; ++_i) \
;         __builtin_amdgcn_global_load_lds((const unsigned*)((const char*)(gbase) + (voff)[_i]), (PG8_LAS unsigned*)(lds + (bufoff) + ldsw + _i * 8192), 16, 0, 0); } while (0)
; #define PG8_LDA(dst, b, h) do { _Pragma("unroll") for (int m = 0; m < 4; ++m) _Pragma("unroll") for (int k = 0; k < 2; ++k) dst[m][k] = *(const PG8_LAS bf16x8*)(lds + PG8_SA(b, h) + aoff + m * 2048 + k * 1024); } while (0)
; #define PG8_LDB(dst, b, h) do { _Pragma("unroll") for (int n = 0; n < 2; ++n) _Pragma("unroll") for (int k = 0; k < 2; ++k) dst[n][k] = *(const PG8_LAS bf16x8*)(lds + PG8_SB(b, h) + boff + n * 2048 + k * 1024); } while (0)
; #define PG8_MMA(ai, bj, At, Bt) do { __builtin_amdgcn_s_setprio(1); _Pragma("unroll") for (int m = 0; m < 4; ++m) _Pragma("unroll") for (int n = 0; n < 2; ++n) _Pragma("unroll") for (int k = 0; k < 2; ++k) \
;         acc[ai][bj][m][n] = __builtin_amdgcn_mfma_f32_16x16x32_bf16(Bt[n][k], At[m][k], acc[ai][bj][m][n], 0, 0, 0); __builtin_amdgcn_s_setprio(0); } while (0)
; #define PG8_WAIT_V(n) asm volatile("s_waitcnt vmcnt(" #n ")" ::: "memory")
; #define PG8_WAIT_L(n) asm volatile("s_waitcnt lgkmcnt(" #n ")" ::: "memory")
; #define PG8_BAR __builtin_amdgcn_s_barrier()
; #define PG8_SCHED __builtin_amdgcn_sched_barrier(0)
; template <class Epi, class Sched, bool ALIGN_EPI = false, bool SP2 = false>
; __device__ __forceinline__ void gemm_phase(PG8_LAS unsigned char* lds, const Gemm g, const Sched& S, const Epi& E) {
;     ...
;             const bool last = (t == nt - 2);
;             const char* a1 = cA + (size_t)(t + 1) * kstep;
;             const char* a2 = last ? nA : cA + (size_t)(t + 2) * kstep; const char* b2 = last ? nB : cB + (size_t)(t + 2) * kstep;
;             const char* a3 = a2 + kstep; const char* b3 = b2 + kstep;
;             if (last && has_next) S.a_ready(nxt);
;             if constexpr (SP2) {
;             PG8_LDB(B0, 0, 0); PG8_LDB(B1, 0, 1); PG8_SCHED; PG8_LDA(At, 0, 0); PG8_STAGE(PG8_SA(1, 1), a1 + hstep, voffA);
;             PG8_WAIT_V(8); PG8_WAIT_L(0); PG8_BAR; PG8_MMA(0, 0, At, B0); PG8_MMA(0, 1, At, B1); PG8_BAR; PG8_SCHED;
;             PG8_LDA(At, 0, 1); PG8_STAGE(PG8_SB(0, 0), b2, voffB); PG8_STAGE(PG8_SB(0, 1), b2 + hstep, voffB); PG8_STAGE(PG8_SA(0, 0), a2, voffA);
.LBB0_1136:
	ds_read_b128 v[130:133], v186
	ds_read_b128 v[134:137], v186 offset:1024
	ds_read_b128 v[138:141], v186 offset:2048
	ds_read_b128 v[166:169], v186 offset:3072
	ds_read_b128 v[170:173], v187
	ds_read_b128 v[174:177], v187 offset:1024
	ds_read_b128 v[178:181], v187 offset:2048
	ds_read_b128 v[182:185], v187 offset:3072
	s_add_u32 s30, s70, 0xfffc0080
	s_addc_u32 s31, s71, -1
	s_cmp_eq_u32 s69, 12
	s_cselect_b32 s75, s1, s31
	s_cselect_b32 s74, s8, s30
	s_cselect_b32 s73, s21, s63
	s_cselect_b32 s72, s33, s61
	v_lshl_add_u64 v[202:203], s[70:71], 0, v[158:159]
	s_add_i32 m0, s28, 0xc000
	ds_read_b128 v[190:193], v188
	ds_read_b128 v[194:197], v188 offset:1024
	ds_read_b128 v[198:201], v188 offset:2048
	ds_read_b128 v[206:209], v188 offset:3072
	ds_read_b128 v[210:213], v188 offset:4096
	ds_read_b128 v[214:217], v188 offset:5120
	ds_read_b128 v[218:221], v188 offset:6144
	ds_read_b128 v[222:225], v188 offset:7168
	global_load_lds_dwordx4 v[202:203], off
	v_lshl_add_u64 v[202:203], s[70:71], 0, v[160:161]
	s_add_i32 m0, s28, 0xe000
	s_nop 0
	global_load_lds_dwordx4 v[202:203], off
	s_waitcnt vmcnt(8)
	s_waitcnt lgkmcnt(0)
	s_barrier
	s_setprio 1
	s_waitcnt lgkmcnt(0)
	v_mfma_f32_16x16x32_bf16 v[126:129], v[130:133], v[190:193], v[126:129]
	v_mfma_f32_16x16x32_bf16 v[122:125], v[138:141], v[190:193], v[122:125]
	v_mfma_f32_16x16x32_bf16 v[118:121], v[130:133], v[198:201], v[118:121]
	v_mfma_f32_16x16x32_bf16 v[114:117], v[138:141], v[198:201], v[114:117]
	v_mfma_f32_16x16x32_bf16 v[110:113], v[130:133], v[210:213], v[110:113]
	v_mfma_f32_16x16x32_bf16 v[106:109], v[138:141], v[210:213], v[106:109]
	v_mfma_f32_16x16x32_bf16 v[102:105], v[130:133], v[218:221], v[102:105]
	v_mfma_f32_16x16x32_bf16 v[98:101], v[138:141], v[218:221], v[98:101]
	v_mfma_f32_16x16x32_bf16 v[126:129], v[134:137], v[194:197], v[126:129]
	v_mfma_f32_16x16x32_bf16 v[122:125], v[166:169], v[194:197], v[122:125]
	v_mfma_f32_16x16x32_bf16 v[118:121], v[134:137], v[206:209], v[118:121]
	v_mfma_f32_16x16x32_bf16 v[114:117], v[166:169], v[206:209], v[114:117]
	v_mfma_f32_16x16x32_bf16 v[110:113], v[134:137], v[214:217], v[110:113]
	v_mfma_f32_16x16x32_bf16 v[106:109], v[166:169], v[214:217], v[106:109]
	v_mfma_f32_16x16x32_bf16 v[102:105], v[134:137], v[222:225], v[102:105]
	v_mfma_f32_16x16x32_bf16 v[98:101], v[166:169], v[222:225], v[98:101]
	s_setprio 0
	s_setprio 1
	v_mfma_f32_16x16x32_bf16 v[62:65], v[170:173], v[190:193], v[62:65]
	v_mfma_f32_16x16x32_bf16 v[58:61], v[178:181], v[190:193], v[58:61]
	v_mfma_f32_16x16x32_bf16 v[54:57], v[170:173], v[198:201], v[54:57]
	v_mfma_f32_16x16x32_bf16 v[50:53], v[178:181], v[198:201], v[50:53]
	v_mfma_f32_16x16x32_bf16 v[46:49], v[170:173], v[210:213], v[46:49]
	v_mfma_f32_16x16x32_bf16 v[42:45], v[178:181], v[210:213], v[42:45]
	v_mfma_f32_16x16x32_bf16 v[38:41], v[170:173], v[218:221], v[38:41]
	v_mfma_f32_16x16x32_bf16 v[34:37], v[178:181], v[218:221], v[34:37]
	v_mfma_f32_16x16x32_bf16 v[62:65], v[174:177], v[194:197], v[62:65]
	v_mfma_f32_16x16x32_bf16 v[58:61], v[182:185], v[194:197], v[58:61]
	v_mfma_f32_16x16x32_bf16 v[54:57], v[174:177], v[206:209], v[54:57]
	v_mfma_f32_16x16x32_bf16 v[50:53], v[182:185], v[206:209], v[50:53]
	s_setprio 2
	s_barrier
	v_mfma_f32_16x16x32_bf16 v[46:49], v[174:177], v[214:217], v[46:49]
	v_mfma_f32_16x16x32_bf16 v[42:45], v[182:185], v[214:217], v[42:45]
	v_mfma_f32_16x16x32_bf16 v[38:41], v[174:177], v[222:225], v[38:41]
	v_mfma_f32_16x16x32_bf16 v[34:37], v[182:185], v[222:225], v[34:37]
	s_setprio 0
	s_add_i32 s30, s7, s81
	v_lshl_add_u64 v[202:203], s[72:73], 0, v[146:147]
	s_mov_b32 m0, s30
	ds_read_b128 v[190:193], v188 offset:16384
	ds_read_b128 v[194:197], v188 offset:17408
	ds_read_b128 v[198:201], v188 offset:18432
	ds_read_b128 v[206:209], v188 offset:19456
	ds_read_b128 v[210:213], v188 offset:20480
	ds_read_b128 v[214:217], v188 offset:21504
	ds_read_b128 v[218:221], v188 offset:22528
	ds_read_b128 v[222:225], v188 offset:23552
	global_load_lds_dwordx4 v[202:203], off
	s_add_i32 m0, s30, 0x2000
	s_add_u32 s30, s72, 0x40000
	v_lshl_add_u64 v[226:227], s[72:73], 0, v[150:151]
	s_addc_u32 s31, s73, 0
	s_add_i32 s94, s92, s81
	global_load_lds_dwordx4 v[226:227], off
	v_lshl_add_u64 v[228:229], s[30:31], 0, v[146:147]
	s_mov_b32 m0, s94
	v_lshl_add_u64 v[230:231], s[74:75], 0, v[148:149]
	global_load_lds_dwordx4 v[228:229], off
	v_lshl_add_u64 v[228:229], s[30:31], 0, v[150:151]
	s_add_i32 m0, s94, 0x2000
	s_nop 0
	global_load_lds_dwordx4 v[228:229], off
	v_lshl_add_u64 v[228:229], s[74:75], 0, v[144:145]
	s_mov_b32 m0, s28
	s_nop 0
	global_load_lds_dwordx4 v[228:229], off
	s_mov_b32 m0, s29
	s_nop 0
	global_load_lds_dwordx4 v[230:231], off
	s_waitcnt vmcnt(8)
	s_waitcnt lgkmcnt(0)
	s_barrier
; #define PG8_STAGE(bufoff, gbase, voff) do { _Pragma("unroll") for (int _i = 0; _i < 2; ++_i) \
;         __builtin_amdgcn_global_load_lds((const unsigned*)((const char*)(gbase) + (voff)[_i]), (PG8_LAS unsigned*)(lds + (bufoff) + ldsw + _i * 8192), 16, 0, 0); } while (0)
; #define PG8_LDA(dst, b, h) do { _Pragma("unroll") for (int m = 0; m < 4; ++m) _Pragma("unroll") for (int k = 0; k < 2; ++k) dst[m][k] = *(const PG8_LAS bf16x8*)(lds + PG8_SA(b, h) + aoff + m * 2048 + k * 1024); } while (0)
; #define PG8_LDB(dst, b, h) do { _Pragma("unroll") for (int n = 0; n < 2; ++n) _Pragma("unroll") for (int k = 0; k < 2; ++k) dst[n][k] = *(const PG8_LAS bf16x8*)(lds + PG8_SB(b, h) + boff + n * 2048 + k * 1024); } while (0)
; #define PG8_MMA(ai, bj, At, Bt) do { __builtin_amdgcn_s_setprio(1); _Pragma("unroll") for (int m = 0; m < 4; ++m) _Pragma("unroll") for (int n = 0; n < 2; ++n) _Pragma("unroll") for (int k = 0; k < 2; ++k) \
;         acc[ai][bj][m][n] = __builtin_amdgcn_mfma_f32_16x16x32_bf16(Bt[n][k], At[m][k], acc[ai][bj][m][n], 0, 0, 0); __builtin_amdgcn_s_setprio(0); } while (0)
; #define PG8_WAIT_V(n) asm volatile("s_waitcnt vmcnt(" #n ")" ::: "memory")
; #define PG8_WAIT_L(n) asm volatile("s_waitcnt lgkmcnt(" #n ")" ::: "memory")
; #define PG8_BAR __builtin_amdgcn_s_barrier()
; #define PG8_SCHED __builtin_amdgcn_sched_barrier(0)
; template <class Epi, class Sched, bool ALIGN_EPI = false, bool SP2 = false>
; __device__ __forceinline__ void gemm_phase(PG8_LAS unsigned char* lds, const Gemm g, const Sched& S, const Epi& E) {
;     ...
;             PG8_WAIT_V(8); PG8_WAIT_L(0); PG8_BAR; PG8_MMA(1, 0, At, B0); PG8_MMA(1, 1, At, B1); PG8_BAR; PG8_SCHED;
;             PG8_LDB(B0, 1, 0); PG8_LDB(B1, 1, 1); PG8_SCHED; PG8_LDA(At, 1, 0); PG8_STAGE(PG8_SA(0, 1), a2 + hstep, voffA);
;             PG8_WAIT_V(8); PG8_WAIT_L(0); PG8_BAR; PG8_MMA(0, 0, At, B0); PG8_MMA(0, 1, At, B1); PG8_BAR; PG8_SCHED;
	s_setprio 1
	s_waitcnt lgkmcnt(0)
	v_mfma_f32_16x16x32_bf16 v[94:97], v[130:133], v[190:193], v[94:97]
	v_mfma_f32_16x16x32_bf16 v[90:93], v[138:141], v[190:193], v[90:93]
	v_mfma_f32_16x16x32_bf16 v[86:89], v[130:133], v[198:201], v[86:89]
	v_mfma_f32_16x16x32_bf16 v[82:85], v[138:141], v[198:201], v[82:85]
	v_mfma_f32_16x16x32_bf16 v[78:81], v[130:133], v[210:213], v[78:81]
	v_mfma_f32_16x16x32_bf16 v[74:77], v[138:141], v[210:213], v[74:77]
	v_mfma_f32_16x16x32_bf16 v[70:73], v[130:133], v[218:221], v[70:73]
	v_mfma_f32_16x16x32_bf16 v[66:69], v[138:141], v[218:221], v[66:69]
	v_mfma_f32_16x16x32_bf16 v[94:97], v[134:137], v[194:197], v[94:97]
	v_mfma_f32_16x16x32_bf16 v[90:93], v[166:169], v[194:197], v[90:93]
	v_mfma_f32_16x16x32_bf16 v[86:89], v[134:137], v[206:209], v[86:89]
	v_mfma_f32_16x16x32_bf16 v[82:85], v[166:169], v[206:209], v[82:85]
	v_mfma_f32_16x16x32_bf16 v[78:81], v[134:137], v[214:217], v[78:81]
	v_mfma_f32_16x16x32_bf16 v[74:77], v[166:169], v[214:217], v[74:77]
	v_mfma_f32_16x16x32_bf16 v[70:73], v[134:137], v[222:225], v[70:73]
	v_mfma_f32_16x16x32_bf16 v[66:69], v[166:169], v[222:225], v[66:69]
	s_setprio 0
	s_setprio 1
	v_mfma_f32_16x16x32_bf16 v[30:33], v[170:173], v[190:193], v[30:33]
	v_mfma_f32_16x16x32_bf16 v[26:29], v[178:181], v[190:193], v[26:29]
	v_mfma_f32_16x16x32_bf16 v[22:25], v[170:173], v[198:201], v[22:25]
	v_mfma_f32_16x16x32_bf16 v[18:21], v[178:181], v[198:201], v[18:21]
	v_mfma_f32_16x16x32_bf16 v[14:17], v[170:173], v[210:213], v[14:17]
	v_mfma_f32_16x16x32_bf16 v[10:13], v[178:181], v[210:213], v[10:13]
	v_mfma_f32_16x16x32_bf16 v[6:9], v[170:173], v[218:221], v[6:9]
	v_mfma_f32_16x16x32_bf16 v[2:5], v[178:181], v[218:221], v[2:5]
	v_mfma_f32_16x16x32_bf16 v[30:33], v[174:177], v[194:197], v[30:33]
	v_mfma_f32_16x16x32_bf16 v[26:29], v[182:185], v[194:197], v[26:29]
	v_mfma_f32_16x16x32_bf16 v[22:25], v[174:177], v[206:209], v[22:25]
	v_mfma_f32_16x16x32_bf16 v[18:21], v[182:185], v[206:209], v[18:21]
	s_setprio 2
	s_barrier
	v_mfma_f32_16x16x32_bf16 v[14:17], v[174:177], v[214:217], v[14:17]
	v_mfma_f32_16x16x32_bf16 v[10:13], v[182:185], v[214:217], v[10:13]
	v_mfma_f32_16x16x32_bf16 v[6:9], v[174:177], v[222:225], v[6:9]
	v_mfma_f32_16x16x32_bf16 v[2:5], v[182:185], v[222:225], v[2:5]
	s_setprio 0
	s_add_i32 s94, 0, 0x18000
	v_add_u32_e32 v152, s94, v155
	s_add_i32 s95, 0, 0x1c000
	ds_read_b128 v[130:133], v152
	ds_read_b128 v[134:137], v152 offset:1024
	ds_read_b128 v[138:141], v152 offset:2048
	ds_read_b128 v[166:169], v152 offset:3072
	v_add_u32_e32 v152, s95, v155
	ds_read_b128 v[170:173], v152
	ds_read_b128 v[174:177], v152 offset:1024
	ds_read_b128 v[178:181], v152 offset:2048
	ds_read_b128 v[182:185], v152 offset:3072
	s_add_u32 s30, s74, 0x40000
	s_addc_u32 s31, s75, 0
	s_mov_b32 m0, s82
	v_lshl_add_u64 v[232:233], s[30:31], 0, v[144:145]
	ds_read_b128 v[190:193], v188 offset:32768
	ds_read_b128 v[194:197], v188 offset:33792
	ds_read_b128 v[198:201], v188 offset:34816
	ds_read_b128 v[206:209], v188 offset:35840
	ds_read_b128 v[210:213], v188 offset:36864
	ds_read_b128 v[214:217], v188 offset:37888
	ds_read_b128 v[218:221], v188 offset:38912
	ds_read_b128 v[222:225], v188 offset:39936
	global_load_lds_dwordx4 v[232:233], off
	v_lshl_add_u64 v[232:233], s[30:31], 0, v[148:149]
	s_mov_b32 m0, s83
	s_nop 0
	global_load_lds_dwordx4 v[232:233], off
	s_waitcnt vmcnt(8)
	s_waitcnt lgkmcnt(0)
	s_barrier
	s_setprio 1
	s_waitcnt lgkmcnt(0)
	v_mfma_f32_16x16x32_bf16 v[126:129], v[130:133], v[190:193], v[126:129]
	v_mfma_f32_16x16x32_bf16 v[122:125], v[138:141], v[190:193], v[122:125]
	v_mfma_f32_16x16x32_bf16 v[118:121], v[130:133], v[198:201], v[118:121]
	v_mfma_f32_16x16x32_bf16 v[114:117], v[138:141], v[198:201], v[114:117]
	v_mfma_f32_16x16x32_bf16 v[110:113], v[130:133], v[210:213], v[110:113]
	v_mfma_f32_16x16x32_bf16 v[106:109], v[138:141], v[210:213], v[106:109]
	v_mfma_f32_16x16x32_bf16 v[102:105], v[130:133], v[218:221], v[102:105]
	v_mfma_f32_16x16x32_bf16 v[98:101], v[138:141], v[218:221], v[98:101]
	v_mfma_f32_16x16x32_bf16 v[126:129], v[134:137], v[194:197], v[126:129]
	v_mfma_f32_16x16x32_bf16 v[122:125], v[166:169], v[194:197], v[122:125]
	v_mfma_f32_16x16x32_bf16 v[118:121], v[134:137], v[206:209], v[118:121]
	v_mfma_f32_16x16x32_bf16 v[114:117], v[166:169], v[206:209], v[114:117]
	v_mfma_f32_16x16x32_bf16 v[110:113], v[134:137], v[214:217], v[110:113]
	v_mfma_f32_16x16x32_bf16 v[106:109], v[166:169], v[214:217], v[106:109]
	v_mfma_f32_16x16x32_bf16 v[102:105], v[134:137], v[222:225], v[102:105]
	v_mfma_f32_16x16x32_bf16 v[98:101], v[166:169], v[222:225], v[98:101]
	s_setprio 0
	s_setprio 1
	v_mfma_f32_16x16x32_bf16 v[62:65], v[170:173], v[190:193], v[62:65]
	v_mfma_f32_16x16x32_bf16 v[58:61], v[178:181], v[190:193], v[58:61]
	v_mfma_f32_16x16x32_bf16 v[54:57], v[170:173], v[198:201], v[54:57]
	v_mfma_f32_16x16x32_bf16 v[50:53], v[178:181], v[198:201], v[50:53]
	v_mfma_f32_16x16x32_bf16 v[46:49], v[170:173], v[210:213], v[46:49]
	v_mfma_f32_16x16x32_bf16 v[42:45], v[178:181], v[210:213], v[42:45]
	v_mfma_f32_16x16x32_bf16 v[38:41], v[170:173], v[218:221], v[38:41]
	v_mfma_f32_16x16x32_bf16 v[34:37], v[178:181], v[218:221], v[34:37]
	v_mfma_f32_16x16x32_bf16 v[62:65], v[174:177], v[194:197], v[62:65]
	v_mfma_f32_16x16x32_bf16 v[58:61], v[182:185], v[194:197], v[58:61]
	v_mfma_f32_16x16x32_bf16 v[54:57], v[174:177], v[206:209], v[54:57]
	v_mfma_f32_16x16x32_bf16 v[50:53], v[182:185], v[206:209], v[50:53]
	s_setprio 2
	s_barrier
; #define PG8_STAGE(bufoff, gbase, voff) do { _Pragma("unroll") for (int _i = 0; _i < 2; ++_i) \
;         __builtin_amdgcn_global_load_lds((const unsigned*)((const char*)(gbase) + (voff)[_i]), (PG8_LAS unsigned*)(lds + (bufoff) + ldsw + _i * 8192), 16, 0, 0); } while (0)
; #define PG8_LDA(dst, b, h) do { _Pragma("unroll") for (int m = 0; m < 4; ++m) _Pragma("unroll") for (int k = 0; k < 2; ++k) dst[m][k] = *(const PG8_LAS bf16x8*)(lds + PG8_SA(b, h) + aoff + m * 2048 + k * 1024); } while (0)
; #define PG8_MMA(ai, bj, At, Bt) do { __builtin_amdgcn_s_setprio(1); _Pragma("unroll") for (int m = 0; m < 4; ++m) _Pragma("unroll") for (int n = 0; n < 2; ++n) _Pragma("unroll") for (int k = 0; k < 2; ++k) \
;         acc[ai][bj][m][n] = __builtin_amdgcn_mfma_f32_16x16x32_bf16(Bt[n][k], At[m][k], acc[ai][bj][m][n], 0, 0, 0); __builtin_amdgcn_s_setprio(0); } while (0)
; #define PG8_WAIT_V(n) asm volatile("s_waitcnt vmcnt(" #n ")" ::: "memory")
; #define PG8_WAIT_L(n) asm volatile("s_waitcnt lgkmcnt(" #n ")" ::: "memory")
; #define PG8_BAR __builtin_amdgcn_s_barrier()
; #define PG8_SCHED __builtin_amdgcn_sched_barrier(0)
; template <class Epi, class Sched, bool ALIGN_EPI = false, bool SP2 = false>
; __device__ __forceinline__ void gemm_phase(PG8_LAS unsigned char* lds, const Gemm g, const Sched& S, const Epi& E) {
;     ...
;         for (int t = 0; t < nt; t += 2) {
;             const bool last = (t == nt - 2);
;             const char* a1 = cA + (size_t)(t + 1) * kstep;
;             const char* a2 = last ? nA : cA + (size_t)(t + 2) * kstep; const char* b2 = last ? nB : cB + (size_t)(t + 2) * kstep;
;             const char* a3 = a2 + kstep; const char* b3 = b2 + kstep;
;     ...
;             PG8_WAIT_V(8); PG8_WAIT_L(0); PG8_BAR; PG8_MMA(0, 0, At, B0); PG8_MMA(0, 1, At, B1); PG8_BAR; PG8_SCHED;
;             PG8_LDA(At, 1, 1); PG8_STAGE(PG8_SB(1, 0), b3, voffB); PG8_STAGE(PG8_SB(1, 1), b3 + hstep, voffB); PG8_STAGE(PG8_SA(1, 0), a3, voffA);
;             PG8_WAIT_V(8); PG8_WAIT_L(0); PG8_BAR; PG8_MMA(1, 0, At, B0); PG8_MMA(1, 1, At, B1); PG8_BAR; PG8_SCHED;
;     ...
;         if constexpr (ALIGN_EPI) { if (wr == 0) PG8_BAR; }
	v_mfma_f32_16x16x32_bf16 v[46:49], v[174:177], v[214:217], v[46:49]
	v_mfma_f32_16x16x32_bf16 v[42:45], v[182:185], v[214:217], v[42:45]
	v_mfma_f32_16x16x32_bf16 v[38:41], v[174:177], v[222:225], v[38:41]
	v_mfma_f32_16x16x32_bf16 v[34:37], v[182:185], v[222:225], v[34:37]
	s_setprio 0
	s_add_i32 s30, s94, s81
	v_lshl_add_u64 v[202:203], v[202:203], 0, s[40:41]
	s_mov_b32 m0, s30
	ds_read_b128 v[190:193], v188 offset:49152
	ds_read_b128 v[194:197], v188 offset:50176
	ds_read_b128 v[198:201], v188 offset:51200
	ds_read_b128 v[206:209], v188 offset:52224
	ds_read_b128 v[210:213], v188 offset:53248
	ds_read_b128 v[214:217], v188 offset:54272
	ds_read_b128 v[218:221], v188 offset:55296
	ds_read_b128 v[222:225], v188 offset:56320
	global_load_lds_dwordx4 v[202:203], off
	s_add_i32 m0, s30, 0x2000
	s_add_u32 s30, s72, 0x40080
	v_lshl_add_u64 v[202:203], v[226:227], 0, s[40:41]
	s_addc_u32 s31, s73, 0
	s_add_i32 s72, s95, s81
	global_load_lds_dwordx4 v[202:203], off
	v_lshl_add_u64 v[202:203], s[30:31], 0, v[146:147]
	s_mov_b32 m0, s72
	s_nop 0
	global_load_lds_dwordx4 v[202:203], off
	v_lshl_add_u64 v[202:203], s[30:31], 0, v[150:151]
	s_add_i32 m0, s72, 0x2000
	s_nop 0
	global_load_lds_dwordx4 v[202:203], off
	v_lshl_add_u64 v[202:203], v[228:229], 0, s[40:41]
	s_mov_b32 m0, s97
	s_nop 0
	global_load_lds_dwordx4 v[202:203], off
	v_lshl_add_u64 v[202:203], v[230:231], 0, s[40:41]
	s_mov_b32 m0, s50
	s_nop 0
	global_load_lds_dwordx4 v[202:203], off
	s_waitcnt vmcnt(8)
	s_waitcnt lgkmcnt(0)
	s_barrier
	s_setprio 1
	s_waitcnt lgkmcnt(0)
	v_mfma_f32_16x16x32_bf16 v[94:97], v[130:133], v[190:193], v[94:97]
	v_mfma_f32_16x16x32_bf16 v[90:93], v[138:141], v[190:193], v[90:93]
	v_mfma_f32_16x16x32_bf16 v[86:89], v[130:133], v[198:201], v[86:89]
	v_mfma_f32_16x16x32_bf16 v[82:85], v[138:141], v[198:201], v[82:85]
	v_mfma_f32_16x16x32_bf16 v[78:81], v[130:133], v[210:213], v[78:81]
	v_mfma_f32_16x16x32_bf16 v[74:77], v[138:141], v[210:213], v[74:77]
	v_mfma_f32_16x16x32_bf16 v[70:73], v[130:133], v[218:221], v[70:73]
	v_mfma_f32_16x16x32_bf16 v[66:69], v[138:141], v[218:221], v[66:69]
	v_mfma_f32_16x16x32_bf16 v[94:97], v[134:137], v[194:197], v[94:97]
	v_mfma_f32_16x16x32_bf16 v[90:93], v[166:169], v[194:197], v[90:93]
	v_mfma_f32_16x16x32_bf16 v[86:89], v[134:137], v[206:209], v[86:89]
	v_mfma_f32_16x16x32_bf16 v[82:85], v[166:169], v[206:209], v[82:85]
	v_mfma_f32_16x16x32_bf16 v[78:81], v[134:137], v[214:217], v[78:81]
	v_mfma_f32_16x16x32_bf16 v[74:77], v[166:169], v[214:217], v[74:77]
	v_mfma_f32_16x16x32_bf16 v[70:73], v[134:137], v[222:225], v[70:73]
	v_mfma_f32_16x16x32_bf16 v[66:69], v[166:169], v[222:225], v[66:69]
	s_setprio 0
	s_setprio 1
	v_mfma_f32_16x16x32_bf16 v[30:33], v[170:173], v[190:193], v[30:33]
	v_mfma_f32_16x16x32_bf16 v[26:29], v[178:181], v[190:193], v[26:29]
	v_mfma_f32_16x16x32_bf16 v[22:25], v[170:173], v[198:201], v[22:25]
	v_mfma_f32_16x16x32_bf16 v[18:21], v[178:181], v[198:201], v[18:21]
	v_mfma_f32_16x16x32_bf16 v[14:17], v[170:173], v[210:213], v[14:17]
	v_mfma_f32_16x16x32_bf16 v[10:13], v[178:181], v[210:213], v[10:13]
	v_mfma_f32_16x16x32_bf16 v[6:9], v[170:173], v[218:221], v[6:9]
	v_mfma_f32_16x16x32_bf16 v[2:5], v[178:181], v[218:221], v[2:5]
	v_mfma_f32_16x16x32_bf16 v[30:33], v[174:177], v[194:197], v[30:33]
	v_mfma_f32_16x16x32_bf16 v[26:29], v[182:185], v[194:197], v[26:29]
	v_mfma_f32_16x16x32_bf16 v[22:25], v[174:177], v[206:209], v[22:25]
	v_mfma_f32_16x16x32_bf16 v[18:21], v[182:185], v[206:209], v[18:21]
	s_setprio 2
	s_barrier
	v_mfma_f32_16x16x32_bf16 v[14:17], v[174:177], v[214:217], v[14:17]
	v_mfma_f32_16x16x32_bf16 v[10:13], v[182:185], v[214:217], v[10:13]
	v_mfma_f32_16x16x32_bf16 v[6:9], v[174:177], v[222:225], v[6:9]
	v_mfma_f32_16x16x32_bf16 v[2:5], v[182:185], v[222:225], v[2:5]
	s_setprio 0
	s_add_i32 s69, s69, 2
	s_add_u32 s70, s70, 0x100
	s_addc_u32 s71, s71, 0
	s_add_u32 s61, s61, 0x100
	s_addc_u32 s63, s63, 0
	s_cmp_gt_u32 s69, 13
	s_cbranch_scc0 .LBB0_1136
	s_and_b64 vcc, exec, s[44:45]
	s_cbranch_vccz .LBB0_1139
	s_barrier

; #define PG8_STAGE(bufoff, gbase, voff) do { _Pragma("unroll") for (int _i = 0; _i < 2; ++_i) \
;         __builtin_amdgcn_global_load_lds((const unsigned*)((const char*)(gbase) + (voff)[_i]), (PG8_LAS unsigned*)(lds + (bufoff) + ldsw + _i * 8192), 16, 0, 0); } while (0)
; #define PG8_LDA(dst, b, h) do { _Pragma("unroll") for (int m = 0; m < 4; ++m) _Pragma("unroll") for (int k = 0; k < 2; ++k) dst[m][k] = *(const PG8_LAS bf16x8*)(lds + PG8_SA(b, h) + aoff + m * 2048 + k * 1024); } while (0)
; #define PG8_LDB(dst, b, h) do { _Pragma("unroll") for (int n = 0; n < 2; ++n) _Pragma("unroll") for (int k = 0; k < 2; ++k) dst[n][k] = *(const PG8_LAS bf16x8*)(lds + PG8_SB(b, h) + boff + n * 2048 + k * 1024); } while (0)
; #define PG8_MMA(ai, bj, At, Bt) do { __builtin_amdgcn_s_setprio(1); _Pragma("unroll") for (int m = 0; m < 4; ++m) _Pragma("unroll") for (int n = 0; n < 2; ++n) _Pragma("unroll") for (int k = 0; k < 2; ++k) \
;         acc[ai][bj][m][n] = __builtin_amdgcn_mfma_f32_16x16x32_bf16(Bt[n][k], At[m][k], acc[ai][bj][m][n], 0, 0, 0); __builtin_amdgcn_s_setprio(0); } while (0)
; #define PG8_WAIT_V(n) asm volatile("s_waitcnt vmcnt(" #n ")" ::: "memory")
; #define PG8_BAR __builtin_amdgcn_s_barrier()
; template <class Epi, class Sched, bool ALIGN_EPI = false, bool SP2 = false>
; __device__ __forceinline__ void gemm_phase(PG8_LAS unsigned char* lds, const Gemm g, const Sched& S, const Epi& E) {
;     ...
;         for (int t = 0; t < nt; t += 2) {
;             const bool last = (t == nt - 2);
;             const char* a1 = cA + (size_t)(t + 1) * kstep;
;             const char* a2 = last ? nA : cA + (size_t)(t + 2) * kstep; const char* b2 = last ? nB : cB + (size_t)(t + 2) * kstep;
;             const char* a3 = a2 + kstep; const char* b3 = b2 + kstep;
;             if (last && has_next) S.a_ready(nxt);
;             if constexpr (SP2) {
;             PG8_LDB(B0, 0, 0); PG8_LDB(B1, 0, 1); PG8_SCHED; PG8_LDA(At, 0, 0); PG8_STAGE(PG8_SA(1, 1), a1 + hstep, voffA);
;             PG8_WAIT_V(8); PG8_WAIT_L(0); PG8_BAR; PG8_MMA(0, 0, At, B0); PG8_MMA(0, 1, At, B1); PG8_BAR; PG8_SCHED;
;             PG8_LDA(At, 0, 1); PG8_STAGE(PG8_SB(0, 0), b2, voffB); PG8_STAGE(PG8_SB(0, 1), b2 + hstep, voffB); PG8_STAGE(PG8_SA(0, 0), a2, voffA);
;             PG8_WAIT_V(8); PG8_WAIT_L(0); PG8_BAR; PG8_MMA(1, 0, At, B0); PG8_MMA(1, 1, At, B1); PG8_BAR; PG8_SCHED;
.LBB0_1673:
	ds_read_b128 v[122:125], v184
	ds_read_b128 v[126:129], v184 offset:1024
	ds_read_b128 v[130:133], v184 offset:2048
	ds_read_b128 v[134:137], v184 offset:3072
	ds_read_b128 v[142:145], v185
	ds_read_b128 v[146:149], v185 offset:1024
	ds_read_b128 v[150:153], v185 offset:2048
	ds_read_b128 v[158:161], v185 offset:3072
	s_add_u32 s30, s26, 0xfffc0080
	s_addc_u32 s31, s27, -1
	s_cmp_eq_u32 s58, 12
	s_cselect_b32 s39, s19, s31
	s_cselect_b32 s38, s54, s30
	s_cselect_b32 s37, s17, s57
	s_cselect_b32 s36, s55, s56
	v_lshl_add_u64 v[218:219], s[26:27], 0, v[170:171]
	s_add_i32 m0, s25, 0xc000
	ds_read_b128 v[178:181], v186
	ds_read_b128 v[188:191], v186 offset:1024
	ds_read_b128 v[192:195], v186 offset:2048
	ds_read_b128 v[196:199], v186 offset:3072
	ds_read_b128 v[200:203], v186 offset:4096
	ds_read_b128 v[206:209], v186 offset:5120
	ds_read_b128 v[210:213], v186 offset:6144
	ds_read_b128 v[214:217], v186 offset:7168
	global_load_lds_dwordx4 v[218:219], off
	v_lshl_add_u64 v[218:219], s[26:27], 0, v[172:173]
	s_add_i32 m0, s25, 0xe000
	s_nop 0
	global_load_lds_dwordx4 v[218:219], off
	s_waitcnt vmcnt(8)
	s_waitcnt lgkmcnt(0)
	s_barrier
	s_setprio 1
	s_waitcnt lgkmcnt(0)
	v_mfma_f32_16x16x32_bf16 v[154:157], v[122:125], v[178:181], v[154:157]
	v_mfma_f32_16x16x32_bf16 v[138:141], v[130:133], v[178:181], v[138:141]
	v_mfma_f32_16x16x32_bf16 v[114:117], v[122:125], v[192:195], v[114:117]
	v_mfma_f32_16x16x32_bf16 v[106:109], v[130:133], v[192:195], v[106:109]
	v_mfma_f32_16x16x32_bf16 v[94:97], v[122:125], v[200:203], v[94:97]
	v_mfma_f32_16x16x32_bf16 v[90:93], v[130:133], v[200:203], v[90:93]
	v_mfma_f32_16x16x32_bf16 v[82:85], v[122:125], v[210:213], v[82:85]
	v_mfma_f32_16x16x32_bf16 v[74:77], v[130:133], v[210:213], v[74:77]
	v_mfma_f32_16x16x32_bf16 v[154:157], v[126:129], v[188:191], v[154:157]
	v_mfma_f32_16x16x32_bf16 v[138:141], v[134:137], v[188:191], v[138:141]
	v_mfma_f32_16x16x32_bf16 v[114:117], v[126:129], v[196:199], v[114:117]
	v_mfma_f32_16x16x32_bf16 v[106:109], v[134:137], v[196:199], v[106:109]
	v_mfma_f32_16x16x32_bf16 v[94:97], v[126:129], v[206:209], v[94:97]
	v_mfma_f32_16x16x32_bf16 v[90:93], v[134:137], v[206:209], v[90:93]
	v_mfma_f32_16x16x32_bf16 v[82:85], v[126:129], v[214:217], v[82:85]
	v_mfma_f32_16x16x32_bf16 v[74:77], v[134:137], v[214:217], v[74:77]
	s_setprio 0
	s_setprio 1
	v_mfma_f32_16x16x32_bf16 v[118:121], v[142:145], v[178:181], v[118:121]
	v_mfma_f32_16x16x32_bf16 v[110:113], v[150:153], v[178:181], v[110:113]
	v_mfma_f32_16x16x32_bf16 v[102:105], v[142:145], v[192:195], v[102:105]
	v_mfma_f32_16x16x32_bf16 v[98:101], v[150:153], v[192:195], v[98:101]
	v_mfma_f32_16x16x32_bf16 v[86:89], v[142:145], v[200:203], v[86:89]
	v_mfma_f32_16x16x32_bf16 v[78:81], v[150:153], v[200:203], v[78:81]
	v_mfma_f32_16x16x32_bf16 v[70:73], v[142:145], v[210:213], v[70:73]
	v_mfma_f32_16x16x32_bf16 v[66:69], v[150:153], v[210:213], v[66:69]
	v_mfma_f32_16x16x32_bf16 v[118:121], v[146:149], v[188:191], v[118:121]
	v_mfma_f32_16x16x32_bf16 v[110:113], v[158:161], v[188:191], v[110:113]
	v_mfma_f32_16x16x32_bf16 v[102:105], v[146:149], v[196:199], v[102:105]
	v_mfma_f32_16x16x32_bf16 v[98:101], v[158:161], v[196:199], v[98:101]
	s_setprio 2
	s_barrier
	v_mfma_f32_16x16x32_bf16 v[86:89], v[146:149], v[206:209], v[86:89]
	v_mfma_f32_16x16x32_bf16 v[78:81], v[158:161], v[206:209], v[78:81]
	v_mfma_f32_16x16x32_bf16 v[70:73], v[146:149], v[214:217], v[70:73]
	v_mfma_f32_16x16x32_bf16 v[66:69], v[158:161], v[214:217], v[66:69]
	s_setprio 0
	s_add_i32 s30, s51, s33
	v_lshl_add_u64 v[218:219], s[36:37], 0, v[164:165]
	s_mov_b32 m0, s30
	ds_read_b128 v[178:181], v186 offset:16384
	ds_read_b128 v[188:191], v186 offset:17408
	ds_read_b128 v[192:195], v186 offset:18432
	ds_read_b128 v[196:199], v186 offset:19456
	ds_read_b128 v[200:203], v186 offset:20480
	ds_read_b128 v[206:209], v186 offset:21504
	ds_read_b128 v[210:213], v186 offset:22528
	ds_read_b128 v[214:217], v186 offset:23552
	global_load_lds_dwordx4 v[218:219], off
	s_add_i32 m0, s30, 0x2000
	s_add_u32 s30, s36, 0x40000
	v_lshl_add_u64 v[220:221], s[36:37], 0, v[168:169]
	s_addc_u32 s31, s37, 0
	s_add_i32 s59, s52, s33
	global_load_lds_dwordx4 v[220:221], off
	v_lshl_add_u64 v[222:223], s[30:31], 0, v[164:165]
	s_mov_b32 m0, s59
	v_lshl_add_u64 v[224:225], s[38:39], 0, v[166:167]
	global_load_lds_dwordx4 v[222:223], off
	v_lshl_add_u64 v[222:223], s[30:31], 0, v[168:169]
	s_add_i32 m0, s59, 0x2000
	s_nop 0
	global_load_lds_dwordx4 v[222:223], off
	v_lshl_add_u64 v[222:223], s[38:39], 0, v[162:163]
	s_mov_b32 m0, s25
	s_nop 0
	global_load_lds_dwordx4 v[222:223], off
	s_mov_b32 m0, s40
	s_nop 0
	global_load_lds_dwordx4 v[224:225], off
	s_waitcnt vmcnt(8)
	s_waitcnt lgkmcnt(0)
	s_barrier
; #define PG8_STAGE(bufoff, gbase, voff) do { _Pragma("unroll") for (int _i = 0; _i < 2; ++_i) \
;         __builtin_amdgcn_global_load_lds((const unsigned*)((const char*)(gbase) + (voff)[_i]), (PG8_LAS unsigned*)(lds + (bufoff) + ldsw + _i * 8192), 16, 0, 0); } while (0)
; #define PG8_LDA(dst, b, h) do { _Pragma("unroll") for (int m = 0; m < 4; ++m) _Pragma("unroll") for (int k = 0; k < 2; ++k) dst[m][k] = *(const PG8_LAS bf16x8*)(lds + PG8_SA(b, h) + aoff + m * 2048 + k * 1024); } while (0)
; #define PG8_LDB(dst, b, h) do { _Pragma("unroll") for (int n = 0; n < 2; ++n) _Pragma("unroll") for (int k = 0; k < 2; ++k) dst[n][k] = *(const PG8_LAS bf16x8*)(lds + PG8_SB(b, h) + boff + n * 2048 + k * 1024); } while (0)
; #define PG8_MMA(ai, bj, At, Bt) do { __builtin_amdgcn_s_setprio(1); _Pragma("unroll") for (int m = 0; m < 4; ++m) _Pragma("unroll") for (int n = 0; n < 2; ++n) _Pragma("unroll") for (int k = 0; k < 2; ++k) \
;         acc[ai][bj][m][n] = __builtin_amdgcn_mfma_f32_16x16x32_bf16(Bt[n][k], At[m][k], acc[ai][bj][m][n], 0, 0, 0); __builtin_amdgcn_s_setprio(0); } while (0)
; #define PG8_WAIT_V(n) asm volatile("s_waitcnt vmcnt(" #n ")" ::: "memory")
; #define PG8_WAIT_L(n) asm volatile("s_waitcnt lgkmcnt(" #n ")" ::: "memory")
; #define PG8_BAR __builtin_amdgcn_s_barrier()
; #define PG8_SCHED __builtin_amdgcn_sched_barrier(0)
; template <class Epi, class Sched, bool ALIGN_EPI = false, bool SP2 = false>
; __device__ __forceinline__ void gemm_phase(PG8_LAS unsigned char* lds, const Gemm g, const Sched& S, const Epi& E) {
;     ...
;             PG8_WAIT_V(8); PG8_WAIT_L(0); PG8_BAR; PG8_MMA(0, 0, At, B0); PG8_MMA(0, 1, At, B1); PG8_BAR; PG8_SCHED;
;             PG8_LDA(At, 0, 1); PG8_STAGE(PG8_SB(0, 0), b2, voffB); PG8_STAGE(PG8_SB(0, 1), b2 + hstep, voffB); PG8_STAGE(PG8_SA(0, 0), a2, voffA);
;             PG8_WAIT_V(8); PG8_WAIT_L(0); PG8_BAR; PG8_MMA(1, 0, At, B0); PG8_MMA(1, 1, At, B1); PG8_BAR; PG8_SCHED;
;             PG8_LDB(B0, 1, 0); PG8_LDB(B1, 1, 1); PG8_SCHED; PG8_LDA(At, 1, 0); PG8_STAGE(PG8_SA(0, 1), a2 + hstep, voffA);
;             PG8_WAIT_V(8); PG8_WAIT_L(0); PG8_BAR; PG8_MMA(0, 0, At, B0); PG8_MMA(0, 1, At, B1); PG8_BAR; PG8_SCHED;
	s_setprio 1
	s_waitcnt lgkmcnt(0)
	v_mfma_f32_16x16x32_bf16 v[62:65], v[122:125], v[178:181], v[62:65]
	v_mfma_f32_16x16x32_bf16 v[58:61], v[130:133], v[178:181], v[58:61]
	v_mfma_f32_16x16x32_bf16 v[50:53], v[122:125], v[192:195], v[50:53]
	v_mfma_f32_16x16x32_bf16 v[42:45], v[130:133], v[192:195], v[42:45]
	v_mfma_f32_16x16x32_bf16 v[30:33], v[122:125], v[200:203], v[30:33]
	v_mfma_f32_16x16x32_bf16 v[26:29], v[130:133], v[200:203], v[26:29]
	v_mfma_f32_16x16x32_bf16 v[18:21], v[122:125], v[210:213], v[18:21]
	v_mfma_f32_16x16x32_bf16 v[10:13], v[130:133], v[210:213], v[10:13]
	v_mfma_f32_16x16x32_bf16 v[62:65], v[126:129], v[188:191], v[62:65]
	v_mfma_f32_16x16x32_bf16 v[58:61], v[134:137], v[188:191], v[58:61]
	v_mfma_f32_16x16x32_bf16 v[50:53], v[126:129], v[196:199], v[50:53]
	v_mfma_f32_16x16x32_bf16 v[42:45], v[134:137], v[196:199], v[42:45]
	v_mfma_f32_16x16x32_bf16 v[30:33], v[126:129], v[206:209], v[30:33]
	v_mfma_f32_16x16x32_bf16 v[26:29], v[134:137], v[206:209], v[26:29]
	v_mfma_f32_16x16x32_bf16 v[18:21], v[126:129], v[214:217], v[18:21]
	v_mfma_f32_16x16x32_bf16 v[10:13], v[134:137], v[214:217], v[10:13]
	s_setprio 0
	s_setprio 1
	v_mfma_f32_16x16x32_bf16 v[54:57], v[142:145], v[178:181], v[54:57]
	v_mfma_f32_16x16x32_bf16 v[46:49], v[150:153], v[178:181], v[46:49]
	v_mfma_f32_16x16x32_bf16 v[38:41], v[142:145], v[192:195], v[38:41]
	v_mfma_f32_16x16x32_bf16 v[34:37], v[150:153], v[192:195], v[34:37]
	v_mfma_f32_16x16x32_bf16 v[22:25], v[142:145], v[200:203], v[22:25]
	v_mfma_f32_16x16x32_bf16 v[14:17], v[150:153], v[200:203], v[14:17]
	v_mfma_f32_16x16x32_bf16 v[6:9], v[142:145], v[210:213], v[6:9]
	v_mfma_f32_16x16x32_bf16 v[2:5], v[150:153], v[210:213], v[2:5]
	v_mfma_f32_16x16x32_bf16 v[54:57], v[146:149], v[188:191], v[54:57]
	v_mfma_f32_16x16x32_bf16 v[46:49], v[158:161], v[188:191], v[46:49]
	v_mfma_f32_16x16x32_bf16 v[38:41], v[146:149], v[196:199], v[38:41]
	v_mfma_f32_16x16x32_bf16 v[34:37], v[158:161], v[196:199], v[34:37]
	s_setprio 2
	s_barrier
	v_mfma_f32_16x16x32_bf16 v[22:25], v[146:149], v[206:209], v[22:25]
	v_mfma_f32_16x16x32_bf16 v[14:17], v[158:161], v[206:209], v[14:17]
	v_mfma_f32_16x16x32_bf16 v[6:9], v[146:149], v[214:217], v[6:9]
	v_mfma_f32_16x16x32_bf16 v[2:5], v[158:161], v[214:217], v[2:5]
	s_setprio 0
	s_add_i32 s59, 0, 0x18000
	s_add_i32 s60, 0, 0x1c000
	v_add_u32_e32 v134, s59, v182
	v_add_u32_e32 v158, s60, v182
	ds_read_b128 v[122:125], v134
	ds_read_b128 v[126:129], v134 offset:1024
	ds_read_b128 v[130:133], v134 offset:2048
	ds_read_b128 v[134:137], v134 offset:3072
	ds_read_b128 v[142:145], v158
	ds_read_b128 v[146:149], v158 offset:1024
	ds_read_b128 v[150:153], v158 offset:2048
	ds_read_b128 v[158:161], v158 offset:3072
	s_add_u32 s30, s38, 0x40000
	s_addc_u32 s31, s39, 0
	s_mov_b32 m0, s41
	v_lshl_add_u64 v[226:227], s[30:31], 0, v[162:163]
	ds_read_b128 v[178:181], v186 offset:32768
	ds_read_b128 v[188:191], v186 offset:33792
	ds_read_b128 v[192:195], v186 offset:34816
	ds_read_b128 v[196:199], v186 offset:35840
	ds_read_b128 v[200:203], v186 offset:36864
	ds_read_b128 v[206:209], v186 offset:37888
	ds_read_b128 v[210:213], v186 offset:38912
	ds_read_b128 v[214:217], v186 offset:39936
	global_load_lds_dwordx4 v[226:227], off
	v_lshl_add_u64 v[226:227], s[30:31], 0, v[166:167]
	s_mov_b32 m0, s42
	s_nop 0
	global_load_lds_dwordx4 v[226:227], off
	s_waitcnt vmcnt(8)
	s_waitcnt lgkmcnt(0)
	s_barrier
	s_setprio 1
	s_waitcnt lgkmcnt(0)
	v_mfma_f32_16x16x32_bf16 v[154:157], v[122:125], v[178:181], v[154:157]
	v_mfma_f32_16x16x32_bf16 v[138:141], v[130:133], v[178:181], v[138:141]
	v_mfma_f32_16x16x32_bf16 v[114:117], v[122:125], v[192:195], v[114:117]
	v_mfma_f32_16x16x32_bf16 v[106:109], v[130:133], v[192:195], v[106:109]
	v_mfma_f32_16x16x32_bf16 v[94:97], v[122:125], v[200:203], v[94:97]
	v_mfma_f32_16x16x32_bf16 v[90:93], v[130:133], v[200:203], v[90:93]
	v_mfma_f32_16x16x32_bf16 v[82:85], v[122:125], v[210:213], v[82:85]
	v_mfma_f32_16x16x32_bf16 v[74:77], v[130:133], v[210:213], v[74:77]
	v_mfma_f32_16x16x32_bf16 v[154:157], v[126:129], v[188:191], v[154:157]
	v_mfma_f32_16x16x32_bf16 v[138:141], v[134:137], v[188:191], v[138:141]
	v_mfma_f32_16x16x32_bf16 v[114:117], v[126:129], v[196:199], v[114:117]
	v_mfma_f32_16x16x32_bf16 v[106:109], v[134:137], v[196:199], v[106:109]
	v_mfma_f32_16x16x32_bf16 v[94:97], v[126:129], v[206:209], v[94:97]
	v_mfma_f32_16x16x32_bf16 v[90:93], v[134:137], v[206:209], v[90:93]
	v_mfma_f32_16x16x32_bf16 v[82:85], v[126:129], v[214:217], v[82:85]
	v_mfma_f32_16x16x32_bf16 v[74:77], v[134:137], v[214:217], v[74:77]
	s_setprio 0
	s_setprio 1
	v_mfma_f32_16x16x32_bf16 v[118:121], v[142:145], v[178:181], v[118:121]
	v_mfma_f32_16x16x32_bf16 v[110:113], v[150:153], v[178:181], v[110:113]
	v_mfma_f32_16x16x32_bf16 v[102:105], v[142:145], v[192:195], v[102:105]
	v_mfma_f32_16x16x32_bf16 v[98:101], v[150:153], v[192:195], v[98:101]
	v_mfma_f32_16x16x32_bf16 v[86:89], v[142:145], v[200:203], v[86:89]
	v_mfma_f32_16x16x32_bf16 v[78:81], v[150:153], v[200:203], v[78:81]
	v_mfma_f32_16x16x32_bf16 v[70:73], v[142:145], v[210:213], v[70:73]
	v_mfma_f32_16x16x32_bf16 v[66:69], v[150:153], v[210:213], v[66:69]
	v_mfma_f32_16x16x32_bf16 v[118:121], v[146:149], v[188:191], v[118:121]
	v_mfma_f32_16x16x32_bf16 v[110:113], v[158:161], v[188:191], v[110:113]
	v_mfma_f32_16x16x32_bf16 v[102:105], v[146:149], v[196:199], v[102:105]
	v_mfma_f32_16x16x32_bf16 v[98:101], v[158:161], v[196:199], v[98:101]
	s_setprio 2
	s_barrier
; #define PG8_STAGE(bufoff, gbase, voff) do { _Pragma("unroll") for (int _i = 0; _i < 2; ++_i) \
;         __builtin_amdgcn_global_load_lds((const unsigned*)((const char*)(gbase) + (voff)[_i]), (PG8_LAS unsigned*)(lds + (bufoff) + ldsw + _i * 8192), 16, 0, 0); } while (0)
; #define PG8_LDA(dst, b, h) do { _Pragma("unroll") for (int m = 0; m < 4; ++m) _Pragma("unroll") for (int k = 0; k < 2; ++k) dst[m][k] = *(const PG8_LAS bf16x8*)(lds + PG8_SA(b, h) + aoff + m * 2048 + k * 1024); } while (0)
; #define PG8_LDB(dst, b, h) do { _Pragma("unroll") for (int n = 0; n < 2; ++n) _Pragma("unroll") for (int k = 0; k < 2; ++k) dst[n][k] = *(const PG8_LAS bf16x8*)(lds + PG8_SB(b, h) + boff + n * 2048 + k * 1024); } while (0)
; template <class Epi, class Sched, bool ALIGN_EPI = false, bool SP2 = false>
; __device__ __forceinline__ void gemm_phase(PG8_LAS unsigned char* lds, const Gemm g, const Sched& S, const Epi& E) {
;     ...
;         for (int t = 0; t < nt; t += 2) {
;             const bool last = (t == nt - 2);
;             const char* a1 = cA + (size_t)(t + 1) * kstep;
;             const char* a2 = last ? nA : cA + (size_t)(t + 2) * kstep; const char* b2 = last ? nB : cB + (size_t)(t + 2) * kstep;
;             const char* a3 = a2 + kstep; const char* b3 = b2 + kstep;
;             if (last && has_next) S.a_ready(nxt);
;             if constexpr (SP2) {
;             PG8_LDB(B0, 0, 0); PG8_LDB(B1, 0, 1); PG8_SCHED; PG8_LDA(At, 0, 0); PG8_STAGE(PG8_SA(1, 1), a1 + hstep, voffA);
;             PG8_WAIT_V(8); PG8_WAIT_L(0); PG8_BAR; PG8_MMA(0, 0, At, B0); PG8_MMA(0, 1, At, B1); PG8_BAR; PG8_SCHED;
;             PG8_LDA(At, 0, 1); PG8_STAGE(PG8_SB(0, 0), b2, voffB); PG8_STAGE(PG8_SB(0, 1), b2 + hstep, voffB); PG8_STAGE(PG8_SA(0, 0), a2, voffA);
;             PG8_WAIT_V(8); PG8_WAIT_L(0); PG8_BAR; PG8_MMA(1, 0, At, B0); PG8_MMA(1, 1, At, B1); PG8_BAR; PG8_SCHED;
;             PG8_LDB(B0, 1, 0); PG8_LDB(B1, 1, 1); PG8_SCHED; PG8_LDA(At, 1, 0); PG8_STAGE(PG8_SA(0, 1), a2 + hstep, voffA);
;             PG8_WAIT_V(8); PG8_WAIT_L(0); PG8_BAR; PG8_MMA(0, 0, At, B0); PG8_MMA(0, 1, At, B1); PG8_BAR; PG8_SCHED;
;             PG8_LDA(At, 1, 1); PG8_STAGE(PG8_SB(1, 0), b3, voffB); PG8_STAGE(PG8_SB(1, 1), b3 + hstep, voffB); PG8_STAGE(PG8_SA(1, 0), a3, voffA);
;             PG8_WAIT_V(8); PG8_WAIT_L(0); PG8_BAR; PG8_MMA(1, 0, At, B0); PG8_MMA(1, 1, At, B1); PG8_BAR; PG8_SCHED;
	v_mfma_f32_16x16x32_bf16 v[86:89], v[146:149], v[206:209], v[86:89]
	v_mfma_f32_16x16x32_bf16 v[78:81], v[158:161], v[206:209], v[78:81]
	v_mfma_f32_16x16x32_bf16 v[70:73], v[146:149], v[214:217], v[70:73]
	v_mfma_f32_16x16x32_bf16 v[66:69], v[158:161], v[214:217], v[66:69]
	s_setprio 0
	s_add_i32 s30, s59, s33
	v_lshl_add_u64 v[218:219], v[218:219], 0, s[10:11]
	s_mov_b32 m0, s30
	ds_read_b128 v[178:181], v186 offset:49152
	ds_read_b128 v[188:191], v186 offset:50176
	ds_read_b128 v[192:195], v186 offset:51200
	ds_read_b128 v[196:199], v186 offset:52224
	ds_read_b128 v[200:203], v186 offset:53248
	ds_read_b128 v[206:209], v186 offset:54272
	ds_read_b128 v[210:213], v186 offset:55296
	ds_read_b128 v[214:217], v186 offset:56320
	global_load_lds_dwordx4 v[218:219], off
	s_add_i32 m0, s30, 0x2000
	s_add_u32 s30, s36, 0x40080
	v_lshl_add_u64 v[218:219], v[220:221], 0, s[10:11]
	s_addc_u32 s31, s37, 0
	s_add_i32 s36, s60, s33
	global_load_lds_dwordx4 v[218:219], off
	v_lshl_add_u64 v[218:219], s[30:31], 0, v[164:165]
	s_mov_b32 m0, s36
	s_nop 0
	global_load_lds_dwordx4 v[218:219], off
	v_lshl_add_u64 v[218:219], s[30:31], 0, v[168:169]
	s_add_i32 m0, s36, 0x2000
	s_nop 0
	global_load_lds_dwordx4 v[218:219], off
	v_lshl_add_u64 v[218:219], v[222:223], 0, s[10:11]
	s_mov_b32 m0, s44
	s_nop 0
	global_load_lds_dwordx4 v[218:219], off
	v_lshl_add_u64 v[218:219], v[224:225], 0, s[10:11]
	s_mov_b32 m0, s45
	s_nop 0
	global_load_lds_dwordx4 v[218:219], off
	s_waitcnt vmcnt(8)
	s_waitcnt lgkmcnt(0)
	s_barrier
	s_setprio 1
	s_waitcnt lgkmcnt(0)
	v_mfma_f32_16x16x32_bf16 v[62:65], v[122:125], v[178:181], v[62:65]
	v_mfma_f32_16x16x32_bf16 v[58:61], v[130:133], v[178:181], v[58:61]
	v_mfma_f32_16x16x32_bf16 v[50:53], v[122:125], v[192:195], v[50:53]
	v_mfma_f32_16x16x32_bf16 v[42:45], v[130:133], v[192:195], v[42:45]
	v_mfma_f32_16x16x32_bf16 v[30:33], v[122:125], v[200:203], v[30:33]
	v_mfma_f32_16x16x32_bf16 v[26:29], v[130:133], v[200:203], v[26:29]
	v_mfma_f32_16x16x32_bf16 v[18:21], v[122:125], v[210:213], v[18:21]
	v_mfma_f32_16x16x32_bf16 v[10:13], v[130:133], v[210:213], v[10:13]
	v_mfma_f32_16x16x32_bf16 v[62:65], v[126:129], v[188:191], v[62:65]
	v_mfma_f32_16x16x32_bf16 v[58:61], v[134:137], v[188:191], v[58:61]
	v_mfma_f32_16x16x32_bf16 v[50:53], v[126:129], v[196:199], v[50:53]
	v_mfma_f32_16x16x32_bf16 v[42:45], v[134:137], v[196:199], v[42:45]
	v_mfma_f32_16x16x32_bf16 v[30:33], v[126:129], v[206:209], v[30:33]
	v_mfma_f32_16x16x32_bf16 v[26:29], v[134:137], v[206:209], v[26:29]
	v_mfma_f32_16x16x32_bf16 v[18:21], v[126:129], v[214:217], v[18:21]
	v_mfma_f32_16x16x32_bf16 v[10:13], v[134:137], v[214:217], v[10:13]
	s_setprio 0
	s_setprio 1
	v_mfma_f32_16x16x32_bf16 v[54:57], v[142:145], v[178:181], v[54:57]
	v_mfma_f32_16x16x32_bf16 v[46:49], v[150:153], v[178:181], v[46:49]
	v_mfma_f32_16x16x32_bf16 v[38:41], v[142:145], v[192:195], v[38:41]
	v_mfma_f32_16x16x32_bf16 v[34:37], v[150:153], v[192:195], v[34:37]
	v_mfma_f32_16x16x32_bf16 v[22:25], v[142:145], v[200:203], v[22:25]
	v_mfma_f32_16x16x32_bf16 v[14:17], v[150:153], v[200:203], v[14:17]
	v_mfma_f32_16x16x32_bf16 v[6:9], v[142:145], v[210:213], v[6:9]
	v_mfma_f32_16x16x32_bf16 v[2:5], v[150:153], v[210:213], v[2:5]
	v_mfma_f32_16x16x32_bf16 v[54:57], v[146:149], v[188:191], v[54:57]
	v_mfma_f32_16x16x32_bf16 v[46:49], v[158:161], v[188:191], v[46:49]
	v_mfma_f32_16x16x32_bf16 v[38:41], v[146:149], v[196:199], v[38:41]
	v_mfma_f32_16x16x32_bf16 v[34:37], v[158:161], v[196:199], v[34:37]
	s_setprio 2
	s_barrier
	v_mfma_f32_16x16x32_bf16 v[22:25], v[146:149], v[206:209], v[22:25]
	v_mfma_f32_16x16x32_bf16 v[14:17], v[158:161], v[206:209], v[14:17]
	v_mfma_f32_16x16x32_bf16 v[6:9], v[146:149], v[214:217], v[6:9]
	v_mfma_f32_16x16x32_bf16 v[2:5], v[158:161], v[214:217], v[2:5]
	s_setprio 0
	s_add_i32 s58, s58, 2
	s_add_u32 s26, s26, 0x100
	s_addc_u32 s27, s27, 0
	s_add_u32 s56, s56, 0x100
	s_addc_u32 s57, s57, 0
	s_cmp_gt_u32 s58, 13
	s_cbranch_scc0 .LBB0_1673
	s_and_b64 vcc, exec, s[12:13]
	s_cbranch_vccz .LBB0_1676
	s_barrier

; #define PG8_STAGE(bufoff, gbase, voff) do { _Pragma("unroll") for (int _i = 0; _i < 2; ++_i) \
;         __builtin_amdgcn_global_load_lds((const unsigned*)((const char*)(gbase) + (voff)[_i]), (PG8_LAS unsigned*)(lds + (bufoff) + ldsw + _i * 8192), 16, 0, 0); } while (0)
; #define PG8_LDA(dst, b, h) do { _Pragma("unroll") for (int m = 0; m < 4; ++m) _Pragma("unroll") for (int k = 0; k < 2; ++k) dst[m][k] = *(const PG8_LAS bf16x8*)(lds + PG8_SA(b, h) + aoff + m * 2048 + k * 1024); } while (0)
; #define PG8_LDB(dst, b, h) do { _Pragma("unroll") for (int n = 0; n < 2; ++n) _Pragma("unroll") for (int k = 0; k < 2; ++k) dst[n][k] = *(const PG8_LAS bf16x8*)(lds + PG8_SB(b, h) + boff + n * 2048 + k * 1024); } while (0)
; #define PG8_MMA(ai, bj, At, Bt) do { __builtin_amdgcn_s_setprio(1); _Pragma("unroll") for (int m = 0; m < 4; ++m) _Pragma("unroll") for (int n = 0; n < 2; ++n) _Pragma("unroll") for (int k = 0; k < 2; ++k) \
;         acc[ai][bj][m][n] = __builtin_amdgcn_mfma_f32_16x16x32_bf16(Bt[n][k], At[m][k], acc[ai][bj][m][n], 0, 0, 0); __builtin_amdgcn_s_setprio(0); } while (0)
; #define PG8_WAIT_V(n) asm volatile("s_waitcnt vmcnt(" #n ")" ::: "memory")
; #define PG8_BAR __builtin_amdgcn_s_barrier()
; template <class Epi, class Sched, bool ALIGN_EPI = false, bool SP2 = false>
; __device__ __forceinline__ void gemm_phase(PG8_LAS unsigned char* lds, const Gemm g, const Sched& S, const Epi& E) {
;     ...
;         for (int t = 0; t < nt; t += 2) {
;             const bool last = (t == nt - 2);
;             const char* a1 = cA + (size_t)(t + 1) * kstep;
;             const char* a2 = last ? nA : cA + (size_t)(t + 2) * kstep; const char* b2 = last ? nB : cB + (size_t)(t + 2) * kstep;
;             const char* a3 = a2 + kstep; const char* b3 = b2 + kstep;
;             if (last && has_next) S.a_ready(nxt);
;             if constexpr (SP2) {
;             PG8_LDB(B0, 0, 0); PG8_LDB(B1, 0, 1); PG8_SCHED; PG8_LDA(At, 0, 0); PG8_STAGE(PG8_SA(1, 1), a1 + hstep, voffA);
;             PG8_WAIT_V(8); PG8_WAIT_L(0); PG8_BAR; PG8_MMA(0, 0, At, B0); PG8_MMA(0, 1, At, B1); PG8_BAR; PG8_SCHED;
;             PG8_LDA(At, 0, 1); PG8_STAGE(PG8_SB(0, 0), b2, voffB); PG8_STAGE(PG8_SB(0, 1), b2 + hstep, voffB); PG8_STAGE(PG8_SA(0, 0), a2, voffA);
;             PG8_WAIT_V(8); PG8_WAIT_L(0); PG8_BAR; PG8_MMA(1, 0, At, B0); PG8_MMA(1, 1, At, B1); PG8_BAR; PG8_SCHED;
.LBB0_1822:
	ds_read_b128 v[154:157], v150
	ds_read_b128 v[158:161], v150 offset:1024
	ds_read_b128 v[162:165], v150 offset:2048
	ds_read_b128 v[166:169], v150 offset:3072
	ds_read_b128 v[170:173], v151
	ds_read_b128 v[174:177], v151 offset:1024
	ds_read_b128 v[178:181], v151 offset:2048
	ds_read_b128 v[182:185], v151 offset:3072
	s_add_u32 s30, s40, 0xfffc0080
	s_addc_u32 s31, s41, -1
	s_cmp_eq_u32 s69, 12
	s_cselect_b32 s45, s25, s31
	s_cselect_b32 s44, s65, s30
	s_cselect_b32 s43, s23, s68
	s_cselect_b32 s42, s66, s67
	v_lshl_add_u64 v[146:147], s[40:41], 0, v[138:139]
	s_add_i32 m0, s39, 0xc000
	ds_read_b128 v[186:189], v152
	ds_read_b128 v[190:193], v152 offset:1024
	ds_read_b128 v[194:197], v152 offset:2048
	ds_read_b128 v[198:201], v152 offset:3072
	ds_read_b128 v[206:209], v152 offset:4096
	ds_read_b128 v[210:213], v152 offset:5120
	ds_read_b128 v[214:217], v152 offset:6144
	ds_read_b128 v[218:221], v152 offset:7168
	global_load_lds_dwordx4 v[146:147], off
	v_lshl_add_u64 v[146:147], s[40:41], 0, v[140:141]
	s_add_i32 m0, s39, 0xe000
	s_nop 0
	global_load_lds_dwordx4 v[146:147], off
	s_waitcnt vmcnt(8)
	s_waitcnt lgkmcnt(0)
	s_barrier
	s_setprio 1
	s_waitcnt lgkmcnt(0)
	v_mfma_f32_16x16x32_bf16 v[126:129], v[154:157], v[186:189], v[126:129]
	v_mfma_f32_16x16x32_bf16 v[122:125], v[162:165], v[186:189], v[122:125]
	v_mfma_f32_16x16x32_bf16 v[114:117], v[154:157], v[194:197], v[114:117]
	v_mfma_f32_16x16x32_bf16 v[106:109], v[162:165], v[194:197], v[106:109]
	v_mfma_f32_16x16x32_bf16 v[98:101], v[154:157], v[206:209], v[98:101]
	v_mfma_f32_16x16x32_bf16 v[90:93], v[162:165], v[206:209], v[90:93]
	v_mfma_f32_16x16x32_bf16 v[82:85], v[154:157], v[214:217], v[82:85]
	v_mfma_f32_16x16x32_bf16 v[74:77], v[162:165], v[214:217], v[74:77]
	v_mfma_f32_16x16x32_bf16 v[126:129], v[158:161], v[190:193], v[126:129]
	v_mfma_f32_16x16x32_bf16 v[122:125], v[166:169], v[190:193], v[122:125]
	v_mfma_f32_16x16x32_bf16 v[114:117], v[158:161], v[198:201], v[114:117]
	v_mfma_f32_16x16x32_bf16 v[106:109], v[166:169], v[198:201], v[106:109]
	v_mfma_f32_16x16x32_bf16 v[98:101], v[158:161], v[210:213], v[98:101]
	v_mfma_f32_16x16x32_bf16 v[90:93], v[166:169], v[210:213], v[90:93]
	v_mfma_f32_16x16x32_bf16 v[82:85], v[158:161], v[218:221], v[82:85]
	v_mfma_f32_16x16x32_bf16 v[74:77], v[166:169], v[218:221], v[74:77]
	s_setprio 0
	s_setprio 1
	v_mfma_f32_16x16x32_bf16 v[118:121], v[170:173], v[186:189], v[118:121]
	v_mfma_f32_16x16x32_bf16 v[110:113], v[178:181], v[186:189], v[110:113]
	v_mfma_f32_16x16x32_bf16 v[102:105], v[170:173], v[194:197], v[102:105]
	v_mfma_f32_16x16x32_bf16 v[94:97], v[178:181], v[194:197], v[94:97]
	v_mfma_f32_16x16x32_bf16 v[86:89], v[170:173], v[206:209], v[86:89]
	v_mfma_f32_16x16x32_bf16 v[78:81], v[178:181], v[206:209], v[78:81]
	v_mfma_f32_16x16x32_bf16 v[70:73], v[170:173], v[214:217], v[70:73]
	v_mfma_f32_16x16x32_bf16 v[66:69], v[178:181], v[214:217], v[66:69]
	v_mfma_f32_16x16x32_bf16 v[118:121], v[174:177], v[190:193], v[118:121]
	v_mfma_f32_16x16x32_bf16 v[110:113], v[182:185], v[190:193], v[110:113]
	v_mfma_f32_16x16x32_bf16 v[102:105], v[174:177], v[198:201], v[102:105]
	v_mfma_f32_16x16x32_bf16 v[94:97], v[182:185], v[198:201], v[94:97]
	s_setprio 2
	s_barrier
	v_mfma_f32_16x16x32_bf16 v[86:89], v[174:177], v[210:213], v[86:89]
	v_mfma_f32_16x16x32_bf16 v[78:81], v[182:185], v[210:213], v[78:81]
	v_mfma_f32_16x16x32_bf16 v[70:73], v[174:177], v[218:221], v[70:73]
	v_mfma_f32_16x16x32_bf16 v[66:69], v[182:185], v[218:221], v[66:69]
	s_setprio 0
	s_add_i32 s30, s58, s50
	v_lshl_add_u64 v[146:147], s[42:43], 0, v[132:133]
	s_mov_b32 m0, s30
	ds_read_b128 v[186:189], v152 offset:16384
	ds_read_b128 v[190:193], v152 offset:17408
	ds_read_b128 v[194:197], v152 offset:18432
	ds_read_b128 v[198:201], v152 offset:19456
	ds_read_b128 v[206:209], v152 offset:20480
	ds_read_b128 v[210:213], v152 offset:21504
	ds_read_b128 v[214:217], v152 offset:22528
	ds_read_b128 v[218:221], v152 offset:23552
	global_load_lds_dwordx4 v[146:147], off
	s_add_i32 m0, s30, 0x2000
	s_add_u32 s30, s42, 0x40000
	v_lshl_add_u64 v[202:203], s[42:43], 0, v[136:137]
	s_addc_u32 s31, s43, 0
	s_add_i32 s70, s59, s50
	global_load_lds_dwordx4 v[202:203], off
	v_lshl_add_u64 v[222:223], s[30:31], 0, v[132:133]
	s_mov_b32 m0, s70
	v_lshl_add_u64 v[224:225], s[44:45], 0, v[134:135]
	global_load_lds_dwordx4 v[222:223], off
	v_lshl_add_u64 v[222:223], s[30:31], 0, v[136:137]
	s_add_i32 m0, s70, 0x2000
	s_nop 0
	global_load_lds_dwordx4 v[222:223], off
	v_lshl_add_u64 v[222:223], s[44:45], 0, v[130:131]
	s_mov_b32 m0, s39
	s_nop 0
	global_load_lds_dwordx4 v[222:223], off
	s_mov_b32 m0, s51
	s_nop 0
	global_load_lds_dwordx4 v[224:225], off
	s_waitcnt vmcnt(8)
	s_waitcnt lgkmcnt(0)
	s_barrier
; #define PG8_STAGE(bufoff, gbase, voff) do { _Pragma("unroll") for (int _i = 0; _i < 2; ++_i) \
;         __builtin_amdgcn_global_load_lds((const unsigned*)((const char*)(gbase) + (voff)[_i]), (PG8_LAS unsigned*)(lds + (bufoff) + ldsw + _i * 8192), 16, 0, 0); } while (0)
; #define PG8_LDA(dst, b, h) do { _Pragma("unroll") for (int m = 0; m < 4; ++m) _Pragma("unroll") for (int k = 0; k < 2; ++k) dst[m][k] = *(const PG8_LAS bf16x8*)(lds + PG8_SA(b, h) + aoff + m * 2048 + k * 1024); } while (0)
; #define PG8_LDB(dst, b, h) do { _Pragma("unroll") for (int n = 0; n < 2; ++n) _Pragma("unroll") for (int k = 0; k < 2; ++k) dst[n][k] = *(const PG8_LAS bf16x8*)(lds + PG8_SB(b, h) + boff + n * 2048 + k * 1024); } while (0)
; #define PG8_MMA(ai, bj, At, Bt) do { __builtin_amdgcn_s_setprio(1); _Pragma("unroll") for (int m = 0; m < 4; ++m) _Pragma("unroll") for (int n = 0; n < 2; ++n) _Pragma("unroll") for (int k = 0; k < 2; ++k) \
;         acc[ai][bj][m][n] = __builtin_amdgcn_mfma_f32_16x16x32_bf16(Bt[n][k], At[m][k], acc[ai][bj][m][n], 0, 0, 0); __builtin_amdgcn_s_setprio(0); } while (0)
; #define PG8_WAIT_V(n) asm volatile("s_waitcnt vmcnt(" #n ")" ::: "memory")
; #define PG8_WAIT_L(n) asm volatile("s_waitcnt lgkmcnt(" #n ")" ::: "memory")
; #define PG8_BAR __builtin_amdgcn_s_barrier()
; #define PG8_SCHED __builtin_amdgcn_sched_barrier(0)
; template <class Epi, class Sched, bool ALIGN_EPI = false, bool SP2 = false>
; __device__ __forceinline__ void gemm_phase(PG8_LAS unsigned char* lds, const Gemm g, const Sched& S, const Epi& E) {
;     ...
;             PG8_WAIT_V(8); PG8_WAIT_L(0); PG8_BAR; PG8_MMA(0, 0, At, B0); PG8_MMA(0, 1, At, B1); PG8_BAR; PG8_SCHED;
;             PG8_LDA(At, 0, 1); PG8_STAGE(PG8_SB(0, 0), b2, voffB); PG8_STAGE(PG8_SB(0, 1), b2 + hstep, voffB); PG8_STAGE(PG8_SA(0, 0), a2, voffA);
;             PG8_WAIT_V(8); PG8_WAIT_L(0); PG8_BAR; PG8_MMA(1, 0, At, B0); PG8_MMA(1, 1, At, B1); PG8_BAR; PG8_SCHED;
;             PG8_LDB(B0, 1, 0); PG8_LDB(B1, 1, 1); PG8_SCHED; PG8_LDA(At, 1, 0); PG8_STAGE(PG8_SA(0, 1), a2 + hstep, voffA);
;             PG8_WAIT_V(8); PG8_WAIT_L(0); PG8_BAR; PG8_MMA(0, 0, At, B0); PG8_MMA(0, 1, At, B1); PG8_BAR; PG8_SCHED;
	s_setprio 1
	s_waitcnt lgkmcnt(0)
	v_mfma_f32_16x16x32_bf16 v[62:65], v[154:157], v[186:189], v[62:65]
	v_mfma_f32_16x16x32_bf16 v[58:61], v[162:165], v[186:189], v[58:61]
	v_mfma_f32_16x16x32_bf16 v[50:53], v[154:157], v[194:197], v[50:53]
	v_mfma_f32_16x16x32_bf16 v[42:45], v[162:165], v[194:197], v[42:45]
	v_mfma_f32_16x16x32_bf16 v[34:37], v[154:157], v[206:209], v[34:37]
	v_mfma_f32_16x16x32_bf16 v[26:29], v[162:165], v[206:209], v[26:29]
	v_mfma_f32_16x16x32_bf16 v[18:21], v[154:157], v[214:217], v[18:21]
	v_mfma_f32_16x16x32_bf16 v[10:13], v[162:165], v[214:217], v[10:13]
	v_mfma_f32_16x16x32_bf16 v[62:65], v[158:161], v[190:193], v[62:65]
	v_mfma_f32_16x16x32_bf16 v[58:61], v[166:169], v[190:193], v[58:61]
	v_mfma_f32_16x16x32_bf16 v[50:53], v[158:161], v[198:201], v[50:53]
	v_mfma_f32_16x16x32_bf16 v[42:45], v[166:169], v[198:201], v[42:45]
	v_mfma_f32_16x16x32_bf16 v[34:37], v[158:161], v[210:213], v[34:37]
	v_mfma_f32_16x16x32_bf16 v[26:29], v[166:169], v[210:213], v[26:29]
	v_mfma_f32_16x16x32_bf16 v[18:21], v[158:161], v[218:221], v[18:21]
	v_mfma_f32_16x16x32_bf16 v[10:13], v[166:169], v[218:221], v[10:13]
	s_setprio 0
	s_setprio 1
	v_mfma_f32_16x16x32_bf16 v[54:57], v[170:173], v[186:189], v[54:57]
	v_mfma_f32_16x16x32_bf16 v[46:49], v[178:181], v[186:189], v[46:49]
	v_mfma_f32_16x16x32_bf16 v[38:41], v[170:173], v[194:197], v[38:41]
	v_mfma_f32_16x16x32_bf16 v[30:33], v[178:181], v[194:197], v[30:33]
	v_mfma_f32_16x16x32_bf16 v[22:25], v[170:173], v[206:209], v[22:25]
	v_mfma_f32_16x16x32_bf16 v[14:17], v[178:181], v[206:209], v[14:17]
	v_mfma_f32_16x16x32_bf16 v[6:9], v[170:173], v[214:217], v[6:9]
	v_mfma_f32_16x16x32_bf16 v[2:5], v[178:181], v[214:217], v[2:5]
	v_mfma_f32_16x16x32_bf16 v[54:57], v[174:177], v[190:193], v[54:57]
	v_mfma_f32_16x16x32_bf16 v[46:49], v[182:185], v[190:193], v[46:49]
	v_mfma_f32_16x16x32_bf16 v[38:41], v[174:177], v[198:201], v[38:41]
	v_mfma_f32_16x16x32_bf16 v[30:33], v[182:185], v[198:201], v[30:33]
	s_setprio 2
	s_barrier
	v_mfma_f32_16x16x32_bf16 v[22:25], v[174:177], v[210:213], v[22:25]
	v_mfma_f32_16x16x32_bf16 v[14:17], v[182:185], v[210:213], v[14:17]
	v_mfma_f32_16x16x32_bf16 v[6:9], v[174:177], v[218:221], v[6:9]
	v_mfma_f32_16x16x32_bf16 v[2:5], v[182:185], v[218:221], v[2:5]
	s_setprio 0
	s_add_i32 s70, 0, 0x18000
	v_add_u32_e32 v153, s70, v148
	s_add_i32 s71, 0, 0x1c000
	ds_read_b128 v[154:157], v153
	ds_read_b128 v[158:161], v153 offset:1024
	ds_read_b128 v[162:165], v153 offset:2048
	ds_read_b128 v[166:169], v153 offset:3072
	v_add_u32_e32 v153, s71, v148
	ds_read_b128 v[170:173], v153
	ds_read_b128 v[174:177], v153 offset:1024
	ds_read_b128 v[178:181], v153 offset:2048
	ds_read_b128 v[182:185], v153 offset:3072
	s_add_u32 s30, s44, 0x40000
	s_addc_u32 s31, s45, 0
	s_mov_b32 m0, s52
	v_lshl_add_u64 v[226:227], s[30:31], 0, v[130:131]
	ds_read_b128 v[186:189], v152 offset:32768
	ds_read_b128 v[190:193], v152 offset:33792
	ds_read_b128 v[194:197], v152 offset:34816
	ds_read_b128 v[198:201], v152 offset:35840
	ds_read_b128 v[206:209], v152 offset:36864
	ds_read_b128 v[210:213], v152 offset:37888
	ds_read_b128 v[214:217], v152 offset:38912
	ds_read_b128 v[218:221], v152 offset:39936
	global_load_lds_dwordx4 v[226:227], off
	v_lshl_add_u64 v[226:227], s[30:31], 0, v[134:135]
	s_mov_b32 m0, s53
	s_nop 0
	global_load_lds_dwordx4 v[226:227], off
	s_waitcnt vmcnt(8)
	s_waitcnt lgkmcnt(0)
	s_barrier
	s_setprio 1
	s_waitcnt lgkmcnt(0)
	v_mfma_f32_16x16x32_bf16 v[126:129], v[154:157], v[186:189], v[126:129]
	v_mfma_f32_16x16x32_bf16 v[122:125], v[162:165], v[186:189], v[122:125]
	v_mfma_f32_16x16x32_bf16 v[114:117], v[154:157], v[194:197], v[114:117]
	v_mfma_f32_16x16x32_bf16 v[106:109], v[162:165], v[194:197], v[106:109]
	v_mfma_f32_16x16x32_bf16 v[98:101], v[154:157], v[206:209], v[98:101]
	v_mfma_f32_16x16x32_bf16 v[90:93], v[162:165], v[206:209], v[90:93]
	v_mfma_f32_16x16x32_bf16 v[82:85], v[154:157], v[214:217], v[82:85]
	v_mfma_f32_16x16x32_bf16 v[74:77], v[162:165], v[214:217], v[74:77]
	v_mfma_f32_16x16x32_bf16 v[126:129], v[158:161], v[190:193], v[126:129]
	v_mfma_f32_16x16x32_bf16 v[122:125], v[166:169], v[190:193], v[122:125]
	v_mfma_f32_16x16x32_bf16 v[114:117], v[158:161], v[198:201], v[114:117]
	v_mfma_f32_16x16x32_bf16 v[106:109], v[166:169], v[198:201], v[106:109]
	v_mfma_f32_16x16x32_bf16 v[98:101], v[158:161], v[210:213], v[98:101]
	v_mfma_f32_16x16x32_bf16 v[90:93], v[166:169], v[210:213], v[90:93]
	v_mfma_f32_16x16x32_bf16 v[82:85], v[158:161], v[218:221], v[82:85]
	v_mfma_f32_16x16x32_bf16 v[74:77], v[166:169], v[218:221], v[74:77]
	s_setprio 0
	s_setprio 1
	v_mfma_f32_16x16x32_bf16 v[118:121], v[170:173], v[186:189], v[118:121]
	v_mfma_f32_16x16x32_bf16 v[110:113], v[178:181], v[186:189], v[110:113]
	v_mfma_f32_16x16x32_bf16 v[102:105], v[170:173], v[194:197], v[102:105]
	v_mfma_f32_16x16x32_bf16 v[94:97], v[178:181], v[194:197], v[94:97]
	v_mfma_f32_16x16x32_bf16 v[86:89], v[170:173], v[206:209], v[86:89]
	v_mfma_f32_16x16x32_bf16 v[78:81], v[178:181], v[206:209], v[78:81]
	v_mfma_f32_16x16x32_bf16 v[70:73], v[170:173], v[214:217], v[70:73]
	v_mfma_f32_16x16x32_bf16 v[66:69], v[178:181], v[214:217], v[66:69]
	v_mfma_f32_16x16x32_bf16 v[118:121], v[174:177], v[190:193], v[118:121]
	v_mfma_f32_16x16x32_bf16 v[110:113], v[182:185], v[190:193], v[110:113]
	v_mfma_f32_16x16x32_bf16 v[102:105], v[174:177], v[198:201], v[102:105]
	v_mfma_f32_16x16x32_bf16 v[94:97], v[182:185], v[198:201], v[94:97]
	s_setprio 2
	s_barrier
; #define PG8_STAGE(bufoff, gbase, voff) do { _Pragma("unroll") for (int _i = 0; _i < 2; ++_i) \
;         __builtin_amdgcn_global_load_lds((const unsigned*)((const char*)(gbase) + (voff)[_i]), (PG8_LAS unsigned*)(lds + (bufoff) + ldsw + _i * 8192), 16, 0, 0); } while (0)
; #define PG8_LDA(dst, b, h) do { _Pragma("unroll") for (int m = 0; m < 4; ++m) _Pragma("unroll") for (int k = 0; k < 2; ++k) dst[m][k] = *(const PG8_LAS bf16x8*)(lds + PG8_SA(b, h) + aoff + m * 2048 + k * 1024); } while (0)
; #define PG8_LDB(dst, b, h) do { _Pragma("unroll") for (int n = 0; n < 2; ++n) _Pragma("unroll") for (int k = 0; k < 2; ++k) dst[n][k] = *(const PG8_LAS bf16x8*)(lds + PG8_SB(b, h) + boff + n * 2048 + k * 1024); } while (0)
; template <class Epi, class Sched, bool ALIGN_EPI = false, bool SP2 = false>
; __device__ __forceinline__ void gemm_phase(PG8_LAS unsigned char* lds, const Gemm g, const Sched& S, const Epi& E) {
;     ...
;         for (int t = 0; t < nt; t += 2) {
;             const bool last = (t == nt - 2);
;             const char* a1 = cA + (size_t)(t + 1) * kstep;
;             const char* a2 = last ? nA : cA + (size_t)(t + 2) * kstep; const char* b2 = last ? nB : cB + (size_t)(t + 2) * kstep;
;             const char* a3 = a2 + kstep; const char* b3 = b2 + kstep;
;             if (last && has_next) S.a_ready(nxt);
;             if constexpr (SP2) {
;             PG8_LDB(B0, 0, 0); PG8_LDB(B1, 0, 1); PG8_SCHED; PG8_LDA(At, 0, 0); PG8_STAGE(PG8_SA(1, 1), a1 + hstep, voffA);
;             PG8_WAIT_V(8); PG8_WAIT_L(0); PG8_BAR; PG8_MMA(0, 0, At, B0); PG8_MMA(0, 1, At, B1); PG8_BAR; PG8_SCHED;
;             PG8_LDA(At, 0, 1); PG8_STAGE(PG8_SB(0, 0), b2, voffB); PG8_STAGE(PG8_SB(0, 1), b2 + hstep, voffB); PG8_STAGE(PG8_SA(0, 0), a2, voffA);
;             PG8_WAIT_V(8); PG8_WAIT_L(0); PG8_BAR; PG8_MMA(1, 0, At, B0); PG8_MMA(1, 1, At, B1); PG8_BAR; PG8_SCHED;
;             PG8_LDB(B0, 1, 0); PG8_LDB(B1, 1, 1); PG8_SCHED; PG8_LDA(At, 1, 0); PG8_STAGE(PG8_SA(0, 1), a2 + hstep, voffA);
;             PG8_WAIT_V(8); PG8_WAIT_L(0); PG8_BAR; PG8_MMA(0, 0, At, B0); PG8_MMA(0, 1, At, B1); PG8_BAR; PG8_SCHED;
;             PG8_LDA(At, 1, 1); PG8_STAGE(PG8_SB(1, 0), b3, voffB); PG8_STAGE(PG8_SB(1, 1), b3 + hstep, voffB); PG8_STAGE(PG8_SA(1, 0), a3, voffA);
;             PG8_WAIT_V(8); PG8_WAIT_L(0); PG8_BAR; PG8_MMA(1, 0, At, B0); PG8_MMA(1, 1, At, B1); PG8_BAR; PG8_SCHED;
	v_mfma_f32_16x16x32_bf16 v[86:89], v[174:177], v[210:213], v[86:89]
	v_mfma_f32_16x16x32_bf16 v[78:81], v[182:185], v[210:213], v[78:81]
	v_mfma_f32_16x16x32_bf16 v[70:73], v[174:177], v[218:221], v[70:73]
	v_mfma_f32_16x16x32_bf16 v[66:69], v[182:185], v[218:221], v[66:69]
	s_setprio 0
	s_add_i32 s30, s70, s50
	v_lshl_add_u64 v[146:147], v[146:147], 0, s[10:11]
	s_mov_b32 m0, s30
	ds_read_b128 v[186:189], v152 offset:49152
	ds_read_b128 v[190:193], v152 offset:50176
	ds_read_b128 v[194:197], v152 offset:51200
	ds_read_b128 v[198:201], v152 offset:52224
	ds_read_b128 v[206:209], v152 offset:53248
	ds_read_b128 v[210:213], v152 offset:54272
	ds_read_b128 v[214:217], v152 offset:55296
	ds_read_b128 v[218:221], v152 offset:56320
	global_load_lds_dwordx4 v[146:147], off
	s_add_i32 m0, s30, 0x2000
	s_add_u32 s30, s42, 0x40080
	v_lshl_add_u64 v[146:147], v[202:203], 0, s[10:11]
	s_addc_u32 s31, s43, 0
	s_add_i32 s42, s71, s50
	global_load_lds_dwordx4 v[146:147], off
	v_lshl_add_u64 v[146:147], s[30:31], 0, v[132:133]
	s_mov_b32 m0, s42
	s_nop 0
	global_load_lds_dwordx4 v[146:147], off
	v_lshl_add_u64 v[146:147], s[30:31], 0, v[136:137]
	s_add_i32 m0, s42, 0x2000
	s_nop 0
	global_load_lds_dwordx4 v[146:147], off
	v_lshl_add_u64 v[146:147], v[222:223], 0, s[10:11]
	s_mov_b32 m0, s55
	s_nop 0
	global_load_lds_dwordx4 v[146:147], off
	v_lshl_add_u64 v[146:147], v[224:225], 0, s[10:11]
	s_mov_b32 m0, s56
	s_nop 0
	global_load_lds_dwordx4 v[146:147], off
	s_waitcnt vmcnt(8)
	s_waitcnt lgkmcnt(0)
	s_barrier
	s_setprio 1
	s_waitcnt lgkmcnt(0)
	v_mfma_f32_16x16x32_bf16 v[62:65], v[154:157], v[186:189], v[62:65]
	v_mfma_f32_16x16x32_bf16 v[58:61], v[162:165], v[186:189], v[58:61]
	v_mfma_f32_16x16x32_bf16 v[50:53], v[154:157], v[194:197], v[50:53]
	v_mfma_f32_16x16x32_bf16 v[42:45], v[162:165], v[194:197], v[42:45]
	v_mfma_f32_16x16x32_bf16 v[34:37], v[154:157], v[206:209], v[34:37]
	v_mfma_f32_16x16x32_bf16 v[26:29], v[162:165], v[206:209], v[26:29]
	v_mfma_f32_16x16x32_bf16 v[18:21], v[154:157], v[214:217], v[18:21]
	v_mfma_f32_16x16x32_bf16 v[10:13], v[162:165], v[214:217], v[10:13]
	v_mfma_f32_16x16x32_bf16 v[62:65], v[158:161], v[190:193], v[62:65]
	v_mfma_f32_16x16x32_bf16 v[58:61], v[166:169], v[190:193], v[58:61]
	v_mfma_f32_16x16x32_bf16 v[50:53], v[158:161], v[198:201], v[50:53]
	v_mfma_f32_16x16x32_bf16 v[42:45], v[166:169], v[198:201], v[42:45]
	v_mfma_f32_16x16x32_bf16 v[34:37], v[158:161], v[210:213], v[34:37]
	v_mfma_f32_16x16x32_bf16 v[26:29], v[166:169], v[210:213], v[26:29]
	v_mfma_f32_16x16x32_bf16 v[18:21], v[158:161], v[218:221], v[18:21]
	v_mfma_f32_16x16x32_bf16 v[10:13], v[166:169], v[218:221], v[10:13]
	s_setprio 0
	s_setprio 1
	v_mfma_f32_16x16x32_bf16 v[54:57], v[170:173], v[186:189], v[54:57]
	v_mfma_f32_16x16x32_bf16 v[46:49], v[178:181], v[186:189], v[46:49]
	v_mfma_f32_16x16x32_bf16 v[38:41], v[170:173], v[194:197], v[38:41]
	v_mfma_f32_16x16x32_bf16 v[30:33], v[178:181], v[194:197], v[30:33]
	v_mfma_f32_16x16x32_bf16 v[22:25], v[170:173], v[206:209], v[22:25]
	v_mfma_f32_16x16x32_bf16 v[14:17], v[178:181], v[206:209], v[14:17]
	v_mfma_f32_16x16x32_bf16 v[6:9], v[170:173], v[214:217], v[6:9]
	v_mfma_f32_16x16x32_bf16 v[2:5], v[178:181], v[214:217], v[2:5]
	v_mfma_f32_16x16x32_bf16 v[54:57], v[174:177], v[190:193], v[54:57]
	v_mfma_f32_16x16x32_bf16 v[46:49], v[182:185], v[190:193], v[46:49]
	v_mfma_f32_16x16x32_bf16 v[38:41], v[174:177], v[198:201], v[38:41]
	v_mfma_f32_16x16x32_bf16 v[30:33], v[182:185], v[198:201], v[30:33]
	s_setprio 2
	s_barrier
	v_mfma_f32_16x16x32_bf16 v[22:25], v[174:177], v[210:213], v[22:25]
	v_mfma_f32_16x16x32_bf16 v[14:17], v[182:185], v[210:213], v[14:17]
	v_mfma_f32_16x16x32_bf16 v[6:9], v[174:177], v[218:221], v[6:9]
	v_mfma_f32_16x16x32_bf16 v[2:5], v[182:185], v[218:221], v[2:5]
	s_setprio 0
	s_add_i32 s69, s69, 2
	s_add_u32 s40, s40, 0x100
	s_addc_u32 s41, s41, 0
	s_add_u32 s67, s67, 0x100
	s_addc_u32 s68, s68, 0
	s_cmp_gt_u32 s69, 13
	s_cbranch_scc0 .LBB0_1822
	s_and_b64 vcc, exec, s[12:13]
	s_cbranch_vccz .LBB0_1825
	s_barrier

; #define PG8_STAGE(bufoff, gbase, voff) do { _Pragma("unroll") for (int _i = 0; _i < 2; ++_i) \
;         __builtin_amdgcn_global_load_lds((const unsigned*)((const char*)(gbase) + (voff)[_i]), (PG8_LAS unsigned*)(lds + (bufoff) + ldsw + _i * 8192), 16, 0, 0); } while (0)
; #define PG8_LDA(dst, b, h) do { _Pragma("unroll") for (int m = 0; m < 4; ++m) _Pragma("unroll") for (int k = 0; k < 2; ++k) dst[m][k] = *(const PG8_LAS bf16x8*)(lds + PG8_SA(b, h) + aoff + m * 2048 + k * 1024); } while (0)
; #define PG8_LDB(dst, b, h) do { _Pragma("unroll") for (int n = 0; n < 2; ++n) _Pragma("unroll") for (int k = 0; k < 2; ++k) dst[n][k] = *(const PG8_LAS bf16x8*)(lds + PG8_SB(b, h) + boff + n * 2048 + k * 1024); } while (0)
; #define PG8_MMA(ai, bj, At, Bt) do { __builtin_amdgcn_s_setprio(1); _Pragma("unroll") for (int m = 0; m < 4; ++m) _Pragma("unroll") for (int n = 0; n < 2; ++n) _Pragma("unroll") for (int k = 0; k < 2; ++k) \
;         acc[ai][bj][m][n] = __builtin_amdgcn_mfma_f32_16x16x32_bf16(Bt[n][k], At[m][k], acc[ai][bj][m][n], 0, 0, 0); __builtin_amdgcn_s_setprio(0); } while (0)
; #define PG8_WAIT_V(n) asm volatile("s_waitcnt vmcnt(" #n ")" ::: "memory")
; #define PG8_BAR __builtin_amdgcn_s_barrier()
; template <class Epi, class Sched, bool ALIGN_EPI = false, bool SP2 = false>
; __device__ __forceinline__ void gemm_phase(PG8_LAS unsigned char* lds, const Gemm g, const Sched& S, const Epi& E) {
;     ...
;         for (int t = 0; t < nt; t += 2) {
;             const bool last = (t == nt - 2);
;             const char* a1 = cA + (size_t)(t + 1) * kstep;
;             const char* a2 = last ? nA : cA + (size_t)(t + 2) * kstep; const char* b2 = last ? nB : cB + (size_t)(t + 2) * kstep;
;             const char* a3 = a2 + kstep; const char* b3 = b2 + kstep;
;             if (last && has_next) S.a_ready(nxt);
;             if constexpr (SP2) {
;             PG8_LDB(B0, 0, 0); PG8_LDB(B1, 0, 1); PG8_SCHED; PG8_LDA(At, 0, 0); PG8_STAGE(PG8_SA(1, 1), a1 + hstep, voffA);
;             PG8_WAIT_V(8); PG8_WAIT_L(0); PG8_BAR; PG8_MMA(0, 0, At, B0); PG8_MMA(0, 1, At, B1); PG8_BAR; PG8_SCHED;
;             PG8_LDA(At, 0, 1); PG8_STAGE(PG8_SB(0, 0), b2, voffB); PG8_STAGE(PG8_SB(0, 1), b2 + hstep, voffB); PG8_STAGE(PG8_SA(0, 0), a2, voffA);
;             PG8_WAIT_V(8); PG8_WAIT_L(0); PG8_BAR; PG8_MMA(1, 0, At, B0); PG8_MMA(1, 1, At, B1); PG8_BAR; PG8_SCHED;
.LBB0_1905:
	ds_read_b128 v[122:125], v184
	ds_read_b128 v[126:129], v184 offset:1024
	ds_read_b128 v[130:133], v184 offset:2048
	ds_read_b128 v[134:137], v184 offset:3072
	ds_read_b128 v[142:145], v185
	ds_read_b128 v[146:149], v185 offset:1024
	ds_read_b128 v[150:153], v185 offset:2048
	ds_read_b128 v[158:161], v185 offset:3072
	s_add_u32 s30, s38, 0xfff00080
	s_addc_u32 s31, s39, -1
	s_cmp_eq_u32 s58, 60
	s_cselect_b32 s43, s23, s31
	s_cselect_b32 s42, s54, s30
	s_cselect_b32 s41, s21, s57
	s_cselect_b32 s40, s55, s56
	v_lshl_add_u64 v[218:219], s[38:39], 0, v[170:171]
	s_add_i32 m0, s37, 0xc000
	ds_read_b128 v[178:181], v186
	ds_read_b128 v[188:191], v186 offset:1024
	ds_read_b128 v[192:195], v186 offset:2048
	ds_read_b128 v[196:199], v186 offset:3072
	ds_read_b128 v[200:203], v186 offset:4096
	ds_read_b128 v[206:209], v186 offset:5120
	ds_read_b128 v[210:213], v186 offset:6144
	ds_read_b128 v[214:217], v186 offset:7168
	global_load_lds_dwordx4 v[218:219], off
	v_lshl_add_u64 v[218:219], s[38:39], 0, v[172:173]
	s_add_i32 m0, s37, 0xe000
	s_nop 0
	global_load_lds_dwordx4 v[218:219], off
	s_waitcnt vmcnt(8)
	s_waitcnt lgkmcnt(0)
	s_barrier
	s_setprio 1
	s_waitcnt lgkmcnt(0)
	v_mfma_f32_16x16x32_bf16 v[154:157], v[122:125], v[178:181], v[154:157]
	v_mfma_f32_16x16x32_bf16 v[138:141], v[130:133], v[178:181], v[138:141]
	v_mfma_f32_16x16x32_bf16 v[114:117], v[122:125], v[192:195], v[114:117]
	v_mfma_f32_16x16x32_bf16 v[106:109], v[130:133], v[192:195], v[106:109]
	v_mfma_f32_16x16x32_bf16 v[94:97], v[122:125], v[200:203], v[94:97]
	v_mfma_f32_16x16x32_bf16 v[90:93], v[130:133], v[200:203], v[90:93]
	v_mfma_f32_16x16x32_bf16 v[82:85], v[122:125], v[210:213], v[82:85]
	v_mfma_f32_16x16x32_bf16 v[74:77], v[130:133], v[210:213], v[74:77]
	v_mfma_f32_16x16x32_bf16 v[154:157], v[126:129], v[188:191], v[154:157]
	v_mfma_f32_16x16x32_bf16 v[138:141], v[134:137], v[188:191], v[138:141]
	v_mfma_f32_16x16x32_bf16 v[114:117], v[126:129], v[196:199], v[114:117]
	v_mfma_f32_16x16x32_bf16 v[106:109], v[134:137], v[196:199], v[106:109]
	v_mfma_f32_16x16x32_bf16 v[94:97], v[126:129], v[206:209], v[94:97]
	v_mfma_f32_16x16x32_bf16 v[90:93], v[134:137], v[206:209], v[90:93]
	v_mfma_f32_16x16x32_bf16 v[82:85], v[126:129], v[214:217], v[82:85]
	v_mfma_f32_16x16x32_bf16 v[74:77], v[134:137], v[214:217], v[74:77]
	s_setprio 0
	s_setprio 1
	v_mfma_f32_16x16x32_bf16 v[118:121], v[142:145], v[178:181], v[118:121]
	v_mfma_f32_16x16x32_bf16 v[110:113], v[150:153], v[178:181], v[110:113]
	v_mfma_f32_16x16x32_bf16 v[102:105], v[142:145], v[192:195], v[102:105]
	v_mfma_f32_16x16x32_bf16 v[98:101], v[150:153], v[192:195], v[98:101]
	v_mfma_f32_16x16x32_bf16 v[86:89], v[142:145], v[200:203], v[86:89]
	v_mfma_f32_16x16x32_bf16 v[78:81], v[150:153], v[200:203], v[78:81]
	v_mfma_f32_16x16x32_bf16 v[70:73], v[142:145], v[210:213], v[70:73]
	v_mfma_f32_16x16x32_bf16 v[66:69], v[150:153], v[210:213], v[66:69]
	v_mfma_f32_16x16x32_bf16 v[118:121], v[146:149], v[188:191], v[118:121]
	v_mfma_f32_16x16x32_bf16 v[110:113], v[158:161], v[188:191], v[110:113]
	v_mfma_f32_16x16x32_bf16 v[102:105], v[146:149], v[196:199], v[102:105]
	v_mfma_f32_16x16x32_bf16 v[98:101], v[158:161], v[196:199], v[98:101]
	s_setprio 2
	s_barrier
	v_mfma_f32_16x16x32_bf16 v[86:89], v[146:149], v[206:209], v[86:89]
	v_mfma_f32_16x16x32_bf16 v[78:81], v[158:161], v[206:209], v[78:81]
	v_mfma_f32_16x16x32_bf16 v[70:73], v[146:149], v[214:217], v[70:73]
	v_mfma_f32_16x16x32_bf16 v[66:69], v[158:161], v[214:217], v[66:69]
	s_setprio 0
	s_add_i32 s30, s49, s33
	v_lshl_add_u64 v[218:219], s[40:41], 0, v[164:165]
	s_mov_b32 m0, s30
	ds_read_b128 v[178:181], v186 offset:16384
	ds_read_b128 v[188:191], v186 offset:17408
	ds_read_b128 v[192:195], v186 offset:18432
	ds_read_b128 v[196:199], v186 offset:19456
	ds_read_b128 v[200:203], v186 offset:20480
	ds_read_b128 v[206:209], v186 offset:21504
	ds_read_b128 v[210:213], v186 offset:22528
	ds_read_b128 v[214:217], v186 offset:23552
	global_load_lds_dwordx4 v[218:219], off
	s_add_i32 m0, s30, 0x2000
	s_add_u32 s30, s40, 0x100000
	v_lshl_add_u64 v[220:221], s[40:41], 0, v[168:169]
	s_addc_u32 s31, s41, 0
	s_add_i32 s59, s52, s33
	global_load_lds_dwordx4 v[220:221], off
	v_lshl_add_u64 v[222:223], s[30:31], 0, v[164:165]
	s_mov_b32 m0, s59
	v_lshl_add_u64 v[224:225], s[42:43], 0, v[166:167]
	global_load_lds_dwordx4 v[222:223], off
	v_lshl_add_u64 v[222:223], s[30:31], 0, v[168:169]
	s_add_i32 m0, s59, 0x2000
	s_nop 0
	global_load_lds_dwordx4 v[222:223], off
	v_lshl_add_u64 v[222:223], s[42:43], 0, v[162:163]
	s_mov_b32 m0, s37
	s_nop 0
	global_load_lds_dwordx4 v[222:223], off
	s_mov_b32 m0, s44
	s_nop 0
	global_load_lds_dwordx4 v[224:225], off
	s_waitcnt vmcnt(8)
	s_waitcnt lgkmcnt(0)
	s_barrier
; #define PG8_STAGE(bufoff, gbase, voff) do { _Pragma("unroll") for (int _i = 0; _i < 2; ++_i) \
;         __builtin_amdgcn_global_load_lds((const unsigned*)((const char*)(gbase) + (voff)[_i]), (PG8_LAS unsigned*)(lds + (bufoff) + ldsw + _i * 8192), 16, 0, 0); } while (0)
; #define PG8_LDA(dst, b, h) do { _Pragma("unroll") for (int m = 0; m < 4; ++m) _Pragma("unroll") for (int k = 0; k < 2; ++k) dst[m][k] = *(const PG8_LAS bf16x8*)(lds + PG8_SA(b, h) + aoff + m * 2048 + k * 1024); } while (0)
; #define PG8_LDB(dst, b, h) do { _Pragma("unroll") for (int n = 0; n < 2; ++n) _Pragma("unroll") for (int k = 0; k < 2; ++k) dst[n][k] = *(const PG8_LAS bf16x8*)(lds + PG8_SB(b, h) + boff + n * 2048 + k * 1024); } while (0)
; #define PG8_MMA(ai, bj, At, Bt) do { __builtin_amdgcn_s_setprio(1); _Pragma("unroll") for (int m = 0; m < 4; ++m) _Pragma("unroll") for (int n = 0; n < 2; ++n) _Pragma("unroll") for (int k = 0; k < 2; ++k) \
;         acc[ai][bj][m][n] = __builtin_amdgcn_mfma_f32_16x16x32_bf16(Bt[n][k], At[m][k], acc[ai][bj][m][n], 0, 0, 0); __builtin_amdgcn_s_setprio(0); } while (0)
; #define PG8_WAIT_V(n) asm volatile("s_waitcnt vmcnt(" #n ")" ::: "memory")
; #define PG8_WAIT_L(n) asm volatile("s_waitcnt lgkmcnt(" #n ")" ::: "memory")
; #define PG8_BAR __builtin_amdgcn_s_barrier()
; #define PG8_SCHED __builtin_amdgcn_sched_barrier(0)
; template <class Epi, class Sched, bool ALIGN_EPI = false, bool SP2 = false>
; __device__ __forceinline__ void gemm_phase(PG8_LAS unsigned char* lds, const Gemm g, const Sched& S, const Epi& E) {
;     ...
;             PG8_WAIT_V(8); PG8_WAIT_L(0); PG8_BAR; PG8_MMA(0, 0, At, B0); PG8_MMA(0, 1, At, B1); PG8_BAR; PG8_SCHED;
;             PG8_LDA(At, 0, 1); PG8_STAGE(PG8_SB(0, 0), b2, voffB); PG8_STAGE(PG8_SB(0, 1), b2 + hstep, voffB); PG8_STAGE(PG8_SA(0, 0), a2, voffA);
;             PG8_WAIT_V(8); PG8_WAIT_L(0); PG8_BAR; PG8_MMA(1, 0, At, B0); PG8_MMA(1, 1, At, B1); PG8_BAR; PG8_SCHED;
;             PG8_LDB(B0, 1, 0); PG8_LDB(B1, 1, 1); PG8_SCHED; PG8_LDA(At, 1, 0); PG8_STAGE(PG8_SA(0, 1), a2 + hstep, voffA);
;             PG8_WAIT_V(8); PG8_WAIT_L(0); PG8_BAR; PG8_MMA(0, 0, At, B0); PG8_MMA(0, 1, At, B1); PG8_BAR; PG8_SCHED;
	s_setprio 1
	s_waitcnt lgkmcnt(0)
	v_mfma_f32_16x16x32_bf16 v[62:65], v[122:125], v[178:181], v[62:65]
	v_mfma_f32_16x16x32_bf16 v[58:61], v[130:133], v[178:181], v[58:61]
	v_mfma_f32_16x16x32_bf16 v[50:53], v[122:125], v[192:195], v[50:53]
	v_mfma_f32_16x16x32_bf16 v[42:45], v[130:133], v[192:195], v[42:45]
	v_mfma_f32_16x16x32_bf16 v[30:33], v[122:125], v[200:203], v[30:33]
	v_mfma_f32_16x16x32_bf16 v[26:29], v[130:133], v[200:203], v[26:29]
	v_mfma_f32_16x16x32_bf16 v[18:21], v[122:125], v[210:213], v[18:21]
	v_mfma_f32_16x16x32_bf16 v[10:13], v[130:133], v[210:213], v[10:13]
	v_mfma_f32_16x16x32_bf16 v[62:65], v[126:129], v[188:191], v[62:65]
	v_mfma_f32_16x16x32_bf16 v[58:61], v[134:137], v[188:191], v[58:61]
	v_mfma_f32_16x16x32_bf16 v[50:53], v[126:129], v[196:199], v[50:53]
	v_mfma_f32_16x16x32_bf16 v[42:45], v[134:137], v[196:199], v[42:45]
	v_mfma_f32_16x16x32_bf16 v[30:33], v[126:129], v[206:209], v[30:33]
	v_mfma_f32_16x16x32_bf16 v[26:29], v[134:137], v[206:209], v[26:29]
	v_mfma_f32_16x16x32_bf16 v[18:21], v[126:129], v[214:217], v[18:21]
	v_mfma_f32_16x16x32_bf16 v[10:13], v[134:137], v[214:217], v[10:13]
	s_setprio 0
	s_setprio 1
	v_mfma_f32_16x16x32_bf16 v[54:57], v[142:145], v[178:181], v[54:57]
	v_mfma_f32_16x16x32_bf16 v[46:49], v[150:153], v[178:181], v[46:49]
	v_mfma_f32_16x16x32_bf16 v[38:41], v[142:145], v[192:195], v[38:41]
	v_mfma_f32_16x16x32_bf16 v[34:37], v[150:153], v[192:195], v[34:37]
	v_mfma_f32_16x16x32_bf16 v[22:25], v[142:145], v[200:203], v[22:25]
	v_mfma_f32_16x16x32_bf16 v[14:17], v[150:153], v[200:203], v[14:17]
	v_mfma_f32_16x16x32_bf16 v[6:9], v[142:145], v[210:213], v[6:9]
	v_mfma_f32_16x16x32_bf16 v[2:5], v[150:153], v[210:213], v[2:5]
	v_mfma_f32_16x16x32_bf16 v[54:57], v[146:149], v[188:191], v[54:57]
	v_mfma_f32_16x16x32_bf16 v[46:49], v[158:161], v[188:191], v[46:49]
	v_mfma_f32_16x16x32_bf16 v[38:41], v[146:149], v[196:199], v[38:41]
	v_mfma_f32_16x16x32_bf16 v[34:37], v[158:161], v[196:199], v[34:37]
	s_setprio 2
	s_barrier
	v_mfma_f32_16x16x32_bf16 v[22:25], v[146:149], v[206:209], v[22:25]
	v_mfma_f32_16x16x32_bf16 v[14:17], v[158:161], v[206:209], v[14:17]
	v_mfma_f32_16x16x32_bf16 v[6:9], v[146:149], v[214:217], v[6:9]
	v_mfma_f32_16x16x32_bf16 v[2:5], v[158:161], v[214:217], v[2:5]
	s_setprio 0
	s_add_i32 s59, 0, 0x18000
	s_add_i32 s60, 0, 0x1c000
	v_add_u32_e32 v134, s59, v182
	v_add_u32_e32 v158, s60, v182
	ds_read_b128 v[122:125], v134
	ds_read_b128 v[126:129], v134 offset:1024
	ds_read_b128 v[130:133], v134 offset:2048
	ds_read_b128 v[134:137], v134 offset:3072
	ds_read_b128 v[142:145], v158
	ds_read_b128 v[146:149], v158 offset:1024
	ds_read_b128 v[150:153], v158 offset:2048
	ds_read_b128 v[158:161], v158 offset:3072
	s_add_u32 s30, s42, 0x100000
	s_addc_u32 s31, s43, 0
	s_mov_b32 m0, s45
	v_lshl_add_u64 v[226:227], s[30:31], 0, v[162:163]
	ds_read_b128 v[178:181], v186 offset:32768
	ds_read_b128 v[188:191], v186 offset:33792
	ds_read_b128 v[192:195], v186 offset:34816
	ds_read_b128 v[196:199], v186 offset:35840
	ds_read_b128 v[200:203], v186 offset:36864
	ds_read_b128 v[206:209], v186 offset:37888
	ds_read_b128 v[210:213], v186 offset:38912
	ds_read_b128 v[214:217], v186 offset:39936
	global_load_lds_dwordx4 v[226:227], off
	v_lshl_add_u64 v[226:227], s[30:31], 0, v[166:167]
	s_mov_b32 m0, s50
	s_nop 0
	global_load_lds_dwordx4 v[226:227], off
	s_waitcnt vmcnt(8)
	s_waitcnt lgkmcnt(0)
	s_barrier
	s_setprio 1
	s_waitcnt lgkmcnt(0)
	v_mfma_f32_16x16x32_bf16 v[154:157], v[122:125], v[178:181], v[154:157]
	v_mfma_f32_16x16x32_bf16 v[138:141], v[130:133], v[178:181], v[138:141]
	v_mfma_f32_16x16x32_bf16 v[114:117], v[122:125], v[192:195], v[114:117]
	v_mfma_f32_16x16x32_bf16 v[106:109], v[130:133], v[192:195], v[106:109]
	v_mfma_f32_16x16x32_bf16 v[94:97], v[122:125], v[200:203], v[94:97]
	v_mfma_f32_16x16x32_bf16 v[90:93], v[130:133], v[200:203], v[90:93]
	v_mfma_f32_16x16x32_bf16 v[82:85], v[122:125], v[210:213], v[82:85]
	v_mfma_f32_16x16x32_bf16 v[74:77], v[130:133], v[210:213], v[74:77]
	v_mfma_f32_16x16x32_bf16 v[154:157], v[126:129], v[188:191], v[154:157]
	v_mfma_f32_16x16x32_bf16 v[138:141], v[134:137], v[188:191], v[138:141]
	v_mfma_f32_16x16x32_bf16 v[114:117], v[126:129], v[196:199], v[114:117]
	v_mfma_f32_16x16x32_bf16 v[106:109], v[134:137], v[196:199], v[106:109]
	v_mfma_f32_16x16x32_bf16 v[94:97], v[126:129], v[206:209], v[94:97]
	v_mfma_f32_16x16x32_bf16 v[90:93], v[134:137], v[206:209], v[90:93]
	v_mfma_f32_16x16x32_bf16 v[82:85], v[126:129], v[214:217], v[82:85]
	v_mfma_f32_16x16x32_bf16 v[74:77], v[134:137], v[214:217], v[74:77]
	s_setprio 0
	s_setprio 1
	v_mfma_f32_16x16x32_bf16 v[118:121], v[142:145], v[178:181], v[118:121]
	v_mfma_f32_16x16x32_bf16 v[110:113], v[150:153], v[178:181], v[110:113]
	v_mfma_f32_16x16x32_bf16 v[102:105], v[142:145], v[192:195], v[102:105]
	v_mfma_f32_16x16x32_bf16 v[98:101], v[150:153], v[192:195], v[98:101]
	v_mfma_f32_16x16x32_bf16 v[86:89], v[142:145], v[200:203], v[86:89]
	v_mfma_f32_16x16x32_bf16 v[78:81], v[150:153], v[200:203], v[78:81]
	v_mfma_f32_16x16x32_bf16 v[70:73], v[142:145], v[210:213], v[70:73]
	v_mfma_f32_16x16x32_bf16 v[66:69], v[150:153], v[210:213], v[66:69]
	v_mfma_f32_16x16x32_bf16 v[118:121], v[146:149], v[188:191], v[118:121]
	v_mfma_f32_16x16x32_bf16 v[110:113], v[158:161], v[188:191], v[110:113]
	v_mfma_f32_16x16x32_bf16 v[102:105], v[146:149], v[196:199], v[102:105]
	v_mfma_f32_16x16x32_bf16 v[98:101], v[158:161], v[196:199], v[98:101]
	s_setprio 2
	s_barrier
; #define PG8_STAGE(bufoff, gbase, voff) do { _Pragma("unroll") for (int _i = 0; _i < 2; ++_i) \
;         __builtin_amdgcn_global_load_lds((const unsigned*)((const char*)(gbase) + (voff)[_i]), (PG8_LAS unsigned*)(lds + (bufoff) + ldsw + _i * 8192), 16, 0, 0); } while (0)
; #define PG8_LDA(dst, b, h) do { _Pragma("unroll") for (int m = 0; m < 4; ++m) _Pragma("unroll") for (int k = 0; k < 2; ++k) dst[m][k] = *(const PG8_LAS bf16x8*)(lds + PG8_SA(b, h) + aoff + m * 2048 + k * 1024); } while (0)
; #define PG8_LDB(dst, b, h) do { _Pragma("unroll") for (int n = 0; n < 2; ++n) _Pragma("unroll") for (int k = 0; k < 2; ++k) dst[n][k] = *(const PG8_LAS bf16x8*)(lds + PG8_SB(b, h) + boff + n * 2048 + k * 1024); } while (0)
; template <class Epi, class Sched, bool ALIGN_EPI = false, bool SP2 = false>
; __device__ __forceinline__ void gemm_phase(PG8_LAS unsigned char* lds, const Gemm g, const Sched& S, const Epi& E) {
;     ...
;         for (int t = 0; t < nt; t += 2) {
;             const bool last = (t == nt - 2);
;             const char* a1 = cA + (size_t)(t + 1) * kstep;
;             const char* a2 = last ? nA : cA + (size_t)(t + 2) * kstep; const char* b2 = last ? nB : cB + (size_t)(t + 2) * kstep;
;             const char* a3 = a2 + kstep; const char* b3 = b2 + kstep;
;             if (last && has_next) S.a_ready(nxt);
;             if constexpr (SP2) {
;             PG8_LDB(B0, 0, 0); PG8_LDB(B1, 0, 1); PG8_SCHED; PG8_LDA(At, 0, 0); PG8_STAGE(PG8_SA(1, 1), a1 + hstep, voffA);
;             PG8_WAIT_V(8); PG8_WAIT_L(0); PG8_BAR; PG8_MMA(0, 0, At, B0); PG8_MMA(0, 1, At, B1); PG8_BAR; PG8_SCHED;
;             PG8_LDA(At, 0, 1); PG8_STAGE(PG8_SB(0, 0), b2, voffB); PG8_STAGE(PG8_SB(0, 1), b2 + hstep, voffB); PG8_STAGE(PG8_SA(0, 0), a2, voffA);
;             PG8_WAIT_V(8); PG8_WAIT_L(0); PG8_BAR; PG8_MMA(1, 0, At, B0); PG8_MMA(1, 1, At, B1); PG8_BAR; PG8_SCHED;
;             PG8_LDB(B0, 1, 0); PG8_LDB(B1, 1, 1); PG8_SCHED; PG8_LDA(At, 1, 0); PG8_STAGE(PG8_SA(0, 1), a2 + hstep, voffA);
;             PG8_WAIT_V(8); PG8_WAIT_L(0); PG8_BAR; PG8_MMA(0, 0, At, B0); PG8_MMA(0, 1, At, B1); PG8_BAR; PG8_SCHED;
;             PG8_LDA(At, 1, 1); PG8_STAGE(PG8_SB(1, 0), b3, voffB); PG8_STAGE(PG8_SB(1, 1), b3 + hstep, voffB); PG8_STAGE(PG8_SA(1, 0), a3, voffA);
;             PG8_WAIT_V(8); PG8_WAIT_L(0); PG8_BAR; PG8_MMA(1, 0, At, B0); PG8_MMA(1, 1, At, B1); PG8_BAR; PG8_SCHED;
	v_mfma_f32_16x16x32_bf16 v[86:89], v[146:149], v[206:209], v[86:89]
	v_mfma_f32_16x16x32_bf16 v[78:81], v[158:161], v[206:209], v[78:81]
	v_mfma_f32_16x16x32_bf16 v[70:73], v[146:149], v[214:217], v[70:73]
	v_mfma_f32_16x16x32_bf16 v[66:69], v[158:161], v[214:217], v[66:69]
	s_setprio 0
	s_add_i32 s30, s59, s33
	v_lshl_add_u64 v[218:219], v[218:219], 0, s[14:15]
	s_mov_b32 m0, s30
	ds_read_b128 v[178:181], v186 offset:49152
	ds_read_b128 v[188:191], v186 offset:50176
	ds_read_b128 v[192:195], v186 offset:51200
	ds_read_b128 v[196:199], v186 offset:52224
	ds_read_b128 v[200:203], v186 offset:53248
	ds_read_b128 v[206:209], v186 offset:54272
	ds_read_b128 v[210:213], v186 offset:55296
	ds_read_b128 v[214:217], v186 offset:56320
	global_load_lds_dwordx4 v[218:219], off
	s_add_i32 m0, s30, 0x2000
	s_add_u32 s30, s40, 0x100080
	v_lshl_add_u64 v[218:219], v[220:221], 0, s[14:15]
	s_addc_u32 s31, s41, 0
	s_add_i32 s40, s60, s33
	global_load_lds_dwordx4 v[218:219], off
	v_lshl_add_u64 v[218:219], s[30:31], 0, v[164:165]
	s_mov_b32 m0, s40
	s_nop 0
	global_load_lds_dwordx4 v[218:219], off
	v_lshl_add_u64 v[218:219], s[30:31], 0, v[168:169]
	s_add_i32 m0, s40, 0x2000
	s_nop 0
	global_load_lds_dwordx4 v[218:219], off
	v_lshl_add_u64 v[218:219], v[222:223], 0, s[14:15]
	s_mov_b32 m0, s46
	s_nop 0
	global_load_lds_dwordx4 v[218:219], off
	v_lshl_add_u64 v[218:219], v[224:225], 0, s[14:15]
	s_mov_b32 m0, s47
	s_nop 0
	global_load_lds_dwordx4 v[218:219], off
	s_waitcnt vmcnt(8)
	s_waitcnt lgkmcnt(0)
	s_barrier
	s_setprio 1
	s_waitcnt lgkmcnt(0)
	v_mfma_f32_16x16x32_bf16 v[62:65], v[122:125], v[178:181], v[62:65]
	v_mfma_f32_16x16x32_bf16 v[58:61], v[130:133], v[178:181], v[58:61]
	v_mfma_f32_16x16x32_bf16 v[50:53], v[122:125], v[192:195], v[50:53]
	v_mfma_f32_16x16x32_bf16 v[42:45], v[130:133], v[192:195], v[42:45]
	v_mfma_f32_16x16x32_bf16 v[30:33], v[122:125], v[200:203], v[30:33]
	v_mfma_f32_16x16x32_bf16 v[26:29], v[130:133], v[200:203], v[26:29]
	v_mfma_f32_16x16x32_bf16 v[18:21], v[122:125], v[210:213], v[18:21]
	v_mfma_f32_16x16x32_bf16 v[10:13], v[130:133], v[210:213], v[10:13]
	v_mfma_f32_16x16x32_bf16 v[62:65], v[126:129], v[188:191], v[62:65]
	v_mfma_f32_16x16x32_bf16 v[58:61], v[134:137], v[188:191], v[58:61]
	v_mfma_f32_16x16x32_bf16 v[50:53], v[126:129], v[196:199], v[50:53]
	v_mfma_f32_16x16x32_bf16 v[42:45], v[134:137], v[196:199], v[42:45]
	v_mfma_f32_16x16x32_bf16 v[30:33], v[126:129], v[206:209], v[30:33]
	v_mfma_f32_16x16x32_bf16 v[26:29], v[134:137], v[206:209], v[26:29]
	v_mfma_f32_16x16x32_bf16 v[18:21], v[126:129], v[214:217], v[18:21]
	v_mfma_f32_16x16x32_bf16 v[10:13], v[134:137], v[214:217], v[10:13]
	s_setprio 0
	s_setprio 1
	v_mfma_f32_16x16x32_bf16 v[54:57], v[142:145], v[178:181], v[54:57]
	v_mfma_f32_16x16x32_bf16 v[46:49], v[150:153], v[178:181], v[46:49]
	v_mfma_f32_16x16x32_bf16 v[38:41], v[142:145], v[192:195], v[38:41]
	v_mfma_f32_16x16x32_bf16 v[34:37], v[150:153], v[192:195], v[34:37]
	v_mfma_f32_16x16x32_bf16 v[22:25], v[142:145], v[200:203], v[22:25]
	v_mfma_f32_16x16x32_bf16 v[14:17], v[150:153], v[200:203], v[14:17]
	v_mfma_f32_16x16x32_bf16 v[6:9], v[142:145], v[210:213], v[6:9]
	v_mfma_f32_16x16x32_bf16 v[2:5], v[150:153], v[210:213], v[2:5]
	v_mfma_f32_16x16x32_bf16 v[54:57], v[146:149], v[188:191], v[54:57]
	v_mfma_f32_16x16x32_bf16 v[46:49], v[158:161], v[188:191], v[46:49]
	v_mfma_f32_16x16x32_bf16 v[38:41], v[146:149], v[196:199], v[38:41]
	v_mfma_f32_16x16x32_bf16 v[34:37], v[158:161], v[196:199], v[34:37]
	s_setprio 2
	s_barrier
	v_mfma_f32_16x16x32_bf16 v[22:25], v[146:149], v[206:209], v[22:25]
	v_mfma_f32_16x16x32_bf16 v[14:17], v[158:161], v[206:209], v[14:17]
	v_mfma_f32_16x16x32_bf16 v[6:9], v[146:149], v[214:217], v[6:9]
	v_mfma_f32_16x16x32_bf16 v[2:5], v[158:161], v[214:217], v[2:5]
	s_setprio 0
	s_add_i32 s58, s58, 2
	s_add_u32 s38, s38, 0x100
	s_addc_u32 s39, s39, 0
	s_add_u32 s56, s56, 0x100
	s_addc_u32 s57, s57, 0
	s_cmp_gt_u32 s58, 61
	s_cbranch_scc0 .LBB0_1905
	s_and_b64 vcc, exec, s[16:17]
	s_cbranch_vccz .LBB0_1908
	s_barrier
